# row-phase wave reductions: ds_bpermute butterflies replaced by permlane32/16_swap + DPP row_ror/quad_perm (bit-identical)
# speedup vs baseline: 1.0034x; 1.0034x over previous
; #define GLOAD(k0) do { _Pragma("unroll") for (int i_ = 0; i_ < 2 * MI; ++i_) ra[i_] = *(const u32x4*)(Ap + (long)(64 * i_) * lda + (k0)); \
;     _Pragma("unroll") for (int i_ = 0; i_ < 2 * NC; ++i_) rb[i_] = *(const u32x4*)(Bp + (long)(64 * i_) * ldb + (k0)); } while (0)
; #define GWRITE(buf) do { char* a_ = As + (buf) * ABUF + rw * 128 + swz; char* b_ = Bs + (buf) * BBUF + rw * 128 + swz; \
;     _Pragma("unroll") for (int i_ = 0; i_ < 2 * MI; ++i_) *(u32x4*)(a_ + i_ * 64 * 128) = ra[i_]; \
;     _Pragma("unroll") for (int i_ = 0; i_ < 2 * NC; ++i_) *(u32x4*)(b_ + i_ * 64 * 128) = rb[i_]; } while (0)
; #define MFMA_ALL(kt_) mfma_tile<MI, NC>(acc, As + ((kt_) & 1) * ABUF, Bs + ((kt_) & 1) * BBUF, rowa0, rowb0, sa, sb, hi)
; #define KBAR() do { asm volatile("s_waitcnt lgkmcnt(0)" ::: "memory"); __builtin_amdgcn_s_barrier(); asm volatile("" ::: "memory"); } while (0)
; template <int MI, int NC>
; DEVI void mfma_tile(f32x16 (&acc)[2 * NC][MI], const char* Ab, const char* Bb, int rowa0, int rowb0, int sa, int sb, int hi) {
;     ...
;     for (int k16 = 0; k16 < 4; ++k16) {
;       const int chn = k16 * 2 + hi;
;       bf16x8 ga[2 * NC], gb[MI];
; #pragma unroll
;       for (int ni = 0; ni < 2 * NC; ++ni) ga[ni] = *(const bf16x8*)(Bb + (rowa0 + 32 * ni) * 128 + ((chn ^ sa) << 4));
; #pragma unroll
;       for (int mi = 0; mi < MI; ++mi) gb[mi] = *(const bf16x8*)(Ab + (rowb0 + 32 * mi) * 128 + ((chn ^ sb) << 4));
; #pragma unroll
;       for (int ni = 0; ni < 2 * NC; ++ni)
; #pragma unroll
;         for (int mi = 0; mi < MI; ++mi)
;           acc[ni][mi] = __builtin_amdgcn_mfma_f32_32x32x16_bf16(ga[ni], gb[mi], acc[ni][mi], 0, 0, 0);
;     }
; template <int MI, int NC>
; DEVI void gemm_kloop(f32x16 (&acc)[2 * NC][MI], const u16* __restrict__ A, long lda, const u16* __restrict__ Bt, long ldb, int K, char* lds) {
;     ...
;     for (int kt = 0; kt < KT; ++kt) {
;       if (kt + 1 < KT) { GWRITE((kt + 1) & 1); if (kt + 2 < KT) GLOAD((kt + 2) * 64); }
;       KBAR();
;       MFMA_ALL(kt);
;       KBAR();
;     }
.LBB0_133:
	v_lshl_add_u64 v[216:217], v[206:207], 0, s[6:7]
	v_add_co_u32_e32 v234, vcc, s34, v216
	v_lshl_add_u64 v[218:219], v[204:205], 0, s[6:7]
	s_nop 0
	v_addc_co_u32_e32 v235, vcc, 0, v217, vcc
	v_add_co_u32_e32 v236, vcc, s35, v216
	s_add_i32 s8, s3, 0x8000
	s_nop 0
	v_addc_co_u32_e32 v237, vcc, 0, v217, vcc
	v_add_co_u32_e32 v238, vcc, s86, v216
	s_and_b32 s9, s8, 0x8000
	s_nop 0
	v_addc_co_u32_e32 v239, vcc, 0, v217, vcc
	v_add_co_u32_e32 v216, vcc, s87, v216
	v_add_u32_e32 v246, s9, v229
	s_nop 0
	v_addc_co_u32_e32 v217, vcc, 0, v217, vcc
	v_add_co_u32_e32 v240, vcc, s25, v218
	v_add_u32_e32 v247, s9, v231
	s_nop 0
	v_addc_co_u32_e32 v241, vcc, 0, v219, vcc
	v_add_co_u32_e32 v242, vcc, s21, v218
	s_waitcnt vmcnt(7)
	ds_write_b128 v246, v[160:163]
	s_waitcnt vmcnt(6)
	ds_write_b128 v246, v[164:167] offset:8192
	s_waitcnt vmcnt(5)
	ds_write_b128 v246, v[168:171] offset:16384
	s_waitcnt vmcnt(4)
	ds_write_b128 v246, v[172:175] offset:24576
	s_waitcnt vmcnt(3)
	ds_write_b128 v247, v[176:179]
	s_waitcnt vmcnt(2)
	ds_write_b128 v247, v[180:183] offset:8192
	s_waitcnt vmcnt(1)
	ds_write_b128 v247, v[184:187] offset:16384
	s_waitcnt vmcnt(0)
	ds_write_b128 v247, v[188:191] offset:24576
	v_addc_co_u32_e32 v243, vcc, 0, v219, vcc
	v_add_co_u32_e32 v244, vcc, s97, v218
	s_and_b32 s3, s3, 0x8000
	s_nop 0
	v_addc_co_u32_e32 v245, vcc, 0, v219, vcc
	global_load_dwordx4 v[160:163], v[234:235], off offset:2304
	global_load_dwordx4 v[164:167], v[236:237], off offset:2304
	global_load_dwordx4 v[168:171], v[238:239], off offset:2304
	global_load_dwordx4 v[172:175], v[216:217], off offset:2304
	global_load_dwordx4 v[176:179], v[218:219], off offset:256
	global_load_dwordx4 v[180:183], v[240:241], off offset:256
	global_load_dwordx4 v[184:187], v[242:243], off offset:256
	global_load_dwordx4 v[188:191], v[244:245], off offset:256
	s_add_i32 s3, s3, 16
	s_add_i32 s9, s3, 0x10000
	v_add3_u32 v248, s3, v232, v233
	v_add3_u32 v216, s9, v232, v226
	s_waitcnt lgkmcnt(0)
	s_barrier
	ds_read_b128 v[234:237], v216
	ds_read_b128 v[238:241], v248
	ds_read_b128 v[242:245], v216 offset:4096
	ds_read_b128 v[246:249], v248 offset:4096
	s_waitcnt lgkmcnt(2)
	v_mfma_f32_32x32x16_bf16 v[112:127], v[234:237], v[238:241], v[112:127]
	v_add3_u32 v217, s9, v230, v226
	s_add_u32 s6, s6, 0x80
	s_addc_u32 s7, s7, 0
	s_cmpk_eq_i32 s6, 0x700
	s_waitcnt lgkmcnt(0)
	v_mfma_f32_32x32x16_bf16 v[80:95], v[234:237], v[246:249], v[80:95]
	v_mfma_f32_32x32x16_bf16 v[96:111], v[242:245], v[238:241], v[96:111]
	v_mfma_f32_32x32x16_bf16 v[64:79], v[242:245], v[246:249], v[64:79]
	ds_read_b128 v[234:237], v216 offset:8192
	ds_read_b128 v[242:245], v216 offset:12288
	v_add3_u32 v216, s3, v230, v233
	s_waitcnt lgkmcnt(1)
	v_mfma_f32_32x32x16_bf16 v[48:63], v[234:237], v[238:241], v[48:63]
	v_mfma_f32_32x32x16_bf16 v[16:31], v[234:237], v[246:249], v[16:31]
	s_waitcnt lgkmcnt(0)
	v_mfma_f32_32x32x16_bf16 v[32:47], v[242:245], v[238:241], v[32:47]
	v_mfma_f32_32x32x16_bf16 v[0:15], v[242:245], v[246:249], v[0:15]
	ds_read_b128 v[234:237], v217
	ds_read_b128 v[238:241], v216
	ds_read_b128 v[242:245], v217 offset:4096
	ds_read_b128 v[246:249], v216 offset:4096
	v_add3_u32 v216, s3, v228, v233
	s_waitcnt lgkmcnt(2)
	v_mfma_f32_32x32x16_bf16 v[112:127], v[234:237], v[238:241], v[112:127]
	s_waitcnt lgkmcnt(0)
	v_mfma_f32_32x32x16_bf16 v[80:95], v[234:237], v[246:249], v[80:95]
	v_mfma_f32_32x32x16_bf16 v[96:111], v[242:245], v[238:241], v[96:111]
	v_mfma_f32_32x32x16_bf16 v[64:79], v[242:245], v[246:249], v[64:79]
	ds_read_b128 v[234:237], v217 offset:8192
	ds_read_b128 v[242:245], v217 offset:12288
	v_add3_u32 v217, s9, v228, v226
	s_waitcnt lgkmcnt(1)
	v_mfma_f32_32x32x16_bf16 v[48:63], v[234:237], v[238:241], v[48:63]
	v_mfma_f32_32x32x16_bf16 v[16:31], v[234:237], v[246:249], v[16:31]
	s_waitcnt lgkmcnt(0)
	v_mfma_f32_32x32x16_bf16 v[32:47], v[242:245], v[238:241], v[32:47]
	v_mfma_f32_32x32x16_bf16 v[0:15], v[242:245], v[246:249], v[0:15]
	ds_read_b128 v[234:237], v217
	ds_read_b128 v[238:241], v216
	ds_read_b128 v[242:245], v217 offset:4096
	ds_read_b128 v[246:249], v216 offset:4096
	v_add3_u32 v216, s3, v227, v233
	s_mov_b32 s3, s8
	s_waitcnt lgkmcnt(2)
	v_mfma_f32_32x32x16_bf16 v[112:127], v[234:237], v[238:241], v[112:127]
	s_waitcnt lgkmcnt(0)
	v_mfma_f32_32x32x16_bf16 v[80:95], v[234:237], v[246:249], v[80:95]
	v_mfma_f32_32x32x16_bf16 v[96:111], v[242:245], v[238:241], v[96:111]
	v_mfma_f32_32x32x16_bf16 v[64:79], v[242:245], v[246:249], v[64:79]
	ds_read_b128 v[234:237], v217 offset:8192
	ds_read_b128 v[242:245], v217 offset:12288
	v_add3_u32 v217, s9, v227, v226
	s_waitcnt lgkmcnt(1)
	v_mfma_f32_32x32x16_bf16 v[48:63], v[234:237], v[238:241], v[48:63]
	v_mfma_f32_32x32x16_bf16 v[16:31], v[234:237], v[246:249], v[16:31]
	s_waitcnt lgkmcnt(0)
	v_mfma_f32_32x32x16_bf16 v[32:47], v[242:245], v[238:241], v[32:47]
	v_mfma_f32_32x32x16_bf16 v[0:15], v[242:245], v[246:249], v[0:15]
	ds_read_b128 v[234:237], v217
	ds_read_b128 v[238:241], v216
	ds_read_b128 v[242:245], v217 offset:4096
	ds_read_b128 v[246:249], v216 offset:4096
	s_waitcnt lgkmcnt(2)
	v_mfma_f32_32x32x16_bf16 v[112:127], v[234:237], v[238:241], v[112:127]
	s_waitcnt lgkmcnt(0)
	v_mfma_f32_32x32x16_bf16 v[80:95], v[234:237], v[246:249], v[80:95]
	v_mfma_f32_32x32x16_bf16 v[96:111], v[242:245], v[238:241], v[96:111]
	v_mfma_f32_32x32x16_bf16 v[64:79], v[242:245], v[246:249], v[64:79]
	ds_read_b128 v[234:237], v217 offset:8192
	ds_read_b128 v[242:245], v217 offset:12288
	s_waitcnt lgkmcnt(0)
	s_barrier
; #define GLOAD(k0) do { _Pragma("unroll") for (int i_ = 0; i_ < 2 * MI; ++i_) ra[i_] = *(const u32x4*)(Ap + (long)(64 * i_) * lda + (k0)); \
;     _Pragma("unroll") for (int i_ = 0; i_ < 2 * NC; ++i_) rb[i_] = *(const u32x4*)(Bp + (long)(64 * i_) * ldb + (k0)); } while (0)
; #define GWRITE(buf) do { char* a_ = As + (buf) * ABUF + rw * 128 + swz; char* b_ = Bs + (buf) * BBUF + rw * 128 + swz; \
;     _Pragma("unroll") for (int i_ = 0; i_ < 2 * MI; ++i_) *(u32x4*)(a_ + i_ * 64 * 128) = ra[i_]; \
;     _Pragma("unroll") for (int i_ = 0; i_ < 2 * NC; ++i_) *(u32x4*)(b_ + i_ * 64 * 128) = rb[i_]; } while (0)
; #define MFMA_ALL(kt_) mfma_tile<MI, NC>(acc, As + ((kt_) & 1) * ABUF, Bs + ((kt_) & 1) * BBUF, rowa0, rowb0, sa, sb, hi)
; #define KBAR() do { asm volatile("s_waitcnt lgkmcnt(0)" ::: "memory"); __builtin_amdgcn_s_barrier(); asm volatile("" ::: "memory"); } while (0)
; template <int MI, int NC>
; DEVI void mfma_tile(f32x16 (&acc)[2 * NC][MI], const char* Ab, const char* Bb, int rowa0, int rowb0, int sa, int sb, int hi) {
;     ...
;     for (int k16 = 0; k16 < 4; ++k16) {
;       const int chn = k16 * 2 + hi;
;       bf16x8 ga[2 * NC], gb[MI];
; #pragma unroll
;       for (int ni = 0; ni < 2 * NC; ++ni) ga[ni] = *(const bf16x8*)(Bb + (rowa0 + 32 * ni) * 128 + ((chn ^ sa) << 4));
; #pragma unroll
;       for (int mi = 0; mi < MI; ++mi) gb[mi] = *(const bf16x8*)(Ab + (rowb0 + 32 * mi) * 128 + ((chn ^ sb) << 4));
; #pragma unroll
;       for (int ni = 0; ni < 2 * NC; ++ni)
; #pragma unroll
;         for (int mi = 0; mi < MI; ++mi)
;           acc[ni][mi] = __builtin_amdgcn_mfma_f32_32x32x16_bf16(ga[ni], gb[mi], acc[ni][mi], 0, 0, 0);
;     }
; template <int MI, int NC>
; DEVI void gemm_kloop(f32x16 (&acc)[2 * NC][MI], const u16* __restrict__ A, long lda, const u16* __restrict__ Bt, long ldb, int K, char* lds) {
;     ...
;     for (int kt = 0; kt < KT; ++kt) {
;       if (kt + 1 < KT) { GWRITE((kt + 1) & 1); if (kt + 2 < KT) GLOAD((kt + 2) * 64); }
;       KBAR();
;       MFMA_ALL(kt);
;       KBAR();
;     }
	s_waitcnt lgkmcnt(1)
	v_mfma_f32_32x32x16_bf16 v[48:63], v[234:237], v[238:241], v[48:63]
	v_mfma_f32_32x32x16_bf16 v[16:31], v[234:237], v[246:249], v[16:31]
	s_waitcnt lgkmcnt(0)
	v_mfma_f32_32x32x16_bf16 v[32:47], v[242:245], v[238:241], v[32:47]
	v_mfma_f32_32x32x16_bf16 v[0:15], v[242:245], v[246:249], v[0:15]
	s_cbranch_scc0 .LBB0_133
	s_waitcnt vmcnt(7)
	ds_write_b128 v229, v[160:163] offset:32768
	s_waitcnt vmcnt(6)
	ds_write_b128 v229, v[164:167] offset:40960
	s_waitcnt vmcnt(5)
	ds_write_b128 v229, v[168:171] offset:49152
	s_waitcnt vmcnt(4)
	ds_write_b128 v229, v[172:175] offset:57344
	s_waitcnt vmcnt(3)
	ds_write_b128 v231, v[176:179] offset:32768
	s_waitcnt vmcnt(2)
	ds_write_b128 v231, v[180:183] offset:40960
	s_waitcnt vmcnt(1)
	ds_write_b128 v231, v[184:187] offset:49152
	s_waitcnt vmcnt(0)
	ds_write_b128 v231, v[188:191] offset:57344
	s_waitcnt lgkmcnt(0)
	s_barrier
	v_add3_u32 v176, s33, v232, v226
	ds_read_b128 v[160:163], v176
	v_add3_u32 v177, 16, v232, v233
	ds_read_b128 v[164:167], v177
	ds_read_b128 v[168:171], v176 offset:4096
	ds_read_b128 v[172:175], v177 offset:4096
	s_waitcnt lgkmcnt(1)
	v_mfma_f32_32x32x16_bf16 v[96:111], v[168:171], v[164:167], v[96:111]
	v_add3_u32 v178, 16, v230, v233
	v_add3_u32 v179, 16, v228, v233
	v_add3_u32 v180, 16, v227, v233
	v_readlane_b32 s3, v254, 5
	s_mov_b64 s[8:9], 0
	v_mfma_f32_32x32x16_bf16 v[112:127], v[160:163], v[164:167], v[112:127]
	s_waitcnt lgkmcnt(0)
	v_mfma_f32_32x32x16_bf16 v[80:95], v[160:163], v[172:175], v[80:95]
	v_mfma_f32_32x32x16_bf16 v[64:79], v[168:171], v[172:175], v[64:79]
	ds_read_b128 v[160:163], v176 offset:8192
	ds_read_b128 v[168:171], v176 offset:12288
	v_add3_u32 v176, s33, v230, v226
	s_waitcnt lgkmcnt(1)
	v_mfma_f32_32x32x16_bf16 v[48:63], v[160:163], v[164:167], v[48:63]
	v_mfma_f32_32x32x16_bf16 v[16:31], v[160:163], v[172:175], v[16:31]
	ds_read_b128 v[160:163], v176
	s_waitcnt lgkmcnt(1)
	v_mfma_f32_32x32x16_bf16 v[32:47], v[168:171], v[164:167], v[32:47]
	v_mfma_f32_32x32x16_bf16 v[0:15], v[168:171], v[172:175], v[0:15]
	ds_read_b128 v[164:167], v178
	ds_read_b128 v[168:171], v176 offset:4096
	ds_read_b128 v[172:175], v178 offset:4096
	s_waitcnt lgkmcnt(2)
	v_mfma_f32_32x32x16_bf16 v[112:127], v[160:163], v[164:167], v[112:127]
	s_waitcnt lgkmcnt(0)
	v_mfma_f32_32x32x16_bf16 v[80:95], v[160:163], v[172:175], v[80:95]
	v_mfma_f32_32x32x16_bf16 v[96:111], v[168:171], v[164:167], v[96:111]
	v_mfma_f32_32x32x16_bf16 v[64:79], v[168:171], v[172:175], v[64:79]
	ds_read_b128 v[160:163], v176 offset:8192
	ds_read_b128 v[168:171], v176 offset:12288
	v_add3_u32 v176, s33, v228, v226
	s_waitcnt lgkmcnt(1)
	v_mfma_f32_32x32x16_bf16 v[48:63], v[160:163], v[164:167], v[48:63]
	v_mfma_f32_32x32x16_bf16 v[16:31], v[160:163], v[172:175], v[16:31]
	ds_read_b128 v[160:163], v176
	s_waitcnt lgkmcnt(1)
	v_mfma_f32_32x32x16_bf16 v[32:47], v[168:171], v[164:167], v[32:47]
	v_mfma_f32_32x32x16_bf16 v[0:15], v[168:171], v[172:175], v[0:15]
	ds_read_b128 v[164:167], v179
	ds_read_b128 v[168:171], v176 offset:4096
	ds_read_b128 v[172:175], v179 offset:4096
	s_waitcnt lgkmcnt(2)
	v_mfma_f32_32x32x16_bf16 v[112:127], v[160:163], v[164:167], v[112:127]
	s_waitcnt lgkmcnt(0)
	v_mfma_f32_32x32x16_bf16 v[80:95], v[160:163], v[172:175], v[80:95]
	v_mfma_f32_32x32x16_bf16 v[96:111], v[168:171], v[164:167], v[96:111]
	v_mfma_f32_32x32x16_bf16 v[64:79], v[168:171], v[172:175], v[64:79]
	ds_read_b128 v[160:163], v176 offset:8192
	ds_read_b128 v[168:171], v176 offset:12288
	v_add3_u32 v176, s33, v227, v226
	s_waitcnt lgkmcnt(1)
	v_mfma_f32_32x32x16_bf16 v[48:63], v[160:163], v[164:167], v[48:63]
	v_mfma_f32_32x32x16_bf16 v[16:31], v[160:163], v[172:175], v[16:31]
	ds_read_b128 v[160:163], v176
	s_waitcnt lgkmcnt(1)
	v_mfma_f32_32x32x16_bf16 v[32:47], v[168:171], v[164:167], v[32:47]
	v_mfma_f32_32x32x16_bf16 v[0:15], v[168:171], v[172:175], v[0:15]
	ds_read_b128 v[164:167], v180
	ds_read_b128 v[168:171], v176 offset:4096
	ds_read_b128 v[172:175], v180 offset:4096
	s_waitcnt lgkmcnt(2)
	v_mfma_f32_32x32x16_bf16 v[112:127], v[160:163], v[164:167], v[112:127]
	s_waitcnt lgkmcnt(0)
	v_mfma_f32_32x32x16_bf16 v[80:95], v[160:163], v[172:175], v[80:95]
	v_mfma_f32_32x32x16_bf16 v[96:111], v[168:171], v[164:167], v[96:111]
	v_mfma_f32_32x32x16_bf16 v[64:79], v[168:171], v[172:175], v[64:79]
	ds_read_b128 v[160:163], v176 offset:8192
	ds_read_b128 v[168:171], v176 offset:12288
	s_waitcnt lgkmcnt(0)
	s_barrier
; #define GLOAD(k0) do { _Pragma("unroll") for (int i_ = 0; i_ < 2 * MI; ++i_) ra[i_] = *(const u32x4*)(Ap + (long)(64 * i_) * lda + (k0)); \
;     _Pragma("unroll") for (int i_ = 0; i_ < 2 * NC; ++i_) rb[i_] = *(const u32x4*)(Bp + (long)(64 * i_) * ldb + (k0)); } while (0)
; #define GWRITE(buf) do { char* a_ = As + (buf) * ABUF + rw * 128 + swz; char* b_ = Bs + (buf) * BBUF + rw * 128 + swz; \
;     _Pragma("unroll") for (int i_ = 0; i_ < 2 * MI; ++i_) *(u32x4*)(a_ + i_ * 64 * 128) = ra[i_]; \
;     _Pragma("unroll") for (int i_ = 0; i_ < 2 * NC; ++i_) *(u32x4*)(b_ + i_ * 64 * 128) = rb[i_]; } while (0)
; #define MFMA_ALL(kt_) mfma_tile<MI, NC>(acc, As + ((kt_) & 1) * ABUF, Bs + ((kt_) & 1) * BBUF, rowa0, rowb0, sa, sb, hi)
; #define KBAR() do { asm volatile("s_waitcnt lgkmcnt(0)" ::: "memory"); __builtin_amdgcn_s_barrier(); asm volatile("" ::: "memory"); } while (0)
; template <int MI, int NC>
; DEVI void mfma_tile(f32x16 (&acc)[2 * NC][MI], const char* Ab, const char* Bb, int rowa0, int rowb0, int sa, int sb, int hi) {
;     ...
;     for (int k16 = 0; k16 < 4; ++k16) {
;       const int chn = k16 * 2 + hi;
;       bf16x8 ga[2 * NC], gb[MI];
; #pragma unroll
;       for (int ni = 0; ni < 2 * NC; ++ni) ga[ni] = *(const bf16x8*)(Bb + (rowa0 + 32 * ni) * 128 + ((chn ^ sa) << 4));
; #pragma unroll
;       for (int mi = 0; mi < MI; ++mi) gb[mi] = *(const bf16x8*)(Ab + (rowb0 + 32 * mi) * 128 + ((chn ^ sb) << 4));
; #pragma unroll
;       for (int ni = 0; ni < 2 * NC; ++ni)
; #pragma unroll
;         for (int mi = 0; mi < MI; ++mi)
;           acc[ni][mi] = __builtin_amdgcn_mfma_f32_32x32x16_bf16(ga[ni], gb[mi], acc[ni][mi], 0, 0, 0);
;     }
; template <int MI, int NC>
; DEVI void gemm_kloop(f32x16 (&acc)[2 * NC][MI], const u16* __restrict__ A, long lda, const u16* __restrict__ Bt, long ldb, int K, char* lds) {
;     ...
;     for (int kt = 0; kt < KT; ++kt) {
;       if (kt + 1 < KT) { GWRITE((kt + 1) & 1); if (kt + 2 < KT) GLOAD((kt + 2) * 64); }
;       KBAR();
;       MFMA_ALL(kt);
;       KBAR();
;     }
	s_waitcnt lgkmcnt(0)
	s_barrier
	v_add3_u32 v176, s3, v232, v226
	s_waitcnt lgkmcnt(1)
	v_mfma_f32_32x32x16_bf16 v[48:63], v[160:163], v[164:167], v[48:63]
	v_mfma_f32_32x32x16_bf16 v[16:31], v[160:163], v[172:175], v[16:31]
	s_waitcnt lgkmcnt(0)
	v_mfma_f32_32x32x16_bf16 v[32:47], v[168:171], v[164:167], v[32:47]
	v_mfma_f32_32x32x16_bf16 v[0:15], v[168:171], v[172:175], v[0:15]
	ds_read_b128 v[160:163], v176
	ds_read_b128 v[164:167], v177 offset:32768
	ds_read_b128 v[168:171], v176 offset:4096
	ds_read_b128 v[172:175], v177 offset:36864
	s_waitcnt lgkmcnt(2)
	v_mfma_f32_32x32x16_bf16 v[112:127], v[160:163], v[164:167], v[112:127]
	s_waitcnt lgkmcnt(0)
	v_mfma_f32_32x32x16_bf16 v[80:95], v[160:163], v[172:175], v[80:95]
	v_mfma_f32_32x32x16_bf16 v[96:111], v[168:171], v[164:167], v[96:111]
	v_mfma_f32_32x32x16_bf16 v[64:79], v[168:171], v[172:175], v[64:79]
	ds_read_b128 v[160:163], v176 offset:8192
	ds_read_b128 v[168:171], v176 offset:12288
	v_add3_u32 v176, s3, v230, v226
	s_waitcnt lgkmcnt(1)
	v_mfma_f32_32x32x16_bf16 v[48:63], v[160:163], v[164:167], v[48:63]
	v_mfma_f32_32x32x16_bf16 v[16:31], v[160:163], v[172:175], v[16:31]
	s_waitcnt lgkmcnt(0)
	v_mfma_f32_32x32x16_bf16 v[32:47], v[168:171], v[164:167], v[32:47]
	v_mfma_f32_32x32x16_bf16 v[0:15], v[168:171], v[172:175], v[0:15]
	ds_read_b128 v[160:163], v176
	ds_read_b128 v[164:167], v178 offset:32768
	ds_read_b128 v[168:171], v176 offset:4096
	ds_read_b128 v[172:175], v178 offset:36864
	s_waitcnt lgkmcnt(2)
	v_mfma_f32_32x32x16_bf16 v[112:127], v[160:163], v[164:167], v[112:127]
	s_waitcnt lgkmcnt(0)
	v_mfma_f32_32x32x16_bf16 v[80:95], v[160:163], v[172:175], v[80:95]
	v_mfma_f32_32x32x16_bf16 v[96:111], v[168:171], v[164:167], v[96:111]
	v_mfma_f32_32x32x16_bf16 v[64:79], v[168:171], v[172:175], v[64:79]
	ds_read_b128 v[160:163], v176 offset:8192
	ds_read_b128 v[168:171], v176 offset:12288
	v_add3_u32 v176, s3, v228, v226
	s_waitcnt lgkmcnt(1)
	v_mfma_f32_32x32x16_bf16 v[48:63], v[160:163], v[164:167], v[48:63]
	v_mfma_f32_32x32x16_bf16 v[16:31], v[160:163], v[172:175], v[16:31]
	s_waitcnt lgkmcnt(0)
	v_mfma_f32_32x32x16_bf16 v[32:47], v[168:171], v[164:167], v[32:47]
	v_mfma_f32_32x32x16_bf16 v[0:15], v[168:171], v[172:175], v[0:15]
	ds_read_b128 v[160:163], v176
	ds_read_b128 v[164:167], v179 offset:32768
	ds_read_b128 v[168:171], v176 offset:4096
	ds_read_b128 v[172:175], v179 offset:36864
	s_waitcnt lgkmcnt(2)
	v_mfma_f32_32x32x16_bf16 v[112:127], v[160:163], v[164:167], v[112:127]
	s_waitcnt lgkmcnt(0)
	v_mfma_f32_32x32x16_bf16 v[80:95], v[160:163], v[172:175], v[80:95]
	v_mfma_f32_32x32x16_bf16 v[96:111], v[168:171], v[164:167], v[96:111]
	v_mfma_f32_32x32x16_bf16 v[64:79], v[168:171], v[172:175], v[64:79]
	ds_read_b128 v[160:163], v176 offset:8192
	ds_read_b128 v[168:171], v176 offset:12288
	v_add3_u32 v176, s3, v227, v226
	s_waitcnt lgkmcnt(1)
	v_mfma_f32_32x32x16_bf16 v[48:63], v[160:163], v[164:167], v[48:63]
	v_mfma_f32_32x32x16_bf16 v[16:31], v[160:163], v[172:175], v[16:31]
	s_waitcnt lgkmcnt(0)
	v_mfma_f32_32x32x16_bf16 v[32:47], v[168:171], v[164:167], v[32:47]
	v_mfma_f32_32x32x16_bf16 v[0:15], v[168:171], v[172:175], v[0:15]
	ds_read_b128 v[160:163], v176
	ds_read_b128 v[164:167], v180 offset:32768
	ds_read_b128 v[168:171], v176 offset:4096
	ds_read_b128 v[172:175], v180 offset:36864
	s_waitcnt lgkmcnt(2)
	v_mfma_f32_32x32x16_bf16 v[112:127], v[160:163], v[164:167], v[112:127]
	s_waitcnt lgkmcnt(0)
	v_mfma_f32_32x32x16_bf16 v[80:95], v[160:163], v[172:175], v[80:95]
	v_mfma_f32_32x32x16_bf16 v[96:111], v[168:171], v[164:167], v[96:111]
	v_mfma_f32_32x32x16_bf16 v[64:79], v[168:171], v[172:175], v[64:79]
	ds_read_b128 v[160:163], v176 offset:8192
	ds_read_b128 v[168:171], v176 offset:12288
	s_waitcnt lgkmcnt(0)
	s_barrier
	s_waitcnt lgkmcnt(1)
	v_mfma_f32_32x32x16_bf16 v[48:63], v[160:163], v[164:167], v[48:63]
	v_mfma_f32_32x32x16_bf16 v[16:31], v[160:163], v[172:175], v[16:31]
	s_waitcnt lgkmcnt(0)
	v_mfma_f32_32x32x16_bf16 v[32:47], v[168:171], v[164:167], v[32:47]
	v_mfma_f32_32x32x16_bf16 v[0:15], v[168:171], v[172:175], v[0:15]

; #define GLOAD(k0) do { _Pragma("unroll") for (int i_ = 0; i_ < 2 * MI; ++i_) ra[i_] = *(const u32x4*)(Ap + (long)(64 * i_) * lda + (k0)); \
;     _Pragma("unroll") for (int i_ = 0; i_ < 2 * NC; ++i_) rb[i_] = *(const u32x4*)(Bp + (long)(64 * i_) * ldb + (k0)); } while (0)
; #define GWRITE(buf) do { char* a_ = As + (buf) * ABUF + rw * 128 + swz; char* b_ = Bs + (buf) * BBUF + rw * 128 + swz; \
;     _Pragma("unroll") for (int i_ = 0; i_ < 2 * MI; ++i_) *(u32x4*)(a_ + i_ * 64 * 128) = ra[i_]; \
;     _Pragma("unroll") for (int i_ = 0; i_ < 2 * NC; ++i_) *(u32x4*)(b_ + i_ * 64 * 128) = rb[i_]; } while (0)
; #define MFMA_ALL(kt_) mfma_tile<MI, NC>(acc, As + ((kt_) & 1) * ABUF, Bs + ((kt_) & 1) * BBUF, rowa0, rowb0, sa, sb, hi)
; #define KBAR() do { asm volatile("s_waitcnt lgkmcnt(0)" ::: "memory"); __builtin_amdgcn_s_barrier(); asm volatile("" ::: "memory"); } while (0)
; template <int MI, int NC>
; DEVI void mfma_tile(f32x16 (&acc)[2 * NC][MI], const char* Ab, const char* Bb, int rowa0, int rowb0, int sa, int sb, int hi) {
;     ...
;     for (int k16 = 0; k16 < 4; ++k16) {
;       const int chn = k16 * 2 + hi;
;       bf16x8 ga[2 * NC], gb[MI];
; #pragma unroll
;       for (int ni = 0; ni < 2 * NC; ++ni) ga[ni] = *(const bf16x8*)(Bb + (rowa0 + 32 * ni) * 128 + ((chn ^ sa) << 4));
; #pragma unroll
;       for (int mi = 0; mi < MI; ++mi) gb[mi] = *(const bf16x8*)(Ab + (rowb0 + 32 * mi) * 128 + ((chn ^ sb) << 4));
; #pragma unroll
;       for (int ni = 0; ni < 2 * NC; ++ni)
; #pragma unroll
;         for (int mi = 0; mi < MI; ++mi)
;           acc[ni][mi] = __builtin_amdgcn_mfma_f32_32x32x16_bf16(ga[ni], gb[mi], acc[ni][mi], 0, 0, 0);
;     }
; template <int MI, int NC>
; DEVI void gemm_kloop(f32x16 (&acc)[2 * NC][MI], const u16* __restrict__ A, long lda, const u16* __restrict__ Bt, long ldb, int K, char* lds) {
;     ...
;     for (int kt = 0; kt < KT; ++kt) {
;       MFMA_ALL(kt);
;       KBAR();
;       if (kt + 1 < KT) { GWRITE((kt + 1) & 1); if (kt + 2 < KT) GLOAD((kt + 2) * 64); }
;       KBAR();
;     }
.LBB0_137:
	s_add_i32 s8, s3, 0xffff8000
	s_and_b32 s8, s8, 0x8000
	s_add_i32 s8, s8, 16
	s_add_i32 s9, s8, 0x10000
	v_add3_u32 v176, s9, v232, v226
	v_add3_u32 v184, s8, v232, v233
	ds_read_b128 v[164:167], v176
	ds_read_b128 v[168:171], v176 offset:4096
	ds_read_b128 v[172:175], v176 offset:8192
	ds_read_b128 v[176:179], v176 offset:12288
	ds_read_b128 v[180:183], v184
	ds_read_b128 v[184:187], v184 offset:4096
	s_waitcnt lgkmcnt(1)
	v_mfma_f32_32x32x16_bf16 v[112:127], v[164:167], v[180:183], v[112:127]
	s_waitcnt lgkmcnt(0)
	v_mfma_f32_32x32x16_bf16 v[80:95], v[164:167], v[184:187], v[80:95]
	v_mfma_f32_32x32x16_bf16 v[64:79], v[168:171], v[184:187], v[64:79]
	v_mfma_f32_32x32x16_bf16 v[16:31], v[172:175], v[184:187], v[16:31]
	v_mfma_f32_32x32x16_bf16 v[32:47], v[176:179], v[180:183], v[32:47]
	v_mfma_f32_32x32x16_bf16 v[0:15], v[176:179], v[184:187], v[0:15]
	v_add3_u32 v176, s9, v230, v226
	v_add3_u32 v184, s8, v230, v233
	v_mfma_f32_32x32x16_bf16 v[96:111], v[168:171], v[180:183], v[96:111]
	v_mfma_f32_32x32x16_bf16 v[48:63], v[172:175], v[180:183], v[48:63]
	ds_read_b128 v[164:167], v176
	ds_read_b128 v[168:171], v176 offset:4096
	ds_read_b128 v[172:175], v176 offset:8192
	ds_read_b128 v[176:179], v176 offset:12288
	ds_read_b128 v[180:183], v184
	ds_read_b128 v[184:187], v184 offset:4096
	s_waitcnt lgkmcnt(1)
	v_mfma_f32_32x32x16_bf16 v[112:127], v[164:167], v[180:183], v[112:127]
	s_waitcnt lgkmcnt(0)
	v_mfma_f32_32x32x16_bf16 v[80:95], v[164:167], v[184:187], v[80:95]
	v_mfma_f32_32x32x16_bf16 v[64:79], v[168:171], v[184:187], v[64:79]
	v_mfma_f32_32x32x16_bf16 v[16:31], v[172:175], v[184:187], v[16:31]
	v_mfma_f32_32x32x16_bf16 v[32:47], v[176:179], v[180:183], v[32:47]
	v_mfma_f32_32x32x16_bf16 v[0:15], v[176:179], v[184:187], v[0:15]
	v_add3_u32 v176, s9, v228, v226
	v_add3_u32 v184, s8, v228, v233
	v_mfma_f32_32x32x16_bf16 v[96:111], v[168:171], v[180:183], v[96:111]
	v_mfma_f32_32x32x16_bf16 v[48:63], v[172:175], v[180:183], v[48:63]
	ds_read_b128 v[164:167], v176
	ds_read_b128 v[168:171], v176 offset:4096
	ds_read_b128 v[172:175], v176 offset:8192
	ds_read_b128 v[176:179], v176 offset:12288
	ds_read_b128 v[180:183], v184
	ds_read_b128 v[184:187], v184 offset:4096
	s_waitcnt lgkmcnt(1)
	v_mfma_f32_32x32x16_bf16 v[112:127], v[164:167], v[180:183], v[112:127]
	s_waitcnt lgkmcnt(0)
	v_mfma_f32_32x32x16_bf16 v[80:95], v[164:167], v[184:187], v[80:95]
	v_mfma_f32_32x32x16_bf16 v[64:79], v[168:171], v[184:187], v[64:79]
	v_mfma_f32_32x32x16_bf16 v[16:31], v[172:175], v[184:187], v[16:31]
	v_mfma_f32_32x32x16_bf16 v[32:47], v[176:179], v[180:183], v[32:47]
	v_mfma_f32_32x32x16_bf16 v[0:15], v[176:179], v[184:187], v[0:15]
	v_add3_u32 v176, s9, v227, v226
	v_add3_u32 v184, s8, v227, v233
	s_and_b32 s8, s3, 0x8000
	v_mfma_f32_32x32x16_bf16 v[96:111], v[168:171], v[180:183], v[96:111]
	v_mfma_f32_32x32x16_bf16 v[48:63], v[172:175], v[180:183], v[48:63]
	ds_read_b128 v[164:167], v176
	ds_read_b128 v[168:171], v176 offset:4096
	ds_read_b128 v[172:175], v176 offset:8192
	ds_read_b128 v[176:179], v176 offset:12288
	ds_read_b128 v[180:183], v184
	ds_read_b128 v[184:187], v184 offset:4096
	s_waitcnt lgkmcnt(0)
	s_barrier
	s_waitcnt lgkmcnt(1)
	v_mfma_f32_32x32x16_bf16 v[112:127], v[164:167], v[180:183], v[112:127]
	s_waitcnt lgkmcnt(0)
	v_mfma_f32_32x32x16_bf16 v[80:95], v[164:167], v[184:187], v[80:95]
	v_add_u32_e32 v164, s8, v229
	s_waitcnt vmcnt(5)
	ds_write_b128 v164, v[132:135]
	ds_write_b128 v164, v[128:131] offset:8192
	s_waitcnt vmcnt(4)
	ds_write_b128 v164, v[136:139] offset:16384
	s_waitcnt vmcnt(3)
	ds_write_b128 v164, v[140:143] offset:24576
	v_add_u32_e32 v128, s8, v231
	v_lshl_add_u64 v[140:141], v[162:163], 0, s[6:7]
	ds_write_b128 v128, v[144:147]
	s_waitcnt vmcnt(2)
	ds_write_b128 v128, v[148:151] offset:8192
	s_waitcnt vmcnt(1)
	ds_write_b128 v128, v[152:155] offset:16384
	s_waitcnt vmcnt(0)
	ds_write_b128 v128, v[156:159] offset:24576
	v_add_co_u32_e32 v128, vcc, s34, v140
	v_lshl_add_u64 v[156:157], v[160:161], 0, s[6:7]
	s_nop 0
	v_addc_co_u32_e32 v129, vcc, 0, v141, vcc
	global_load_dwordx4 v[132:135], v[128:129], off offset:2304
	global_load_dwordx4 v[144:147], v[156:157], off offset:256
	v_add_co_u32_e32 v128, vcc, s35, v140
	v_mfma_f32_32x32x16_bf16 v[96:111], v[168:171], v[180:183], v[96:111]
	s_nop 0
	v_addc_co_u32_e32 v129, vcc, 0, v141, vcc
	v_add_co_u32_e32 v136, vcc, s86, v140
	global_load_dwordx4 v[128:131], v[128:129], off offset:2304
	s_nop 0
	v_addc_co_u32_e32 v137, vcc, 0, v141, vcc
	v_add_co_u32_e32 v140, vcc, s87, v140
	global_load_dwordx4 v[136:139], v[136:137], off offset:2304
	s_nop 0
	v_addc_co_u32_e32 v141, vcc, 0, v141, vcc
	v_add_co_u32_e32 v148, vcc, s25, v156
	global_load_dwordx4 v[140:143], v[140:141], off offset:2304
	s_nop 0
	v_addc_co_u32_e32 v149, vcc, 0, v157, vcc
	v_add_co_u32_e32 v152, vcc, s21, v156
	global_load_dwordx4 v[148:151], v[148:149], off offset:256
	s_nop 0
	v_addc_co_u32_e32 v153, vcc, 0, v157, vcc
	v_add_co_u32_e32 v156, vcc, s97, v156
	global_load_dwordx4 v[152:155], v[152:153], off offset:256
	s_nop 0
	v_addc_co_u32_e32 v157, vcc, 0, v157, vcc
	global_load_dwordx4 v[156:159], v[156:157], off offset:256
	v_mfma_f32_32x32x16_bf16 v[64:79], v[168:171], v[184:187], v[64:79]
	s_waitcnt lgkmcnt(0)
	s_barrier
	s_add_u32 s6, s6, 0x80
	s_addc_u32 s7, s7, 0
	s_add_i32 s3, s3, 0x8000
	s_cmpk_eq_i32 s6, 0x700
	v_mfma_f32_32x32x16_bf16 v[48:63], v[172:175], v[180:183], v[48:63]
	v_mfma_f32_32x32x16_bf16 v[16:31], v[172:175], v[184:187], v[16:31]
	v_mfma_f32_32x32x16_bf16 v[32:47], v[176:179], v[180:183], v[32:47]
	v_mfma_f32_32x32x16_bf16 v[0:15], v[176:179], v[184:187], v[0:15]
	s_cbranch_scc0 .LBB0_137
; #define GLOAD(k0) do { _Pragma("unroll") for (int i_ = 0; i_ < 2 * MI; ++i_) ra[i_] = *(const u32x4*)(Ap + (long)(64 * i_) * lda + (k0)); \
;     _Pragma("unroll") for (int i_ = 0; i_ < 2 * NC; ++i_) rb[i_] = *(const u32x4*)(Bp + (long)(64 * i_) * ldb + (k0)); } while (0)
; #define GWRITE(buf) do { char* a_ = As + (buf) * ABUF + rw * 128 + swz; char* b_ = Bs + (buf) * BBUF + rw * 128 + swz; \
;     _Pragma("unroll") for (int i_ = 0; i_ < 2 * MI; ++i_) *(u32x4*)(a_ + i_ * 64 * 128) = ra[i_]; \
;     _Pragma("unroll") for (int i_ = 0; i_ < 2 * NC; ++i_) *(u32x4*)(b_ + i_ * 64 * 128) = rb[i_]; } while (0)
; #define MFMA_ALL(kt_) mfma_tile<MI, NC>(acc, As + ((kt_) & 1) * ABUF, Bs + ((kt_) & 1) * BBUF, rowa0, rowb0, sa, sb, hi)
; #define KBAR() do { asm volatile("s_waitcnt lgkmcnt(0)" ::: "memory"); __builtin_amdgcn_s_barrier(); asm volatile("" ::: "memory"); } while (0)
; template <int MI, int NC>
; DEVI void mfma_tile(f32x16 (&acc)[2 * NC][MI], const char* Ab, const char* Bb, int rowa0, int rowb0, int sa, int sb, int hi) {
;     ...
;     for (int k16 = 0; k16 < 4; ++k16) {
;       const int chn = k16 * 2 + hi;
;       bf16x8 ga[2 * NC], gb[MI];
; #pragma unroll
;       for (int ni = 0; ni < 2 * NC; ++ni) ga[ni] = *(const bf16x8*)(Bb + (rowa0 + 32 * ni) * 128 + ((chn ^ sa) << 4));
; #pragma unroll
;       for (int mi = 0; mi < MI; ++mi) gb[mi] = *(const bf16x8*)(Ab + (rowb0 + 32 * mi) * 128 + ((chn ^ sb) << 4));
; #pragma unroll
;       for (int ni = 0; ni < 2 * NC; ++ni)
; #pragma unroll
;         for (int mi = 0; mi < MI; ++mi)
;           acc[ni][mi] = __builtin_amdgcn_mfma_f32_32x32x16_bf16(ga[ni], gb[mi], acc[ni][mi], 0, 0, 0);
;     }
; template <int MI, int NC>
; DEVI void gemm_kloop(f32x16 (&acc)[2 * NC][MI], const u16* __restrict__ A, long lda, const u16* __restrict__ Bt, long ldb, int K, char* lds) {
;     ...
;     for (int kt = 0; kt < KT; ++kt) {
;       MFMA_ALL(kt);
;       KBAR();
;       if (kt + 1 < KT) { GWRITE((kt + 1) & 1); if (kt + 2 < KT) GLOAD((kt + 2) * 64); }
;       KBAR();
;     }
	v_add3_u32 v172, s33, v232, v226
	ds_read_b128 v[160:163], v172
	v_add3_u32 v173, 16, v232, v233
	ds_read_b128 v[164:167], v173
	ds_read_b128 v[168:171], v173 offset:4096
	v_add3_u32 v174, 16, v230, v233
	v_add3_u32 v175, 16, v228, v233
	v_add3_u32 v176, 16, v227, v233
	v_readlane_b32 s3, v254, 5
	s_waitcnt lgkmcnt(1)
	v_mfma_f32_32x32x16_bf16 v[112:127], v[160:163], v[164:167], v[112:127]
	s_waitcnt lgkmcnt(0)
	v_mfma_f32_32x32x16_bf16 v[80:95], v[160:163], v[168:171], v[80:95]
	ds_read_b128 v[160:163], v172 offset:4096
	s_waitcnt lgkmcnt(0)
	v_mfma_f32_32x32x16_bf16 v[96:111], v[160:163], v[164:167], v[96:111]
	v_mfma_f32_32x32x16_bf16 v[64:79], v[160:163], v[168:171], v[64:79]
	ds_read_b128 v[160:163], v172 offset:8192
	s_waitcnt lgkmcnt(0)
	v_mfma_f32_32x32x16_bf16 v[48:63], v[160:163], v[164:167], v[48:63]
	v_mfma_f32_32x32x16_bf16 v[16:31], v[160:163], v[168:171], v[16:31]
	ds_read_b128 v[160:163], v172 offset:12288
	v_add3_u32 v172, s33, v230, v226
	s_waitcnt lgkmcnt(0)
	v_mfma_f32_32x32x16_bf16 v[32:47], v[160:163], v[164:167], v[32:47]
	ds_read_b128 v[164:167], v174
	v_mfma_f32_32x32x16_bf16 v[0:15], v[160:163], v[168:171], v[0:15]
	ds_read_b128 v[160:163], v172
	ds_read_b128 v[168:171], v174 offset:4096
	s_waitcnt lgkmcnt(1)
	v_mfma_f32_32x32x16_bf16 v[112:127], v[160:163], v[164:167], v[112:127]
	s_waitcnt lgkmcnt(0)
	v_mfma_f32_32x32x16_bf16 v[80:95], v[160:163], v[168:171], v[80:95]
	ds_read_b128 v[160:163], v172 offset:4096
	s_waitcnt lgkmcnt(0)
	v_mfma_f32_32x32x16_bf16 v[96:111], v[160:163], v[164:167], v[96:111]
	v_mfma_f32_32x32x16_bf16 v[64:79], v[160:163], v[168:171], v[64:79]
	ds_read_b128 v[160:163], v172 offset:8192
	s_waitcnt lgkmcnt(0)
	v_mfma_f32_32x32x16_bf16 v[48:63], v[160:163], v[164:167], v[48:63]
	v_mfma_f32_32x32x16_bf16 v[16:31], v[160:163], v[168:171], v[16:31]
	ds_read_b128 v[160:163], v172 offset:12288
	v_add3_u32 v172, s33, v228, v226
	s_waitcnt lgkmcnt(0)
	v_mfma_f32_32x32x16_bf16 v[32:47], v[160:163], v[164:167], v[32:47]
	ds_read_b128 v[164:167], v175
	v_mfma_f32_32x32x16_bf16 v[0:15], v[160:163], v[168:171], v[0:15]
	ds_read_b128 v[160:163], v172
	ds_read_b128 v[168:171], v175 offset:4096
	s_waitcnt lgkmcnt(1)
	v_mfma_f32_32x32x16_bf16 v[112:127], v[160:163], v[164:167], v[112:127]
	s_waitcnt lgkmcnt(0)
	v_mfma_f32_32x32x16_bf16 v[80:95], v[160:163], v[168:171], v[80:95]
	ds_read_b128 v[160:163], v172 offset:4096
	s_waitcnt lgkmcnt(0)
	v_mfma_f32_32x32x16_bf16 v[96:111], v[160:163], v[164:167], v[96:111]
	v_mfma_f32_32x32x16_bf16 v[64:79], v[160:163], v[168:171], v[64:79]
	ds_read_b128 v[160:163], v172 offset:8192
	s_waitcnt lgkmcnt(0)
	v_mfma_f32_32x32x16_bf16 v[48:63], v[160:163], v[164:167], v[48:63]
	v_mfma_f32_32x32x16_bf16 v[16:31], v[160:163], v[168:171], v[16:31]
	ds_read_b128 v[160:163], v172 offset:12288
	v_add3_u32 v172, s33, v227, v226
	s_waitcnt lgkmcnt(0)
	v_mfma_f32_32x32x16_bf16 v[32:47], v[160:163], v[164:167], v[32:47]
	ds_read_b128 v[164:167], v176
	v_mfma_f32_32x32x16_bf16 v[0:15], v[160:163], v[168:171], v[0:15]
	ds_read_b128 v[160:163], v172
	ds_read_b128 v[168:171], v176 offset:4096
	s_waitcnt lgkmcnt(1)
	v_mfma_f32_32x32x16_bf16 v[112:127], v[160:163], v[164:167], v[112:127]
	s_waitcnt lgkmcnt(0)
	v_mfma_f32_32x32x16_bf16 v[80:95], v[160:163], v[168:171], v[80:95]
	ds_read_b128 v[160:163], v172 offset:4096
	s_waitcnt lgkmcnt(0)
	v_mfma_f32_32x32x16_bf16 v[96:111], v[160:163], v[164:167], v[96:111]
	v_mfma_f32_32x32x16_bf16 v[64:79], v[160:163], v[168:171], v[64:79]
	ds_read_b128 v[160:163], v172 offset:8192
	s_waitcnt lgkmcnt(0)
	v_mfma_f32_32x32x16_bf16 v[48:63], v[160:163], v[164:167], v[48:63]
	v_mfma_f32_32x32x16_bf16 v[16:31], v[160:163], v[168:171], v[16:31]
	ds_read_b128 v[160:163], v172 offset:12288
	s_waitcnt lgkmcnt(0)
	s_barrier
	s_waitcnt vmcnt(7)
	ds_write_b128 v229, v[132:135] offset:32768
	s_waitcnt vmcnt(5)
	ds_write_b128 v229, v[128:131] offset:40960
	s_waitcnt vmcnt(4)
	ds_write_b128 v229, v[136:139] offset:49152
	s_waitcnt vmcnt(3)
	ds_write_b128 v229, v[140:143] offset:57344
	ds_write_b128 v231, v[144:147] offset:32768
	s_waitcnt vmcnt(2)
	ds_write_b128 v231, v[148:151] offset:40960
	s_waitcnt vmcnt(1)
	ds_write_b128 v231, v[152:155] offset:49152
	s_waitcnt vmcnt(0)
	ds_write_b128 v231, v[156:159] offset:57344
	s_waitcnt lgkmcnt(0)
	s_barrier
; #define GLOAD(k0) do { _Pragma("unroll") for (int i_ = 0; i_ < 2 * MI; ++i_) ra[i_] = *(const u32x4*)(Ap + (long)(64 * i_) * lda + (k0)); \
;     _Pragma("unroll") for (int i_ = 0; i_ < 2 * NC; ++i_) rb[i_] = *(const u32x4*)(Bp + (long)(64 * i_) * ldb + (k0)); } while (0)
; #define GWRITE(buf) do { char* a_ = As + (buf) * ABUF + rw * 128 + swz; char* b_ = Bs + (buf) * BBUF + rw * 128 + swz; \
;     _Pragma("unroll") for (int i_ = 0; i_ < 2 * MI; ++i_) *(u32x4*)(a_ + i_ * 64 * 128) = ra[i_]; \
;     _Pragma("unroll") for (int i_ = 0; i_ < 2 * NC; ++i_) *(u32x4*)(b_ + i_ * 64 * 128) = rb[i_]; } while (0)
; #define MFMA_ALL(kt_) mfma_tile<MI, NC>(acc, As + ((kt_) & 1) * ABUF, Bs + ((kt_) & 1) * BBUF, rowa0, rowb0, sa, sb, hi)
; #define KBAR() do { asm volatile("s_waitcnt lgkmcnt(0)" ::: "memory"); __builtin_amdgcn_s_barrier(); asm volatile("" ::: "memory"); } while (0)
; template <int MI, int NC>
; DEVI void mfma_tile(f32x16 (&acc)[2 * NC][MI], const char* Ab, const char* Bb, int rowa0, int rowb0, int sa, int sb, int hi) {
;     ...
;     for (int k16 = 0; k16 < 4; ++k16) {
;       const int chn = k16 * 2 + hi;
;       bf16x8 ga[2 * NC], gb[MI];
; #pragma unroll
;       for (int ni = 0; ni < 2 * NC; ++ni) ga[ni] = *(const bf16x8*)(Bb + (rowa0 + 32 * ni) * 128 + ((chn ^ sa) << 4));
; #pragma unroll
;       for (int mi = 0; mi < MI; ++mi) gb[mi] = *(const bf16x8*)(Ab + (rowb0 + 32 * mi) * 128 + ((chn ^ sb) << 4));
; #pragma unroll
;       for (int ni = 0; ni < 2 * NC; ++ni)
; #pragma unroll
;         for (int mi = 0; mi < MI; ++mi)
;           acc[ni][mi] = __builtin_amdgcn_mfma_f32_32x32x16_bf16(ga[ni], gb[mi], acc[ni][mi], 0, 0, 0);
;     }
; template <int MI, int NC>
; DEVI void gemm_kloop(f32x16 (&acc)[2 * NC][MI], const u16* __restrict__ A, long lda, const u16* __restrict__ Bt, long ldb, int K, char* lds) {
;     ...
;     for (int kt = 0; kt < KT; ++kt) {
;       MFMA_ALL(kt);
;       KBAR();
;       if (kt + 1 < KT) { GWRITE((kt + 1) & 1); if (kt + 2 < KT) GLOAD((kt + 2) * 64); }
;       KBAR();
;     }
	v_add3_u32 v140, s3, v232, v226
	ds_read_b128 v[128:131], v140
	ds_read_b128 v[132:135], v173 offset:32768
	ds_read_b128 v[136:139], v173 offset:36864
	s_waitcnt lgkmcnt(1)
	v_mfma_f32_32x32x16_bf16 v[112:127], v[128:131], v[132:135], v[112:127]
	s_waitcnt lgkmcnt(0)
	v_mfma_f32_32x32x16_bf16 v[80:95], v[128:131], v[136:139], v[80:95]
	ds_read_b128 v[128:131], v140 offset:4096
	s_waitcnt lgkmcnt(0)
	v_mfma_f32_32x32x16_bf16 v[96:111], v[128:131], v[132:135], v[96:111]
	v_mfma_f32_32x32x16_bf16 v[64:79], v[128:131], v[136:139], v[64:79]
	ds_read_b128 v[128:131], v140 offset:8192
	s_waitcnt lgkmcnt(0)
	v_mfma_f32_32x32x16_bf16 v[48:63], v[128:131], v[132:135], v[48:63]
	v_mfma_f32_32x32x16_bf16 v[16:31], v[128:131], v[136:139], v[16:31]
	ds_read_b128 v[128:131], v140 offset:12288
	v_add3_u32 v140, s3, v230, v226
	v_mfma_f32_32x32x16_bf16 v[32:47], v[160:163], v[164:167], v[32:47]
	v_mfma_f32_32x32x16_bf16 v[0:15], v[160:163], v[168:171], v[0:15]
	s_waitcnt lgkmcnt(0)
	v_mfma_f32_32x32x16_bf16 v[32:47], v[128:131], v[132:135], v[32:47]
	v_mfma_f32_32x32x16_bf16 v[0:15], v[128:131], v[136:139], v[0:15]
	ds_read_b128 v[128:131], v140
	ds_read_b128 v[132:135], v174 offset:32768
	ds_read_b128 v[136:139], v174 offset:36864
	s_waitcnt lgkmcnt(1)
	v_mfma_f32_32x32x16_bf16 v[112:127], v[128:131], v[132:135], v[112:127]
	s_waitcnt lgkmcnt(0)
	v_mfma_f32_32x32x16_bf16 v[80:95], v[128:131], v[136:139], v[80:95]
	ds_read_b128 v[128:131], v140 offset:4096
	s_waitcnt lgkmcnt(0)
	v_mfma_f32_32x32x16_bf16 v[96:111], v[128:131], v[132:135], v[96:111]
	v_mfma_f32_32x32x16_bf16 v[64:79], v[128:131], v[136:139], v[64:79]
	ds_read_b128 v[128:131], v140 offset:8192
	s_waitcnt lgkmcnt(0)
	v_mfma_f32_32x32x16_bf16 v[48:63], v[128:131], v[132:135], v[48:63]
	v_mfma_f32_32x32x16_bf16 v[16:31], v[128:131], v[136:139], v[16:31]
	ds_read_b128 v[128:131], v140 offset:12288
	v_add3_u32 v140, s3, v228, v226
	s_waitcnt lgkmcnt(0)
	v_mfma_f32_32x32x16_bf16 v[32:47], v[128:131], v[132:135], v[32:47]
	v_mfma_f32_32x32x16_bf16 v[0:15], v[128:131], v[136:139], v[0:15]
	ds_read_b128 v[128:131], v140
	ds_read_b128 v[132:135], v175 offset:32768
	ds_read_b128 v[136:139], v175 offset:36864
	s_waitcnt lgkmcnt(1)
	v_mfma_f32_32x32x16_bf16 v[112:127], v[128:131], v[132:135], v[112:127]
	s_waitcnt lgkmcnt(0)
	v_mfma_f32_32x32x16_bf16 v[80:95], v[128:131], v[136:139], v[80:95]
	ds_read_b128 v[128:131], v140 offset:4096
	s_waitcnt lgkmcnt(0)
	v_mfma_f32_32x32x16_bf16 v[96:111], v[128:131], v[132:135], v[96:111]
	v_mfma_f32_32x32x16_bf16 v[64:79], v[128:131], v[136:139], v[64:79]
	ds_read_b128 v[128:131], v140 offset:8192
	s_waitcnt lgkmcnt(0)
	v_mfma_f32_32x32x16_bf16 v[48:63], v[128:131], v[132:135], v[48:63]
	v_mfma_f32_32x32x16_bf16 v[16:31], v[128:131], v[136:139], v[16:31]
	ds_read_b128 v[128:131], v140 offset:12288
	v_add3_u32 v140, s3, v227, v226
	s_waitcnt lgkmcnt(0)
	v_mfma_f32_32x32x16_bf16 v[32:47], v[128:131], v[132:135], v[32:47]
	v_mfma_f32_32x32x16_bf16 v[0:15], v[128:131], v[136:139], v[0:15]
	ds_read_b128 v[128:131], v140
	ds_read_b128 v[132:135], v176 offset:32768
	ds_read_b128 v[136:139], v176 offset:36864
	s_waitcnt lgkmcnt(1)
	v_mfma_f32_32x32x16_bf16 v[112:127], v[128:131], v[132:135], v[112:127]
	s_waitcnt lgkmcnt(0)
	v_mfma_f32_32x32x16_bf16 v[80:95], v[128:131], v[136:139], v[80:95]
	ds_read_b128 v[128:131], v140 offset:4096
	s_waitcnt lgkmcnt(0)
	v_mfma_f32_32x32x16_bf16 v[96:111], v[128:131], v[132:135], v[96:111]
	v_mfma_f32_32x32x16_bf16 v[64:79], v[128:131], v[136:139], v[64:79]
	ds_read_b128 v[128:131], v140 offset:8192
	s_waitcnt lgkmcnt(0)
	v_mfma_f32_32x32x16_bf16 v[48:63], v[128:131], v[132:135], v[48:63]
	v_mfma_f32_32x32x16_bf16 v[16:31], v[128:131], v[136:139], v[16:31]
	ds_read_b128 v[128:131], v140 offset:12288
	s_waitcnt lgkmcnt(0)
	s_barrier
	s_waitcnt lgkmcnt(0)
	s_barrier
	s_waitcnt lgkmcnt(0)
	v_mfma_f32_32x32x16_bf16 v[32:47], v[128:131], v[132:135], v[32:47]
	v_mfma_f32_32x32x16_bf16 v[0:15], v[128:131], v[136:139], v[0:15]

; DEVI int otid() { int t = threadIdx.x; asm volatile("" : "+v"(t)); return t; }
; DEVI float wave_sum(float v) {
; #pragma unroll
;   for (int m = 32; m >= 1; m >>= 1) v += __shfl_xor(v, m);
;   return v;
; DEVI void phase_prep(const Params& p, int l) {
;   const int lane = otid() & 63;
;   const int gw = blockIdx.x * 8 + (otid() >> 6), nw = gridDim.x * 8;
;   const float lam_init = 0.8f - 0.6f * expf(-0.3f * (float)l);
;   const float* dl = p.diff_lam + l * 256;
;   const float s01 = wave_sum(dl[lane] * dl[64 + lane]), s23 = wave_sum(dl[128 + lane] * dl[192 + lane]);
;   const float lam = expf(s01) - expf(s23) + lam_init;
;   const u16* feat = (const u16*)(p.ws + OFF_FEAT);
;   const u16* og0 = (const u16*)(p.ws + OFF_OG); const u16* og1 = og0 + (long)RP * 1024;
;   const u16* od0 = (const u16*)(p.ws + OFF_OD); const u16* od1 = od0 + (long)RP * 1024;
;   u16* ya = (u16*)(p.ws + OFF_YA); u16* yb = (u16*)(p.ws + OFF_YB);
;   const f32x4 gg = *(const f32x4*)(p.gla_norm_g + l * 256 + lane * 4);
;   const float dg0 = p.diff_norm_g[l * 128 + lane * 2] * (1.f - lam_init), dg1 = p.diff_norm_g[l * 128 + lane * 2 + 1] * (1.f - lam_init);
;   for (int r = gw; r < RP; r += nw) {
.LBB0_492:
	s_or_b64 exec, exec, s[2:3]
	s_lshl_b32 s36, s70, 8
	v_readlane_b32 s68, v252, 2
	v_readlane_b32 s69, v252, 3
	v_readlane_b32 s70, v252, 4
	v_readlane_b32 s71, v252, 5
	v_readlane_b32 s72, v252, 6
	v_readlane_b32 s73, v252, 7
	v_readlane_b32 s74, v252, 8
	v_readlane_b32 s75, v252, 9
	s_mov_b64 s[8:9], s[68:69]
	v_mov_b32_e32 v6, v208
	s_lshl_b64 s[2:3], s[36:37], 2
	s_mov_b64 s[12:13], s[72:73]
	s_barrier
	s_add_u32 s6, s12, s2
	v_and_b32_e32 v12, 63, v6
	v_mov_b32_e32 v0, v208
	s_addc_u32 s7, s13, s3
	v_lshlrev_b32_e32 v1, 2, v12
	global_load_dword v2, v1, s[6:7]
	global_load_dword v3, v1, s[6:7] offset:256
	global_load_dword v4, v1, s[6:7] offset:512
	s_nop 0
	global_load_dword v1, v1, s[6:7] offset:768
	v_and_b32_e32 v5, 64, v209
	v_xor_b32_e32 v7, 32, v209
	v_add_u32_e32 v5, 64, v5
	v_cmp_lt_i32_e32 vcc, v7, v5
	v_xor_b32_e32 v8, 16, v209
	v_xor_b32_e32 v9, 8, v209
	v_cndmask_b32_e32 v7, v209, v7, vcc
	v_lshlrev_b32_e32 v204, 2, v7
	v_cmp_lt_i32_e32 vcc, v8, v5
	v_xor_b32_e32 v10, 4, v209
	v_xor_b32_e32 v11, 2, v209
	v_cndmask_b32_e32 v8, v209, v8, vcc
	v_lshlrev_b32_e32 v205, 2, v8
	v_cmp_lt_i32_e32 vcc, v9, v5
	v_xor_b32_e32 v13, 1, v209
	v_ashrrev_i32_e32 v0, 6, v0
	v_readlane_b32 s6, v252, 47
	s_mov_b64 s[10:11], s[70:71]
	s_mov_b64 s[14:15], s[74:75]
	v_readlane_b32 s70, v254, 28
	v_readlane_b32 s76, v252, 10
	v_readlane_b32 s77, v252, 11
	v_readlane_b32 s78, v252, 12
	v_readlane_b32 s79, v252, 13
	v_readlane_b32 s80, v252, 14
	v_readlane_b32 s81, v252, 15
	v_readlane_b32 s82, v252, 16
	v_readlane_b32 s83, v252, 17
	v_readlane_b32 s71, v254, 29
	s_waitcnt vmcnt(2)
	v_mul_f32_e32 v7, v2, v3
	ds_bpermute_b32 v7, v204, v7
	s_waitcnt vmcnt(0)
	v_mul_f32_e32 v14, v4, v1
	ds_bpermute_b32 v14, v204, v14
	s_waitcnt lgkmcnt(1)
	v_fmac_f32_e32 v7, v2, v3
	v_cndmask_b32_e32 v3, v209, v9, vcc
	s_waitcnt lgkmcnt(0)
	v_fmac_f32_e32 v14, v4, v1
	v_mov_b32_e32 v1, v7
	v_mov_b32_e32 v2, v14
	v_lshlrev_b32_e32 v206, 2, v3
	v_cmp_lt_i32_e32 vcc, v10, v5
	s_waitcnt lgkmcnt(1)
	s_nop 1
	v_permlane16_swap_b32_e32 v7, v1
	v_add_f32_e32 v1, v7, v1
	s_waitcnt lgkmcnt(0)
	s_nop 1
	v_permlane16_swap_b32_e32 v14, v2
	v_add_f32_e32 v2, v14, v2
	v_cndmask_b32_e32 v7, v209, v10, vcc
	v_lshlrev_b32_e32 v207, 2, v7
	v_cmp_lt_i32_e32 vcc, v11, v5
	s_waitcnt lgkmcnt(1)
	s_nop 1
	v_add_f32_dpp v1, v1, v1 row_ror:8 row_mask:0xf bank_mask:0xf
	s_waitcnt lgkmcnt(0)
	s_nop 1
	v_add_f32_dpp v2, v2, v2 row_ror:8 row_mask:0xf bank_mask:0xf
	v_cndmask_b32_e32 v7, v209, v11, vcc
	v_lshlrev_b32_e32 v220, 2, v7
	v_cmp_lt_i32_e32 vcc, v13, v5
	s_waitcnt lgkmcnt(1)
	s_nop 1
	v_add_f32_dpp v1, v1, v1 row_ror:4 row_mask:0xf bank_mask:0xf
	s_waitcnt lgkmcnt(0)
	s_nop 1
	v_add_f32_dpp v2, v2, v2 row_ror:4 row_mask:0xf bank_mask:0xf
	v_cndmask_b32_e32 v5, v209, v13, vcc
	v_lshlrev_b32_e32 v221, 2, v5
	s_waitcnt lgkmcnt(1)
	s_nop 1
	v_add_f32_dpp v5, v1, v1 quad_perm:[2,3,0,1] row_mask:0xf bank_mask:0xf
	s_waitcnt lgkmcnt(0)
	s_nop 1
	v_add_f32_dpp v7, v2, v2 quad_perm:[2,3,0,1] row_mask:0xf bank_mask:0xf
	v_add_u32_e32 v4, s6, v0
	s_movk_i32 s6, 0x4200
	v_cmp_gt_i32_e32 vcc, s6, v4
	s_and_saveexec_b64 s[6:7], vcc
	s_cbranch_execz .LBB0_499
	s_lshl_b32 s8, s70, 7
	v_readlane_b32 s68, v252, 2
	v_readlane_b32 s69, v252, 3
	v_lshl_or_b32 v192, v12, 1, s8
	v_readlane_b32 s70, v252, 4
	v_readlane_b32 s71, v252, 5
	v_readlane_b32 s72, v252, 6
	v_readlane_b32 s73, v252, 7
	v_readlane_b32 s74, v252, 8
	v_readlane_b32 s75, v252, 9
	s_mov_b64 s[8:9], s[68:69]
	s_mov_b64 s[10:11], s[70:71]
	s_mov_b64 s[14:15], s[74:75]
	v_lshl_add_u64 v[0:1], v[192:193], 2, s[14:15]
	s_add_u32 s2, s10, s2
	global_load_dwordx2 v[14:15], v[0:1], off
	s_addc_u32 s3, s11, s3
	v_lshlrev_b32_e32 v0, 4, v12
	global_load_dwordx4 v[0:3], v0, s[2:3]
	s_mov_b64 s[12:13], s[72:73]
	v_readlane_b32 s70, v254, 28
	s_waitcnt lgkmcnt(1)
	s_nop 1
	v_add_f32_dpp v16, v5, v5 quad_perm:[1,0,3,2] row_mask:0xf bank_mask:0xf
	s_waitcnt lgkmcnt(0)
	s_nop 1
	v_add_f32_dpp v17, v7, v7 quad_perm:[1,0,3,2] row_mask:0xf bank_mask:0xf
	v_lshlrev_b32_e32 v10, 3, v6
	v_mad_i64_i32 v[6:7], s[2:3], v4, s93, 0
	v_cvt_f32_u32_e32 v13, s70
	v_ashrrev_i32_e32 v5, 31, v4
	v_mul_f32_e32 v18, 0x3fb8aa3b, v16
	s_mov_b32 s2, 0x3fb8aa3b
	v_mul_f32_e32 v19, 0x3fb8aa3b, v17
	v_lshlrev_b64 v[8:9], 11, v[4:5]
	v_and_b32_e32 v5, 0x1f8, v10
	v_fma_f32 v20, v16, s2, -v18
	v_rndne_f32_e32 v21, v18
	v_fma_f32 v22, v17, s2, -v19
	v_rndne_f32_e32 v23, v19
	v_or_b32_e32 v10, v8, v5
	v_or_b32_e32 v6, v6, v5
	v_fmac_f32_e32 v20, 0x32a5705f, v16
	v_sub_f32_e32 v5, v18, v21
	v_fmac_f32_e32 v22, 0x32a5705f, v17
	v_sub_f32_e32 v18, v19, v23
	v_add_f32_e32 v5, v5, v20
	v_lshl_or_b32 v8, v12, 2, v8
	v_cvt_i32_f32_e32 v12, v21
	v_mul_f32_e32 v13, 0xbe99999a, v13
	v_add_f32_e32 v18, v18, v22
	v_exp_f32_e32 v5, v5
	v_cvt_i32_f32_e32 v19, v23
	v_mul_f32_e32 v20, 0x3fb8aa3b, v13
	v_exp_f32_e32 v18, v18
	v_fma_f32 v21, v13, s2, -v20
	v_rndne_f32_e32 v22, v20
	v_fmac_f32_e32 v21, 0x32a5705f, v13
	v_sub_f32_e32 v20, v20, v22
	s_mov_b32 s2, 0xc2ce8ed0
	v_add_f32_e32 v20, v20, v21
	v_ldexp_f32 v5, v5, v12
	v_cmp_ngt_f32_e32 vcc, s2, v16
	v_cvt_i32_f32_e32 v22, v22
	v_exp_f32_e32 v20, v20
	v_ldexp_f32 v12, v18, v19
	v_cndmask_b32_e32 v5, 0, v5, vcc
	v_cmp_ngt_f32_e32 vcc, s2, v17
	s_mov_b32 s3, 0x42b17218
	v_mov_b32_e32 v11, v9
	v_cndmask_b32_e32 v12, 0, v12, vcc
	v_cmp_nlt_f32_e32 vcc, s3, v16
	s_mov_b64 s[8:9], 0
	v_readlane_b32 s76, v252, 10
	v_cndmask_b32_e32 v5, v212, v5, vcc
	v_cmp_nlt_f32_e32 vcc, s3, v17
	v_readlane_b32 s77, v252, 11
	v_readlane_b32 s78, v252, 12
	v_cndmask_b32_e32 v12, v212, v12, vcc
	v_sub_f32_e32 v5, v5, v12
	v_ldexp_f32 v12, v20, v22
	v_cmp_ngt_f32_e32 vcc, s2, v13
	v_readlane_b32 s79, v252, 13
	v_readlane_b32 s80, v252, 14
	v_cndmask_b32_e32 v12, 0, v12, vcc
	v_cmp_nlt_f32_e32 vcc, s3, v13
	v_mov_b32_e32 v13, 0x3f4ccccd
	v_readlane_b32 s81, v252, 15
	v_cndmask_b32_e32 v12, v212, v12, vcc
	v_fmamk_f32 v12, v12, 0xbf19999a, v13
	v_sub_f32_e32 v16, 1.0, v12
	v_add_f32_e32 v12, v12, v5
	v_mov_b32_e32 v13, v12
	v_readlane_b32 s82, v252, 16
	v_readlane_b32 s83, v252, 17
	v_readlane_b32 s71, v254, 29
	s_waitcnt vmcnt(1)
	v_pk_mul_f32 v[14:15], v[16:17], v[14:15] op_sel_hi:[0,1]
	s_branch .LBB0_495

; DEVI float bflo(unsigned w) { return __uint_as_float(w << 16); }
; DEVI float bfhi(unsigned w) { return __uint_as_float(w & 0xffff0000u); }
; DEVI void phase_prep(const Params& p, int l) {
;     ...
;   for (int r = gw; r < RP; r += nw) {
;     if (l == 1 && rr_of(r) >= SEQ) continue;
;     u32x2 ga[4], gb[4], gr[4]; unsigned da[8], db[8];
; #pragma unroll
;     for (int u = 0; u < 4; ++u) {
;       const long off = (long)r * 1024 + u * 256 + lane * 4;
;       ga[u] = *(const u32x2*)(og0 + off); gb[u] = *(const u32x2*)(og1 + off);
;       gr[u] = *(const u32x2*)(feat + (long)r * NF + F_GR + u * 256 + lane * 4);
;     }
; #pragma unroll
;     for (int h = 0; h < 8; ++h) {
;       const long off = (long)r * 1024 + h * 128 + lane * 2;
;       da[h] = *(const unsigned*)(od0 + off); db[h] = *(const unsigned*)(od1 + off);
;     }
;     float o[4][4], ss[4], e0[8], e1[8], sd[8];
; #pragma unroll
;     for (int u = 0; u < 4; ++u) {
;       o[u][0] = bflo(ga[u][0]) + bflo(gb[u][0]); o[u][1] = bfhi(ga[u][0]) + bfhi(gb[u][0]);
;       o[u][2] = bflo(ga[u][1]) + bflo(gb[u][1]); o[u][3] = bfhi(ga[u][1]) + bfhi(gb[u][1]);
;       ss[u] = o[u][0] * o[u][0] + o[u][1] * o[u][1] + o[u][2] * o[u][2] + o[u][3] * o[u][3];
;     }
; #pragma unroll
;     for (int h = 0; h < 8; ++h) {
;       e0[h] = bflo(da[h]) - lam * bflo(db[h]); e1[h] = bfhi(da[h]) - lam * bfhi(db[h]);
;       sd[h] = e0[h] * e0[h] + e1[h] * e1[h];
;     }
.LBB0_497:
	s_and_saveexec_b64 s[10:11], s[2:3]
	s_cbranch_execz .LBB0_494
	v_lshl_add_u64 v[18:19], s[90:91], 0, v[10:11]
	v_add_co_u32_e32 v42, vcc, 0x22bec000, v18
	v_lshl_add_u64 v[16:17], s[90:91], 0, v[6:7]
	s_nop 0
	v_addc_co_u32_e32 v43, vcc, 0, v19, vcc
	v_add_co_u32_e32 v18, vcc, 0x24cec000, v18
	global_load_dwordx2 v[72:73], v[42:43], off offset:2048
	s_nop 0
	v_addc_co_u32_e32 v19, vcc, 0, v19, vcc
	v_add_co_u32_e32 v16, vcc, 0x7eed000, v16
	global_load_dwordx2 v[78:79], v[18:19], off offset:2048
	s_nop 0
	v_addc_co_u32_e32 v17, vcc, 0, v17, vcc
	global_load_dwordx2 v[74:75], v[16:17], off offset:2048
	global_load_dwordx2 v[68:69], v[42:43], off offset:2560
	global_load_dwordx2 v[66:67], v[18:19], off offset:2560
	global_load_dwordx2 v[52:53], v[16:17], off offset:2560
	global_load_dwordx2 v[64:65], v[42:43], off offset:3072
	global_load_dwordx2 v[62:63], v[18:19], off offset:3072
	global_load_dwordx2 v[60:61], v[16:17], off offset:3072
	global_load_dwordx2 v[58:59], v[42:43], off offset:3584
	global_load_dwordx2 v[56:57], v[18:19], off offset:3584
	global_load_dwordx2 v[54:55], v[16:17], off offset:3584
	v_lshl_add_u64 v[18:19], s[90:91], 0, v[8:9]
	s_mov_b32 s2, 0x26dec000
	v_add_co_u32_e32 v16, vcc, s2, v18
	s_mov_b32 s2, 0x28eec000
	s_nop 0
	v_addc_co_u32_e32 v17, vcc, 0, v19, vcc
	v_add_co_u32_e32 v18, vcc, s2, v18
	global_load_dword v5, v[16:17], off offset:2048
	s_nop 0
	v_addc_co_u32_e32 v19, vcc, 0, v19, vcc
	global_load_dword v20, v[18:19], off offset:2048
	global_load_dword v21, v[16:17], off offset:2304
	global_load_dword v22, v[18:19], off offset:2304
	global_load_dword v23, v[16:17], off offset:2560
	global_load_dword v24, v[18:19], off offset:2560
	global_load_dword v25, v[16:17], off offset:2816
	global_load_dword v26, v[18:19], off offset:2816
	global_load_dword v27, v[16:17], off offset:3072
	global_load_dword v29, v[18:19], off offset:3072
	global_load_dword v31, v[16:17], off offset:3328
	global_load_dword v33, v[18:19], off offset:3328
	global_load_dword v70, v[16:17], off offset:3584
	global_load_dword v71, v[18:19], off offset:3584
	global_load_dword v76, v[16:17], off offset:3840
	global_load_dword v77, v[18:19], off offset:3840
	s_waitcnt vmcnt(25)
	v_and_b32_e32 v82, 0xffff0000, v75
	v_lshlrev_b32_e32 v80, 16, v72
	v_and_b32_e32 v81, 0xffff0000, v72
	s_waitcnt vmcnt(24)
	v_lshlrev_b32_e32 v88, 16, v68
	v_and_b32_e32 v89, 0xffff0000, v68
	s_waitcnt vmcnt(23)
	v_lshlrev_b32_e32 v68, 16, v66
	v_lshlrev_b32_e32 v72, 16, v78
	s_waitcnt vmcnt(14)
	v_lshlrev_b32_e32 v46, 16, v20
	v_and_b32_e32 v47, 0xffff0000, v20
	s_waitcnt vmcnt(13)
	v_lshlrev_b32_e32 v48, 16, v21
	v_and_b32_e32 v49, 0xffff0000, v21
	s_waitcnt vmcnt(12)
	v_lshlrev_b32_e32 v50, 16, v22
	v_and_b32_e32 v51, 0xffff0000, v22
	s_waitcnt vmcnt(11)
	v_lshlrev_b32_e32 v34, 16, v23
	s_waitcnt vmcnt(10)
	v_lshlrev_b32_e32 v36, 16, v24
	v_and_b32_e32 v35, 0xffff0000, v23
	v_and_b32_e32 v37, 0xffff0000, v24
	s_waitcnt vmcnt(9)
	v_lshlrev_b32_e32 v38, 16, v25
	s_waitcnt vmcnt(3)
	v_lshlrev_b32_e32 v18, 16, v70
	s_waitcnt vmcnt(2)
	v_lshlrev_b32_e32 v20, 16, v71
	v_and_b32_e32 v19, 0xffff0000, v70
	v_and_b32_e32 v21, 0xffff0000, v71
	v_lshlrev_b32_e32 v70, 16, v73
	v_and_b32_e32 v71, 0xffff0000, v73
	v_and_b32_e32 v73, 0xffff0000, v78
	v_pk_add_f32 v[72:73], v[80:81], v[72:73]
	v_lshlrev_b32_e32 v80, 16, v74
	v_and_b32_e32 v81, 0xffff0000, v74
	v_mul_f32_e32 v74, 0xbfb8aa3b, v80
	v_lshlrev_b32_e32 v44, 16, v5
	v_and_b32_e32 v45, 0xffff0000, v5
	v_lshlrev_b32_e32 v5, 16, v75
	v_fma_f32 v75, v80, s54, -v74
	v_rndne_f32_e32 v83, v74
	v_fmac_f32_e32 v75, 0xb2a5705f, v80
	v_sub_f32_e32 v74, v74, v83
	v_add_f32_e32 v74, v74, v75
	v_exp_f32_e32 v74, v74
	v_cvt_i32_f32_e32 v75, v83
	v_cmp_nlt_f32_e32 vcc, s55, v80
	v_and_b32_e32 v39, 0xffff0000, v25
	s_waitcnt vmcnt(1)
	v_lshlrev_b32_e32 v22, 16, v76
	v_ldexp_f32 v74, v74, v75
	v_mul_f32_e32 v75, 0xbfb8aa3b, v81
	v_fma_f32 v83, v81, s54, -v75
	v_rndne_f32_e32 v84, v75
	v_fmac_f32_e32 v83, 0xb2a5705f, v81
	v_sub_f32_e32 v75, v75, v84
	v_add_f32_e32 v75, v75, v83
	v_exp_f32_e32 v75, v75
	v_cvt_i32_f32_e32 v83, v84
	v_cndmask_b32_e32 v74, 0, v74, vcc
	v_cmp_ngt_f32_e32 vcc, s56, v80
	s_waitcnt vmcnt(0)
	v_lshlrev_b32_e32 v24, 16, v77
	v_ldexp_f32 v75, v75, v83
	v_cndmask_b32_e32 v74, v212, v74, vcc
	v_cmp_nlt_f32_e32 vcc, s55, v81
	v_and_b32_e32 v23, 0xffff0000, v76
	v_and_b32_e32 v25, 0xffff0000, v77
	v_cndmask_b32_e32 v75, 0, v75, vcc
	v_cmp_ngt_f32_e32 vcc, s56, v81
	v_lshlrev_b32_e32 v76, 16, v79
	v_and_b32_e32 v77, 0xffff0000, v79
	v_cndmask_b32_e32 v75, v212, v75, vcc
	v_pk_add_f32 v[74:75], v[74:75], 1.0 op_sel_hi:[1,0]
	v_pk_add_f32 v[70:71], v[70:71], v[76:77]
	v_div_scale_f32 v83, s[2:3], v75, v75, v81
	v_rcp_f32_e32 v84, v83
	v_pk_mul_f32 v[78:79], v[72:73], v[72:73]
	v_pk_mul_f32 v[76:77], v[70:71], v[70:71]
	v_lshlrev_b32_e32 v40, 16, v26
	v_fma_f32 v85, -v83, v84, 1.0
	v_fmac_f32_e32 v84, v85, v84
	v_div_scale_f32 v85, vcc, v81, v75, v81
	v_mul_f32_e32 v86, v85, v84
	v_fma_f32 v87, -v83, v86, v85
	v_fmac_f32_e32 v86, v87, v84
	v_fma_f32 v83, -v83, v86, v85
	v_div_fmas_f32 v83, v83, v84, v86
	v_div_fixup_f32 v75, v83, v75, v81
	v_div_scale_f32 v81, s[2:3], v74, v74, v80
	v_rcp_f32_e32 v83, v81
	v_and_b32_e32 v41, 0xffff0000, v26
	v_pk_fma_f32 v[34:35], v[12:13], v[36:37], v[34:35] neg_lo:[1,0,0] neg_hi:[1,0,0]
	v_pk_fma_f32 v[38:39], v[12:13], v[40:41], v[38:39] neg_lo:[1,0,0] neg_hi:[1,0,0]
	v_fma_f32 v84, -v81, v83, 1.0
	v_fmac_f32_e32 v83, v84, v83
	v_div_scale_f32 v84, vcc, v80, v74, v80
	v_mul_f32_e32 v85, v84, v83
	v_fma_f32 v86, -v81, v85, v84
	v_fmac_f32_e32 v85, v86, v83
	v_fma_f32 v81, -v81, v85, v84
; DEVI float bflo(unsigned w) { return __uint_as_float(w << 16); }
; DEVI float bfhi(unsigned w) { return __uint_as_float(w & 0xffff0000u); }
; DEVI void phase_prep(const Params& p, int l) {
;     ...
;     float o[4][4], ss[4], e0[8], e1[8], sd[8];
; #pragma unroll
;     for (int u = 0; u < 4; ++u) {
;       o[u][0] = bflo(ga[u][0]) + bflo(gb[u][0]); o[u][1] = bfhi(ga[u][0]) + bfhi(gb[u][0]);
;       o[u][2] = bflo(ga[u][1]) + bflo(gb[u][1]); o[u][3] = bfhi(ga[u][1]) + bfhi(gb[u][1]);
;       ss[u] = o[u][0] * o[u][0] + o[u][1] * o[u][1] + o[u][2] * o[u][2] + o[u][3] * o[u][3];
;     }
; #pragma unroll
;     for (int h = 0; h < 8; ++h) {
;       e0[h] = bflo(da[h]) - lam * bflo(db[h]); e1[h] = bfhi(da[h]) - lam * bfhi(db[h]);
;       sd[h] = e0[h] * e0[h] + e1[h] * e1[h];
;     }
; #pragma unroll
;     for (int m = 32; m >= 1; m >>= 1) {
; #pragma unroll
;       for (int u = 0; u < 4; ++u) ss[u] += __shfl_xor(ss[u], m);
; #pragma unroll
;       for (int h = 0; h < 8; ++h) sd[h] += __shfl_xor(sd[h], m);
;     }
	v_div_fmas_f32 v81, v81, v83, v85
	v_div_fixup_f32 v74, v81, v74, v80
	v_mul_f32_e32 v80, 0xbfb8aa3b, v5
	v_fma_f32 v81, v5, s54, -v80
	v_rndne_f32_e32 v83, v80
	v_fmac_f32_e32 v81, 0xb2a5705f, v5
	v_sub_f32_e32 v80, v80, v83
	v_add_f32_e32 v80, v80, v81
	v_exp_f32_e32 v80, v80
	v_cvt_i32_f32_e32 v81, v83
	v_cmp_nlt_f32_e32 vcc, s55, v5
	v_pk_mul_f32 v[36:37], v[34:35], v[34:35]
	v_pk_mul_f32 v[40:41], v[38:39], v[38:39]
	v_ldexp_f32 v80, v80, v81
	v_mul_f32_e32 v81, 0xbfb8aa3b, v82
	v_fma_f32 v83, v82, s54, -v81
	v_rndne_f32_e32 v84, v81
	v_fmac_f32_e32 v83, 0xb2a5705f, v82
	v_sub_f32_e32 v81, v81, v84
	v_add_f32_e32 v81, v81, v83
	v_exp_f32_e32 v81, v81
	v_cvt_i32_f32_e32 v83, v84
	v_cndmask_b32_e32 v80, 0, v80, vcc
	v_cmp_ngt_f32_e32 vcc, s56, v5
	v_lshlrev_b32_e32 v26, 16, v27
	v_ldexp_f32 v81, v81, v83
	v_cndmask_b32_e32 v80, v212, v80, vcc
	v_cmp_nlt_f32_e32 vcc, s55, v82
	v_lshlrev_b32_e32 v28, 16, v29
	v_and_b32_e32 v27, 0xffff0000, v27
	v_cndmask_b32_e32 v81, 0, v81, vcc
	v_cmp_ngt_f32_e32 vcc, s56, v82
	v_and_b32_e32 v29, 0xffff0000, v29
	v_lshlrev_b32_e32 v30, 16, v31
	v_cndmask_b32_e32 v81, v212, v81, vcc
	v_pk_add_f32 v[80:81], v[80:81], 1.0 op_sel_hi:[1,0]
	v_lshlrev_b32_e32 v32, 16, v33
	v_div_scale_f32 v83, s[2:3], v81, v81, v82
	v_rcp_f32_e32 v84, v83
	v_and_b32_e32 v31, 0xffff0000, v31
	v_and_b32_e32 v33, 0xffff0000, v33
	v_pk_fma_f32 v[26:27], v[12:13], v[28:29], v[26:27] neg_lo:[1,0,0] neg_hi:[1,0,0]
	v_fma_f32 v85, -v83, v84, 1.0
	v_fmac_f32_e32 v84, v85, v84
	v_div_scale_f32 v85, vcc, v82, v81, v82
	v_mul_f32_e32 v86, v85, v84
	v_fma_f32 v87, -v83, v86, v85
	v_fmac_f32_e32 v86, v87, v84
	v_fma_f32 v83, -v83, v86, v85
	v_div_fmas_f32 v83, v83, v84, v86
	v_div_fixup_f32 v83, v83, v81, v82
	v_div_scale_f32 v81, s[2:3], v80, v80, v5
	v_rcp_f32_e32 v82, v81
	v_pk_fma_f32 v[30:31], v[12:13], v[32:33], v[30:31] neg_lo:[1,0,0] neg_hi:[1,0,0]
	v_pk_mul_f32 v[28:29], v[26:27], v[26:27]
	v_pk_mul_f32 v[32:33], v[30:31], v[30:31]
	v_fma_f32 v84, -v81, v82, 1.0
	v_fmac_f32_e32 v82, v84, v82
	v_div_scale_f32 v84, vcc, v5, v80, v5
	v_mul_f32_e32 v85, v84, v82
	v_fma_f32 v86, -v81, v85, v84
	v_fmac_f32_e32 v85, v86, v82
	v_fma_f32 v81, -v81, v85, v84
	v_div_fmas_f32 v81, v81, v82, v85
	v_div_fixup_f32 v82, v81, v80, v5
	v_lshlrev_b32_e32 v80, 16, v69
	v_and_b32_e32 v81, 0xffff0000, v69
	v_and_b32_e32 v69, 0xffff0000, v66
	v_lshlrev_b32_e32 v84, 16, v67
	v_and_b32_e32 v85, 0xffff0000, v67
	v_pk_add_f32 v[66:67], v[88:89], v[68:69]
	v_lshlrev_b32_e32 v68, 16, v52
	v_and_b32_e32 v69, 0xffff0000, v52
	v_mul_f32_e32 v52, 0xbfb8aa3b, v68
	v_pk_add_f32 v[80:81], v[80:81], v[84:85]
	v_lshlrev_b32_e32 v5, 16, v53
	v_and_b32_e32 v84, 0xffff0000, v53
	v_fma_f32 v53, v68, s54, -v52
	v_rndne_f32_e32 v85, v52
	v_fmac_f32_e32 v53, 0xb2a5705f, v68
	v_sub_f32_e32 v52, v52, v85
	v_add_f32_e32 v52, v52, v53
	v_exp_f32_e32 v52, v52
	v_cvt_i32_f32_e32 v53, v85
	v_cmp_nlt_f32_e32 vcc, s55, v68
	v_pk_mul_f32 v[88:89], v[66:67], v[66:67]
	v_pk_mul_f32 v[86:87], v[80:81], v[80:81]
	v_ldexp_f32 v52, v52, v53
	v_mul_f32_e32 v53, 0xbfb8aa3b, v69
	v_fma_f32 v85, v69, s54, -v53
	v_rndne_f32_e32 v90, v53
	v_fmac_f32_e32 v85, 0xb2a5705f, v69
	v_sub_f32_e32 v53, v53, v90
	v_add_f32_e32 v53, v53, v85
	v_exp_f32_e32 v53, v53
	v_cvt_i32_f32_e32 v85, v90
	v_cndmask_b32_e32 v52, 0, v52, vcc
	v_cmp_ngt_f32_e32 vcc, s56, v68
	v_pk_fma_f32 v[18:19], v[12:13], v[20:21], v[18:19] neg_lo:[1,0,0] neg_hi:[1,0,0]
	v_ldexp_f32 v53, v53, v85
	v_cndmask_b32_e32 v52, v212, v52, vcc
	v_cmp_nlt_f32_e32 vcc, s55, v69
	v_pk_fma_f32 v[22:23], v[12:13], v[24:25], v[22:23] neg_lo:[1,0,0] neg_hi:[1,0,0]
	v_pk_mul_f32 v[20:21], v[18:19], v[18:19]
	v_cndmask_b32_e32 v53, 0, v53, vcc
	v_cmp_ngt_f32_e32 vcc, s56, v69
	v_pk_mul_f32 v[24:25], v[22:23], v[22:23]
	s_nop 0
	v_cndmask_b32_e32 v53, v212, v53, vcc
	v_pk_add_f32 v[52:53], v[52:53], 1.0 op_sel_hi:[1,0]
	s_nop 0
	v_div_scale_f32 v85, s[2:3], v53, v53, v69
	v_rcp_f32_e32 v90, v85
	s_nop 0
	v_fma_f32 v91, -v85, v90, 1.0
	v_fmac_f32_e32 v90, v91, v90
	v_div_scale_f32 v91, vcc, v69, v53, v69
	v_mul_f32_e32 v92, v91, v90
	v_fma_f32 v93, -v85, v92, v91
	v_fmac_f32_e32 v92, v93, v90
	v_fma_f32 v85, -v85, v92, v91
	v_div_fmas_f32 v85, v85, v90, v92
	v_div_fixup_f32 v69, v85, v53, v69
	v_div_scale_f32 v53, s[2:3], v52, v52, v68
	v_rcp_f32_e32 v85, v53
	s_mov_b32 s2, 0x358637bd
	v_fma_f32 v90, -v53, v85, 1.0
	v_fmac_f32_e32 v85, v90, v85
	v_div_scale_f32 v90, vcc, v68, v52, v68
	v_mul_f32_e32 v91, v90, v85
	v_fma_f32 v92, -v53, v91, v90
	v_fmac_f32_e32 v91, v92, v85
	v_fma_f32 v53, -v53, v91, v90
	v_div_fmas_f32 v53, v53, v85, v91
	v_div_fixup_f32 v68, v53, v52, v68
	v_mov_b32_e32 v52, v88
	v_mov_b32_e32 v53, v78
	v_mov_b32_e32 v78, v89
	v_pk_add_f32 v[52:53], v[52:53], v[78:79]
	v_mov_b32_e32 v78, v86
	v_mov_b32_e32 v79, v76
	v_pk_add_f32 v[52:53], v[78:79], v[52:53]
	v_mov_b32_e32 v76, v87
	v_pk_add_f32 v[52:53], v[76:77], v[52:53]
	v_mov_b32_e32 v77, v53
	v_mov_b32_e32 v76, v52
	s_waitcnt lgkmcnt(0)
	s_nop 1
	v_permlane32_swap_b32_e32 v52, v76
	v_permlane32_swap_b32_e32 v53, v77
	v_pk_add_f32 v[52:53], v[52:53], v[76:77]
	v_mov_b32_e32 v77, v53
	v_mov_b32_e32 v76, v52
	s_waitcnt lgkmcnt(0)
	s_nop 1
	v_permlane16_swap_b32_e32 v52, v76
	v_permlane16_swap_b32_e32 v53, v77
	v_pk_add_f32 v[52:53], v[52:53], v[76:77]
	s_waitcnt lgkmcnt(0)
	s_nop 1
	v_add_f32_dpp v52, v52, v52 row_ror:8 row_mask:0xf bank_mask:0xf
	v_add_f32_dpp v53, v53, v53 row_ror:8 row_mask:0xf bank_mask:0xf
	s_waitcnt lgkmcnt(0)
	s_nop 1
	v_add_f32_dpp v52, v52, v52 row_ror:4 row_mask:0xf bank_mask:0xf
	v_add_f32_dpp v53, v53, v53 row_ror:4 row_mask:0xf bank_mask:0xf
	s_waitcnt lgkmcnt(0)
; DEVI float bflo(unsigned w) { return __uint_as_float(w << 16); }
; DEVI float bfhi(unsigned w) { return __uint_as_float(w & 0xffff0000u); }
; DEVI void st4bf(u16* p, float a, float b, float c, float d) { u32x2 w = {cvtpk(a, b), cvtpk(c, d)}; *(u32x2*)p = w; }
; DEVI float siluf(float x) { return x / (1.f + expf(-x)); }
; DEVI void phase_prep(const Params& p, int l) {
;     ...
; #pragma unroll
;     for (int m = 32; m >= 1; m >>= 1) {
; #pragma unroll
;       for (int u = 0; u < 4; ++u) ss[u] += __shfl_xor(ss[u], m);
; #pragma unroll
;       for (int h = 0; h < 8; ++h) sd[h] += __shfl_xor(sd[h], m);
;     }
; #pragma unroll
;     for (int u = 0; u < 4; ++u) {
;       const float rsd = rsqrtf(ss[u] * (1.f / 256.f) + EPS);
;       const float rv[4] = {bflo(gr[u][0]), bfhi(gr[u][0]), bflo(gr[u][1]), bfhi(gr[u][1])};
;       float y[4];
; #pragma unroll
;       for (int j = 0; j < 4; ++j) y[j] = o[u][j] * rsd * gg[j] * siluf(rv[j]);
;       st4bf(ya + (long)r * 1024 + u * 256 + lane * 4, y[0], y[1], y[2], y[3]);
	s_nop 1
	v_add_f32_dpp v52, v52, v52 quad_perm:[2,3,0,1] row_mask:0xf bank_mask:0xf
	v_add_f32_dpp v53, v53, v53 quad_perm:[2,3,0,1] row_mask:0xf bank_mask:0xf
	s_waitcnt lgkmcnt(0)
	s_nop 1
	v_add_f32_dpp v76, v52, v52 quad_perm:[1,0,3,2] row_mask:0xf bank_mask:0xf
	v_add_f32_dpp v77, v53, v53 quad_perm:[1,0,3,2] row_mask:0xf bank_mask:0xf
	v_mov_b64_e32 v[52:53], s[2:3]
	v_pk_fma_f32 v[76:77], v[76:77], s[26:27], v[52:53] op_sel_hi:[1,0,0]
	s_nop 0
	v_mul_f32_e32 v78, 0x4b800000, v77
	v_cmp_gt_f32_e64 s[2:3], s59, v77
	v_cmp_gt_f32_e32 vcc, s59, v76
	s_nop 0
	v_cndmask_b32_e64 v77, v77, v78, s[2:3]
	v_rsq_f32_e32 v77, v77
	s_nop 0
	v_mul_f32_e32 v78, 0x45800000, v77
	v_cndmask_b32_e64 v78, v77, v78, s[2:3]
	v_pk_mul_f32 v[72:73], v[72:73], v[78:79] op_sel_hi:[1,0]
	v_pk_mul_f32 v[70:71], v[70:71], v[78:79] op_sel_hi:[1,0]
	v_pk_mul_f32 v[72:73], v[0:1], v[72:73]
	v_pk_mul_f32 v[70:71], v[2:3], v[70:71]
	v_pk_mul_f32 v[72:73], v[74:75], v[72:73]
	v_pk_mul_f32 v[70:71], v[82:83], v[70:71]
	v_cvt_pk_bf16_f32 v72, v72, v73
	v_cvt_pk_bf16_f32 v73, v70, v71
	v_mul_f32_e32 v70, 0x4b800000, v76
	v_cndmask_b32_e32 v70, v76, v70, vcc
	v_rsq_f32_e32 v70, v70
	global_store_dwordx2 v[42:43], v[72:73], off offset:2048
	v_lshlrev_b32_e32 v78, 16, v56
	v_and_b32_e32 v79, 0xffff0000, v56
	v_mul_f32_e32 v71, 0x45800000, v70
	v_cndmask_b32_e32 v70, v70, v71, vcc
	v_pk_mul_f32 v[66:67], v[66:67], v[70:71] op_sel_hi:[1,0]
	v_cmp_nlt_f32_e32 vcc, s55, v5
	v_pk_mul_f32 v[66:67], v[0:1], v[66:67]
	s_nop 0
	v_pk_mul_f32 v[66:67], v[68:69], v[66:67]
	v_mul_f32_e32 v68, 0xbfb8aa3b, v5
	v_fma_f32 v69, v5, s54, -v68
	v_rndne_f32_e32 v71, v68
	v_fmac_f32_e32 v69, 0xb2a5705f, v5
	v_sub_f32_e32 v68, v68, v71
	v_add_f32_e32 v68, v68, v69
	v_exp_f32_e32 v68, v68
	v_cvt_i32_f32_e32 v69, v71
	v_pk_mul_f32 v[70:71], v[80:81], v[70:71] op_sel_hi:[1,0]
	v_cvt_pk_bf16_f32 v66, v66, v67
	v_pk_mul_f32 v[70:71], v[2:3], v[70:71]
	v_ldexp_f32 v68, v68, v69
	v_mul_f32_e32 v69, 0xbfb8aa3b, v84
	v_fma_f32 v72, v84, s54, -v69
	v_rndne_f32_e32 v73, v69
	v_fmac_f32_e32 v72, 0xb2a5705f, v84
	v_sub_f32_e32 v69, v69, v73
	v_add_f32_e32 v69, v69, v72
	v_exp_f32_e32 v69, v69
	v_cvt_i32_f32_e32 v72, v73
	v_cndmask_b32_e32 v68, 0, v68, vcc
	v_cmp_ngt_f32_e32 vcc, s56, v5
	v_ldexp_f32 v69, v69, v72
	s_nop 0
	v_cndmask_b32_e32 v68, v212, v68, vcc
	v_cmp_nlt_f32_e32 vcc, s55, v84
	s_nop 1
	v_cndmask_b32_e32 v69, 0, v69, vcc
	v_cmp_ngt_f32_e32 vcc, s56, v84
	s_nop 1
	v_cndmask_b32_e32 v69, v212, v69, vcc
	v_pk_add_f32 v[68:69], v[68:69], 1.0 op_sel_hi:[1,0]
	s_nop 0
	v_div_scale_f32 v72, s[2:3], v69, v69, v84
	v_rcp_f32_e32 v73, v72
	s_nop 0
	v_fma_f32 v74, -v72, v73, 1.0
	v_fmac_f32_e32 v73, v74, v73
	v_div_scale_f32 v74, vcc, v84, v69, v84
	v_mul_f32_e32 v75, v74, v73
	v_fma_f32 v76, -v72, v75, v74
	v_fmac_f32_e32 v75, v76, v73
	v_fma_f32 v72, -v72, v75, v74
	v_div_fmas_f32 v72, v72, v73, v75
	v_div_fixup_f32 v69, v72, v69, v84
	v_div_scale_f32 v72, s[2:3], v68, v68, v5
	v_rcp_f32_e32 v73, v72
	s_nop 0
	v_fma_f32 v74, -v72, v73, 1.0
	v_fmac_f32_e32 v73, v74, v73
	v_div_scale_f32 v74, vcc, v5, v68, v5
	v_mul_f32_e32 v75, v74, v73
	v_fma_f32 v76, -v72, v75, v74
	v_fmac_f32_e32 v75, v76, v73
	v_fma_f32 v72, -v72, v75, v74
	v_div_fmas_f32 v72, v72, v73, v75
	v_div_fixup_f32 v68, v72, v68, v5
	v_pk_mul_f32 v[68:69], v[68:69], v[70:71]
	v_lshlrev_b32_e32 v70, 16, v64
	v_cvt_pk_bf16_f32 v67, v68, v69
	global_store_dwordx2 v[42:43], v[66:67], off offset:2560
	v_lshlrev_b32_e32 v66, 16, v65
	v_and_b32_e32 v67, 0xffff0000, v65
	v_and_b32_e32 v71, 0xffff0000, v64
	v_lshlrev_b32_e32 v64, 16, v62
	v_and_b32_e32 v65, 0xffff0000, v62
	v_lshlrev_b32_e32 v68, 16, v63
	v_and_b32_e32 v69, 0xffff0000, v63
	v_pk_add_f32 v[62:63], v[70:71], v[64:65]
	v_lshlrev_b32_e32 v70, 16, v60
	v_and_b32_e32 v71, 0xffff0000, v60
	v_mul_f32_e32 v60, 0xbfb8aa3b, v70
	v_lshlrev_b32_e32 v5, 16, v61
	v_and_b32_e32 v72, 0xffff0000, v61
	v_fma_f32 v61, v70, s54, -v60
	v_rndne_f32_e32 v73, v60
	v_fmac_f32_e32 v61, 0xb2a5705f, v70
	v_sub_f32_e32 v60, v60, v73
	v_add_f32_e32 v60, v60, v61
	v_exp_f32_e32 v60, v60
	v_cvt_i32_f32_e32 v61, v73
	v_cmp_nlt_f32_e32 vcc, s55, v70
	v_pk_add_f32 v[66:67], v[66:67], v[68:69]
	v_pk_mul_f32 v[64:65], v[62:63], v[62:63]
	v_ldexp_f32 v60, v60, v61
	v_mul_f32_e32 v61, 0xbfb8aa3b, v71
	v_fma_f32 v73, v71, s54, -v61
	v_rndne_f32_e32 v74, v61
	v_fmac_f32_e32 v73, 0xb2a5705f, v71
	v_sub_f32_e32 v61, v61, v74
	v_add_f32_e32 v61, v61, v73
	v_exp_f32_e32 v61, v61
	v_cvt_i32_f32_e32 v73, v74
	v_cndmask_b32_e32 v60, 0, v60, vcc
	v_cmp_ngt_f32_e32 vcc, s56, v70
	v_pk_mul_f32 v[68:69], v[66:67], v[66:67]
	v_ldexp_f32 v61, v61, v73
	v_cndmask_b32_e32 v60, v212, v60, vcc
	v_cmp_nlt_f32_e32 vcc, s55, v71
	s_nop 1
	v_cndmask_b32_e32 v61, 0, v61, vcc
	v_cmp_ngt_f32_e32 vcc, s56, v71
	s_nop 1
	v_cndmask_b32_e32 v61, v212, v61, vcc
	v_pk_add_f32 v[60:61], v[60:61], 1.0 op_sel_hi:[1,0]
	s_nop 0
	v_div_scale_f32 v73, s[2:3], v61, v61, v71
	v_rcp_f32_e32 v74, v73
	s_nop 0
	v_fma_f32 v75, -v73, v74, 1.0
	v_fmac_f32_e32 v74, v75, v74
	v_div_scale_f32 v75, vcc, v71, v61, v71
	v_mul_f32_e32 v76, v75, v74
	v_fma_f32 v77, -v73, v76, v75
	v_fmac_f32_e32 v76, v77, v74
	v_fma_f32 v73, -v73, v76, v75
	v_div_fmas_f32 v73, v73, v74, v76
	v_div_fixup_f32 v61, v73, v61, v71
	v_div_scale_f32 v71, s[2:3], v60, v60, v70
	v_rcp_f32_e32 v73, v71
	s_nop 0
	v_fma_f32 v74, -v71, v73, 1.0
	v_fmac_f32_e32 v73, v74, v73
	v_div_scale_f32 v74, vcc, v70, v60, v70
	v_mul_f32_e32 v75, v74, v73
	v_fma_f32 v76, -v71, v75, v74
	v_fmac_f32_e32 v75, v76, v73
	v_fma_f32 v71, -v71, v75, v74
	v_div_fmas_f32 v71, v71, v73, v75
	v_div_fixup_f32 v60, v71, v60, v70
; DEVI float bflo(unsigned w) { return __uint_as_float(w << 16); }
; DEVI float bfhi(unsigned w) { return __uint_as_float(w & 0xffff0000u); }
; DEVI void st4bf(u16* p, float a, float b, float c, float d) { u32x2 w = {cvtpk(a, b), cvtpk(c, d)}; *(u32x2*)p = w; }
; DEVI float siluf(float x) { return x / (1.f + expf(-x)); }
; DEVI void phase_prep(const Params& p, int l) {
;     ...
;     float o[4][4], ss[4], e0[8], e1[8], sd[8];
; #pragma unroll
;     for (int u = 0; u < 4; ++u) {
;       o[u][0] = bflo(ga[u][0]) + bflo(gb[u][0]); o[u][1] = bfhi(ga[u][0]) + bfhi(gb[u][0]);
;       o[u][2] = bflo(ga[u][1]) + bflo(gb[u][1]); o[u][3] = bfhi(ga[u][1]) + bfhi(gb[u][1]);
;       ss[u] = o[u][0] * o[u][0] + o[u][1] * o[u][1] + o[u][2] * o[u][2] + o[u][3] * o[u][3];
;     }
; #pragma unroll
;     for (int h = 0; h < 8; ++h) {
;       e0[h] = bflo(da[h]) - lam * bflo(db[h]); e1[h] = bfhi(da[h]) - lam * bfhi(db[h]);
;       sd[h] = e0[h] * e0[h] + e1[h] * e1[h];
;     }
; #pragma unroll
;     for (int m = 32; m >= 1; m >>= 1) {
; #pragma unroll
;       for (int u = 0; u < 4; ++u) ss[u] += __shfl_xor(ss[u], m);
; #pragma unroll
;       for (int h = 0; h < 8; ++h) sd[h] += __shfl_xor(sd[h], m);
;     }
; #pragma unroll
;     for (int u = 0; u < 4; ++u) {
;       const float rsd = rsqrtf(ss[u] * (1.f / 256.f) + EPS);
;       const float rv[4] = {bflo(gr[u][0]), bfhi(gr[u][0]), bflo(gr[u][1]), bfhi(gr[u][1])};
;       float y[4];
; #pragma unroll
;       for (int j = 0; j < 4; ++j) y[j] = o[u][j] * rsd * gg[j] * siluf(rv[j]);
;       st4bf(ya + (long)r * 1024 + u * 256 + lane * 4, y[0], y[1], y[2], y[3]);
	v_mul_f32_e32 v70, 0xbfb8aa3b, v5
	v_fma_f32 v71, v5, s54, -v70
	v_rndne_f32_e32 v73, v70
	v_fmac_f32_e32 v71, 0xb2a5705f, v5
	v_sub_f32_e32 v70, v70, v73
	v_add_f32_e32 v70, v70, v71
	v_exp_f32_e32 v70, v70
	v_cvt_i32_f32_e32 v71, v73
	v_cmp_nlt_f32_e32 vcc, s55, v5
	v_ldexp_f32 v70, v70, v71
	v_mul_f32_e32 v71, 0xbfb8aa3b, v72
	v_fma_f32 v73, v72, s54, -v71
	v_rndne_f32_e32 v74, v71
	v_fmac_f32_e32 v73, 0xb2a5705f, v72
	v_sub_f32_e32 v71, v71, v74
	v_add_f32_e32 v71, v71, v73
	v_exp_f32_e32 v71, v71
	v_cvt_i32_f32_e32 v73, v74
	v_cndmask_b32_e32 v70, 0, v70, vcc
	v_cmp_ngt_f32_e32 vcc, s56, v5
	v_ldexp_f32 v71, v71, v73
	s_nop 0
	v_cndmask_b32_e32 v70, v212, v70, vcc
	v_cmp_nlt_f32_e32 vcc, s55, v72
	s_nop 1
	v_cndmask_b32_e32 v71, 0, v71, vcc
	v_cmp_ngt_f32_e32 vcc, s56, v72
	s_nop 1
	v_cndmask_b32_e32 v71, v212, v71, vcc
	v_pk_add_f32 v[70:71], v[70:71], 1.0 op_sel_hi:[1,0]
	s_nop 0
	v_div_scale_f32 v73, s[2:3], v71, v71, v72
	v_rcp_f32_e32 v74, v73
	s_nop 0
	v_fma_f32 v75, -v73, v74, 1.0
	v_fmac_f32_e32 v74, v75, v74
	v_div_scale_f32 v75, vcc, v72, v71, v72
	v_mul_f32_e32 v76, v75, v74
	v_fma_f32 v77, -v73, v76, v75
	v_fmac_f32_e32 v76, v77, v74
	v_fma_f32 v73, -v73, v76, v75
	v_div_fmas_f32 v73, v73, v74, v76
	v_div_fixup_f32 v73, v73, v71, v72
	v_div_scale_f32 v71, s[2:3], v70, v70, v5
	v_rcp_f32_e32 v72, v71
	v_and_b32_e32 v77, 0xffff0000, v58
	v_fma_f32 v74, -v71, v72, 1.0
	v_fmac_f32_e32 v72, v74, v72
	v_div_scale_f32 v74, vcc, v5, v70, v5
	v_mul_f32_e32 v75, v74, v72
	v_fma_f32 v76, -v71, v75, v74
	v_fmac_f32_e32 v75, v76, v72
	v_fma_f32 v71, -v71, v75, v74
	v_lshlrev_b32_e32 v76, 16, v58
	v_lshlrev_b32_e32 v58, 16, v54
	v_div_fmas_f32 v71, v71, v72, v75
	v_lshlrev_b32_e32 v74, 16, v57
	v_and_b32_e32 v75, 0xffff0000, v57
	v_pk_add_f32 v[56:57], v[76:77], v[78:79]
	v_and_b32_e32 v78, 0xffff0000, v54
	v_mul_f32_e32 v54, 0xbfb8aa3b, v58
	v_div_fixup_f32 v72, v71, v70, v5
	v_lshlrev_b32_e32 v70, 16, v59
	v_and_b32_e32 v71, 0xffff0000, v59
	v_lshlrev_b32_e32 v5, 16, v55
	v_and_b32_e32 v59, 0xffff0000, v55
	v_fma_f32 v55, v58, s54, -v54
	v_rndne_f32_e32 v79, v54
	v_fmac_f32_e32 v55, 0xb2a5705f, v58
	v_sub_f32_e32 v54, v54, v79
	v_add_f32_e32 v54, v54, v55
	v_exp_f32_e32 v54, v54
	v_cvt_i32_f32_e32 v55, v79
	v_cmp_nlt_f32_e32 vcc, s55, v58
	v_pk_add_f32 v[70:71], v[70:71], v[74:75]
	v_pk_mul_f32 v[76:77], v[56:57], v[56:57]
	v_ldexp_f32 v54, v54, v55
	v_mul_f32_e32 v55, 0xbfb8aa3b, v78
	v_fma_f32 v79, v78, s54, -v55
	v_rndne_f32_e32 v80, v55
	v_fmac_f32_e32 v79, 0xb2a5705f, v78
	v_sub_f32_e32 v55, v55, v80
	v_add_f32_e32 v55, v55, v79
	v_exp_f32_e32 v55, v55
	v_cvt_i32_f32_e32 v79, v80
	v_cndmask_b32_e32 v54, 0, v54, vcc
	v_cmp_ngt_f32_e32 vcc, s56, v58
	v_pk_mul_f32 v[74:75], v[70:71], v[70:71]
	v_ldexp_f32 v55, v55, v79
	v_cndmask_b32_e32 v54, v212, v54, vcc
	v_cmp_nlt_f32_e32 vcc, s55, v78
	s_nop 1
	v_cndmask_b32_e32 v55, 0, v55, vcc
	v_cmp_ngt_f32_e32 vcc, s56, v78
	s_nop 1
	v_cndmask_b32_e32 v55, v212, v55, vcc
	v_pk_add_f32 v[54:55], v[54:55], 1.0 op_sel_hi:[1,0]
	s_nop 0
	v_div_scale_f32 v79, s[2:3], v55, v55, v78
	v_rcp_f32_e32 v80, v79
	s_nop 0
	v_fma_f32 v81, -v79, v80, 1.0
	v_fmac_f32_e32 v80, v81, v80
	v_div_scale_f32 v81, vcc, v78, v55, v78
	v_mul_f32_e32 v82, v81, v80
	v_fma_f32 v83, -v79, v82, v81
	v_fmac_f32_e32 v82, v83, v80
	v_fma_f32 v79, -v79, v82, v81
	v_div_fmas_f32 v79, v79, v80, v82
	v_div_fixup_f32 v55, v79, v55, v78
	v_div_scale_f32 v78, s[2:3], v54, v54, v58
	v_rcp_f32_e32 v79, v78
	s_nop 0
	v_fma_f32 v80, -v78, v79, 1.0
	v_fmac_f32_e32 v79, v80, v79
	v_div_scale_f32 v80, vcc, v58, v54, v58
	v_mul_f32_e32 v81, v80, v79
	v_fma_f32 v82, -v78, v81, v80
	v_fmac_f32_e32 v81, v82, v79
	v_fma_f32 v78, -v78, v81, v80
	v_div_fmas_f32 v78, v78, v79, v81
	v_div_fixup_f32 v54, v78, v54, v58
	v_mov_b32_e32 v78, v76
	v_mov_b32_e32 v79, v64
	v_mov_b32_e32 v64, v77
	v_pk_add_f32 v[64:65], v[78:79], v[64:65]
	v_mov_b32_e32 v76, v74
	v_mov_b32_e32 v77, v68
	v_pk_add_f32 v[64:65], v[76:77], v[64:65]
	v_mov_b32_e32 v68, v75
	v_pk_add_f32 v[64:65], v[68:69], v[64:65]
	v_mov_b32_e32 v69, v65
	v_mov_b32_e32 v68, v64
	s_waitcnt lgkmcnt(0)
	s_nop 1
	v_permlane32_swap_b32_e32 v64, v68
	v_permlane32_swap_b32_e32 v65, v69
	v_pk_add_f32 v[64:65], v[64:65], v[68:69]
	v_mov_b32_e32 v69, v65
	v_mov_b32_e32 v68, v64
	s_waitcnt lgkmcnt(0)
	s_nop 1
	v_permlane16_swap_b32_e32 v64, v68
	v_permlane16_swap_b32_e32 v65, v69
	v_pk_add_f32 v[64:65], v[64:65], v[68:69]
	s_waitcnt lgkmcnt(0)
	s_nop 1
	v_add_f32_dpp v64, v64, v64 row_ror:8 row_mask:0xf bank_mask:0xf
	v_add_f32_dpp v65, v65, v65 row_ror:8 row_mask:0xf bank_mask:0xf
	s_waitcnt lgkmcnt(0)
	s_nop 1
	v_add_f32_dpp v64, v64, v64 row_ror:4 row_mask:0xf bank_mask:0xf
	v_add_f32_dpp v65, v65, v65 row_ror:4 row_mask:0xf bank_mask:0xf
	s_waitcnt lgkmcnt(0)
	s_nop 1
	v_add_f32_dpp v64, v64, v64 quad_perm:[2,3,0,1] row_mask:0xf bank_mask:0xf
	v_add_f32_dpp v65, v65, v65 quad_perm:[2,3,0,1] row_mask:0xf bank_mask:0xf
	s_waitcnt lgkmcnt(0)
; DEVI unsigned cvtpk(float lo, float hi) { f32x2_t v = {lo, hi}; bf16x2_t b = __builtin_convertvector(v, bf16x2_t); return __builtin_bit_cast(unsigned, b); }
; DEVI float bflo(unsigned w) { return __uint_as_float(w << 16); }
; DEVI float bfhi(unsigned w) { return __uint_as_float(w & 0xffff0000u); }
; DEVI void st4bf(u16* p, float a, float b, float c, float d) { u32x2 w = {cvtpk(a, b), cvtpk(c, d)}; *(u32x2*)p = w; }
; DEVI float siluf(float x) { return x / (1.f + expf(-x)); }
; DEVI void phase_prep(const Params& p, int l) {
;     ...
; #pragma unroll
;     for (int m = 32; m >= 1; m >>= 1) {
; #pragma unroll
;       for (int u = 0; u < 4; ++u) ss[u] += __shfl_xor(ss[u], m);
; #pragma unroll
;       for (int h = 0; h < 8; ++h) sd[h] += __shfl_xor(sd[h], m);
;     }
; #pragma unroll
;     for (int u = 0; u < 4; ++u) {
;       const float rsd = rsqrtf(ss[u] * (1.f / 256.f) + EPS);
;       const float rv[4] = {bflo(gr[u][0]), bfhi(gr[u][0]), bflo(gr[u][1]), bfhi(gr[u][1])};
;       float y[4];
; #pragma unroll
;       for (int j = 0; j < 4; ++j) y[j] = o[u][j] * rsd * gg[j] * siluf(rv[j]);
;       st4bf(ya + (long)r * 1024 + u * 256 + lane * 4, y[0], y[1], y[2], y[3]);
;     }
; #pragma unroll
;     for (int h = 0; h < 8; ++h) {
;       const float rsd = rsqrtf(sd[h] * (1.f / 128.f) + EPS);
;       *(unsigned*)(yb + (long)r * 1024 + h * 128 + lane * 2) = cvtpk(e0[h] * rsd * dg0, e1[h] * rsd * dg1);
	s_nop 1
	v_add_f32_dpp v64, v64, v64 quad_perm:[1,0,3,2] row_mask:0xf bank_mask:0xf
	v_add_f32_dpp v65, v65, v65 quad_perm:[1,0,3,2] row_mask:0xf bank_mask:0xf
	s_nop 0
	v_pk_fma_f32 v[64:65], v[64:65], s[26:27], v[52:53] op_sel_hi:[1,0,0]
	s_nop 0
	v_mul_f32_e32 v58, 0x4b800000, v65
	v_cmp_gt_f32_e64 s[2:3], s59, v65
	v_cmp_gt_f32_e32 vcc, s59, v64
	s_nop 0
	v_cndmask_b32_e64 v58, v65, v58, s[2:3]
	v_rsq_f32_e32 v58, v58
	s_nop 0
	v_mul_f32_e32 v65, 0x45800000, v58
	v_cndmask_b32_e64 v58, v58, v65, s[2:3]
	v_pk_mul_f32 v[62:63], v[62:63], v[58:59] op_sel_hi:[1,0]
	s_nop 0
	v_pk_mul_f32 v[62:63], v[0:1], v[62:63]
	s_nop 0
	v_pk_mul_f32 v[60:61], v[60:61], v[62:63]
	v_pk_mul_f32 v[62:63], v[66:67], v[58:59] op_sel_hi:[1,0]
	v_mul_f32_e32 v58, 0x4b800000, v64
	v_cndmask_b32_e32 v58, v64, v58, vcc
	v_rsq_f32_e32 v58, v58
	v_pk_mul_f32 v[62:63], v[2:3], v[62:63]
	v_cvt_pk_bf16_f32 v60, v60, v61
	v_pk_mul_f32 v[62:63], v[72:73], v[62:63]
	s_nop 0
	v_cvt_pk_bf16_f32 v61, v62, v63
	global_store_dwordx2 v[42:43], v[60:61], off offset:3072
	v_mul_f32_e32 v60, 0x45800000, v58
	v_cndmask_b32_e32 v58, v58, v60, vcc
	v_pk_mul_f32 v[56:57], v[56:57], v[58:59] op_sel_hi:[1,0]
	v_cmp_nlt_f32_e32 vcc, s55, v5
	v_pk_mul_f32 v[56:57], v[0:1], v[56:57]
	s_nop 0
	v_pk_mul_f32 v[54:55], v[54:55], v[56:57]
	v_mul_f32_e32 v56, 0xbfb8aa3b, v5
	v_fma_f32 v57, v5, s54, -v56
	v_rndne_f32_e32 v60, v56
	v_fmac_f32_e32 v57, 0xb2a5705f, v5
	v_sub_f32_e32 v56, v56, v60
	v_add_f32_e32 v56, v56, v57
	v_exp_f32_e32 v56, v56
	v_cvt_i32_f32_e32 v57, v60
	v_pk_mul_f32 v[60:61], v[70:71], v[58:59] op_sel_hi:[1,0]
	v_cvt_pk_bf16_f32 v54, v54, v55
	v_pk_mul_f32 v[60:61], v[2:3], v[60:61]
	v_ldexp_f32 v56, v56, v57
	v_mul_f32_e32 v57, 0xbfb8aa3b, v59
	v_fma_f32 v58, v59, s54, -v57
	v_rndne_f32_e32 v62, v57
	v_fmac_f32_e32 v58, 0xb2a5705f, v59
	v_sub_f32_e32 v57, v57, v62
	v_add_f32_e32 v57, v57, v58
	v_exp_f32_e32 v57, v57
	v_cvt_i32_f32_e32 v58, v62
	v_cndmask_b32_e32 v56, 0, v56, vcc
	v_cmp_ngt_f32_e32 vcc, s56, v5
	v_ldexp_f32 v57, v57, v58
	s_nop 0
	v_cndmask_b32_e32 v56, v212, v56, vcc
	v_cmp_nlt_f32_e32 vcc, s55, v59
	s_nop 1
	v_cndmask_b32_e32 v57, 0, v57, vcc
	v_cmp_ngt_f32_e32 vcc, s56, v59
	s_nop 1
	v_cndmask_b32_e32 v57, v212, v57, vcc
	v_pk_add_f32 v[56:57], v[56:57], 1.0 op_sel_hi:[1,0]
	s_nop 0
	v_div_scale_f32 v58, s[2:3], v57, v57, v59
	v_rcp_f32_e32 v62, v58
	s_nop 0
	v_fma_f32 v63, -v58, v62, 1.0
	v_fmac_f32_e32 v62, v63, v62
	v_div_scale_f32 v63, vcc, v59, v57, v59
	v_mul_f32_e32 v64, v63, v62
	v_fma_f32 v65, -v58, v64, v63
	v_fmac_f32_e32 v64, v65, v62
	v_fma_f32 v58, -v58, v64, v63
	v_div_fmas_f32 v58, v58, v62, v64
	v_div_fixup_f32 v57, v58, v57, v59
	v_div_scale_f32 v58, s[2:3], v56, v56, v5
	v_rcp_f32_e32 v59, v58
	s_nop 0
	v_fma_f32 v62, -v58, v59, 1.0
	v_fmac_f32_e32 v59, v62, v59
	v_div_scale_f32 v62, vcc, v5, v56, v5
	v_mul_f32_e32 v63, v62, v59
	v_fma_f32 v64, -v58, v63, v62
	v_fmac_f32_e32 v63, v64, v59
	v_fma_f32 v58, -v58, v63, v62
	v_div_fmas_f32 v58, v58, v59, v63
	v_div_fixup_f32 v56, v58, v56, v5
	v_pk_mul_f32 v[56:57], v[56:57], v[60:61]
	s_nop 0
	v_cvt_pk_bf16_f32 v55, v56, v57
	global_store_dwordx2 v[42:43], v[54:55], off offset:3584
	v_pk_fma_f32 v[42:43], v[12:13], v[46:47], v[44:45] neg_lo:[1,0,0] neg_hi:[1,0,0]
	v_pk_fma_f32 v[46:47], v[12:13], v[50:51], v[48:49] neg_lo:[1,0,0] neg_hi:[1,0,0]
	v_pk_mul_f32 v[44:45], v[42:43], v[42:43]
	v_pk_mul_f32 v[48:49], v[46:47], v[46:47]
	v_mov_b32_e32 v51, v44
	v_mov_b32_e32 v50, v48
	v_mov_b32_e32 v44, v49
	v_pk_add_f32 v[44:45], v[50:51], v[44:45]
	v_mov_b32_e32 v49, v45
	v_mov_b32_e32 v48, v44
	s_waitcnt lgkmcnt(0)
	s_nop 1
	v_permlane32_swap_b32_e32 v44, v48
	v_permlane32_swap_b32_e32 v45, v49
	v_pk_add_f32 v[44:45], v[44:45], v[48:49]
	v_mov_b32_e32 v49, v45
	v_mov_b32_e32 v48, v44
	s_waitcnt lgkmcnt(0)
	s_nop 1
	v_permlane16_swap_b32_e32 v44, v48
	v_permlane16_swap_b32_e32 v45, v49
	v_pk_add_f32 v[44:45], v[44:45], v[48:49]
	s_waitcnt lgkmcnt(0)
	s_nop 1
	v_add_f32_dpp v44, v44, v44 row_ror:8 row_mask:0xf bank_mask:0xf
	v_add_f32_dpp v45, v45, v45 row_ror:8 row_mask:0xf bank_mask:0xf
	s_waitcnt lgkmcnt(0)
	s_nop 1
	v_add_f32_dpp v44, v44, v44 row_ror:4 row_mask:0xf bank_mask:0xf
	v_add_f32_dpp v45, v45, v45 row_ror:4 row_mask:0xf bank_mask:0xf
	s_waitcnt lgkmcnt(0)
	s_nop 1
	v_add_f32_dpp v44, v44, v44 quad_perm:[2,3,0,1] row_mask:0xf bank_mask:0xf
	v_add_f32_dpp v45, v45, v45 quad_perm:[2,3,0,1] row_mask:0xf bank_mask:0xf
	s_waitcnt lgkmcnt(0)
	s_nop 1
	v_add_f32_dpp v44, v44, v44 quad_perm:[1,0,3,2] row_mask:0xf bank_mask:0xf
	v_add_f32_dpp v45, v45, v45 quad_perm:[1,0,3,2] row_mask:0xf bank_mask:0xf
	s_nop 0
	v_pk_fma_f32 v[44:45], v[44:45], s[28:29], v[52:53] op_sel_hi:[1,0,0]
	s_nop 0
	v_mul_f32_e32 v5, 0x4b800000, v45
	v_cmp_gt_f32_e64 s[2:3], s59, v45
	v_cmp_gt_f32_e32 vcc, s59, v44
	s_nop 0
	v_cndmask_b32_e64 v5, v45, v5, s[2:3]
	v_rsq_f32_e32 v5, v5
	s_nop 0
	v_mul_f32_e32 v45, 0x45800000, v5
	v_cndmask_b32_e64 v48, v5, v45, s[2:3]
	v_pk_mul_f32 v[42:43], v[42:43], v[48:49] op_sel_hi:[1,0]
	s_nop 0
	v_pk_mul_f32 v[42:43], v[14:15], v[42:43]
	s_nop 0
	v_cvt_pk_bf16_f32 v5, v42, v43
	global_store_dword v[16:17], v5, off offset:2048
	v_mul_f32_e32 v5, 0x4b800000, v44
	v_cndmask_b32_e32 v5, v44, v5, vcc
	v_rsq_f32_e32 v5, v5
	s_nop 0
	v_mul_f32_e32 v42, 0x45800000, v5
	v_cndmask_b32_e32 v42, v5, v42, vcc
	v_pk_mul_f32 v[42:43], v[46:47], v[42:43] op_sel_hi:[1,0]
	s_nop 0
	v_pk_mul_f32 v[42:43], v[14:15], v[42:43]
	s_nop 0
	v_cvt_pk_bf16_f32 v5, v42, v43
	v_mov_b32_e32 v42, v40
	v_mov_b32_e32 v43, v36
	v_mov_b32_e32 v36, v41
	v_pk_add_f32 v[36:37], v[42:43], v[36:37]
	v_mov_b32_e32 v41, v37
	v_mov_b32_e32 v40, v36
	global_store_dword v[16:17], v5, off offset:2304
	s_waitcnt lgkmcnt(0)
; DEVI unsigned cvtpk(float lo, float hi) { f32x2_t v = {lo, hi}; bf16x2_t b = __builtin_convertvector(v, bf16x2_t); return __builtin_bit_cast(unsigned, b); }
; DEVI float bflo(unsigned w) { return __uint_as_float(w << 16); }
; DEVI float bfhi(unsigned w) { return __uint_as_float(w & 0xffff0000u); }
; DEVI void st4bf(u16* p, float a, float b, float c, float d) { u32x2 w = {cvtpk(a, b), cvtpk(c, d)}; *(u32x2*)p = w; }
; DEVI float siluf(float x) { return x / (1.f + expf(-x)); }
; DEVI void phase_prep(const Params& p, int l) {
;     ...
; #pragma unroll
;     for (int m = 32; m >= 1; m >>= 1) {
; #pragma unroll
;       for (int u = 0; u < 4; ++u) ss[u] += __shfl_xor(ss[u], m);
; #pragma unroll
;       for (int h = 0; h < 8; ++h) sd[h] += __shfl_xor(sd[h], m);
;     }
; #pragma unroll
;     for (int u = 0; u < 4; ++u) {
;       const float rsd = rsqrtf(ss[u] * (1.f / 256.f) + EPS);
;       const float rv[4] = {bflo(gr[u][0]), bfhi(gr[u][0]), bflo(gr[u][1]), bfhi(gr[u][1])};
;       float y[4];
; #pragma unroll
;       for (int j = 0; j < 4; ++j) y[j] = o[u][j] * rsd * gg[j] * siluf(rv[j]);
;       st4bf(ya + (long)r * 1024 + u * 256 + lane * 4, y[0], y[1], y[2], y[3]);
;     }
; #pragma unroll
;     for (int h = 0; h < 8; ++h) {
;       const float rsd = rsqrtf(sd[h] * (1.f / 128.f) + EPS);
;       *(unsigned*)(yb + (long)r * 1024 + h * 128 + lane * 2) = cvtpk(e0[h] * rsd * dg0, e1[h] * rsd * dg1);
;     }
	s_nop 1
	v_permlane32_swap_b32_e32 v36, v40
	v_permlane32_swap_b32_e32 v37, v41
	v_pk_add_f32 v[36:37], v[36:37], v[40:41]
	v_mov_b32_e32 v41, v37
	v_mov_b32_e32 v40, v36
	s_waitcnt lgkmcnt(0)
	s_nop 1
	v_permlane16_swap_b32_e32 v36, v40
	v_permlane16_swap_b32_e32 v37, v41
	v_pk_add_f32 v[36:37], v[36:37], v[40:41]
	s_waitcnt lgkmcnt(0)
	s_nop 1
	v_add_f32_dpp v36, v36, v36 row_ror:8 row_mask:0xf bank_mask:0xf
	v_add_f32_dpp v37, v37, v37 row_ror:8 row_mask:0xf bank_mask:0xf
	s_waitcnt lgkmcnt(0)
	s_nop 1
	v_add_f32_dpp v36, v36, v36 row_ror:4 row_mask:0xf bank_mask:0xf
	v_add_f32_dpp v37, v37, v37 row_ror:4 row_mask:0xf bank_mask:0xf
	s_waitcnt lgkmcnt(0)
	s_nop 1
	v_add_f32_dpp v36, v36, v36 quad_perm:[2,3,0,1] row_mask:0xf bank_mask:0xf
	v_add_f32_dpp v37, v37, v37 quad_perm:[2,3,0,1] row_mask:0xf bank_mask:0xf
	s_waitcnt lgkmcnt(0)
	s_nop 1
	v_add_f32_dpp v36, v36, v36 quad_perm:[1,0,3,2] row_mask:0xf bank_mask:0xf
	v_add_f32_dpp v37, v37, v37 quad_perm:[1,0,3,2] row_mask:0xf bank_mask:0xf
	s_nop 0
	v_pk_fma_f32 v[36:37], v[36:37], s[28:29], v[52:53] op_sel_hi:[1,0,0]
	s_nop 0
	v_mul_f32_e32 v5, 0x4b800000, v37
	v_cmp_gt_f32_e64 s[2:3], s59, v37
	v_cmp_gt_f32_e32 vcc, s59, v36
	s_nop 0
	v_cndmask_b32_e64 v5, v37, v5, s[2:3]
	v_rsq_f32_e32 v5, v5
	s_nop 0
	v_mul_f32_e32 v37, 0x45800000, v5
	v_cndmask_b32_e64 v40, v5, v37, s[2:3]
	v_pk_mul_f32 v[34:35], v[34:35], v[40:41] op_sel_hi:[1,0]
	s_nop 0
	v_pk_mul_f32 v[34:35], v[14:15], v[34:35]
	s_nop 0
	v_cvt_pk_bf16_f32 v5, v34, v35
	global_store_dword v[16:17], v5, off offset:2560
	v_mul_f32_e32 v5, 0x4b800000, v36
	v_cndmask_b32_e32 v5, v36, v5, vcc
	v_rsq_f32_e32 v5, v5
	s_nop 0
	v_mul_f32_e32 v34, 0x45800000, v5
	v_cndmask_b32_e32 v34, v5, v34, vcc
	v_pk_mul_f32 v[34:35], v[38:39], v[34:35] op_sel_hi:[1,0]
	s_nop 0
	v_pk_mul_f32 v[34:35], v[14:15], v[34:35]
	s_nop 0
	v_cvt_pk_bf16_f32 v5, v34, v35
	v_mov_b32_e32 v34, v32
	v_mov_b32_e32 v35, v28
	v_mov_b32_e32 v28, v33
	v_pk_add_f32 v[28:29], v[34:35], v[28:29]
	v_mov_b32_e32 v33, v29
	v_mov_b32_e32 v32, v28
	global_store_dword v[16:17], v5, off offset:2816
	s_waitcnt lgkmcnt(0)
	s_nop 1
	v_permlane32_swap_b32_e32 v28, v32
	v_permlane32_swap_b32_e32 v29, v33
	v_pk_add_f32 v[28:29], v[28:29], v[32:33]
	v_mov_b32_e32 v33, v29
	v_mov_b32_e32 v32, v28
	s_waitcnt lgkmcnt(0)
	s_nop 1
	v_permlane16_swap_b32_e32 v28, v32
	v_permlane16_swap_b32_e32 v29, v33
	v_pk_add_f32 v[28:29], v[28:29], v[32:33]
	s_waitcnt lgkmcnt(0)
	s_nop 1
	v_add_f32_dpp v28, v28, v28 row_ror:8 row_mask:0xf bank_mask:0xf
	v_add_f32_dpp v29, v29, v29 row_ror:8 row_mask:0xf bank_mask:0xf
	s_waitcnt lgkmcnt(0)
	s_nop 1
	v_add_f32_dpp v28, v28, v28 row_ror:4 row_mask:0xf bank_mask:0xf
	v_add_f32_dpp v29, v29, v29 row_ror:4 row_mask:0xf bank_mask:0xf
	s_waitcnt lgkmcnt(0)
	s_nop 1
	v_add_f32_dpp v28, v28, v28 quad_perm:[2,3,0,1] row_mask:0xf bank_mask:0xf
	v_add_f32_dpp v29, v29, v29 quad_perm:[2,3,0,1] row_mask:0xf bank_mask:0xf
	s_waitcnt lgkmcnt(0)
	s_nop 1
	v_add_f32_dpp v28, v28, v28 quad_perm:[1,0,3,2] row_mask:0xf bank_mask:0xf
	v_add_f32_dpp v29, v29, v29 quad_perm:[1,0,3,2] row_mask:0xf bank_mask:0xf
	s_nop 0
	v_pk_fma_f32 v[28:29], v[28:29], s[28:29], v[52:53] op_sel_hi:[1,0,0]
	s_nop 0
	v_mul_f32_e32 v5, 0x4b800000, v29
	v_cmp_gt_f32_e64 s[2:3], s59, v29
	v_cmp_gt_f32_e32 vcc, s59, v28
	s_nop 0
	v_cndmask_b32_e64 v5, v29, v5, s[2:3]
	v_rsq_f32_e32 v5, v5
	s_nop 0
	v_mul_f32_e32 v29, 0x45800000, v5
	v_cndmask_b32_e64 v32, v5, v29, s[2:3]
	v_pk_mul_f32 v[26:27], v[26:27], v[32:33] op_sel_hi:[1,0]
	s_nop 0
	v_pk_mul_f32 v[26:27], v[14:15], v[26:27]
	s_nop 0
	v_cvt_pk_bf16_f32 v5, v26, v27
	global_store_dword v[16:17], v5, off offset:3072
	v_mul_f32_e32 v5, 0x4b800000, v28
	v_cndmask_b32_e32 v5, v28, v5, vcc
	v_rsq_f32_e32 v5, v5
	s_nop 0
	v_mul_f32_e32 v26, 0x45800000, v5
	v_cndmask_b32_e32 v26, v5, v26, vcc
	v_pk_mul_f32 v[26:27], v[30:31], v[26:27] op_sel_hi:[1,0]
	s_nop 0
	v_pk_mul_f32 v[26:27], v[14:15], v[26:27]
	s_nop 0
	v_cvt_pk_bf16_f32 v5, v26, v27
	v_mov_b32_e32 v26, v24
	v_mov_b32_e32 v27, v20
	v_mov_b32_e32 v20, v25
	v_pk_add_f32 v[20:21], v[26:27], v[20:21]
	v_mov_b32_e32 v25, v21
	v_mov_b32_e32 v24, v20
	global_store_dword v[16:17], v5, off offset:3328
	s_waitcnt lgkmcnt(0)
	s_nop 1
	v_permlane32_swap_b32_e32 v20, v24
	v_permlane32_swap_b32_e32 v21, v25
	v_pk_add_f32 v[20:21], v[20:21], v[24:25]
	v_mov_b32_e32 v25, v21
	v_mov_b32_e32 v24, v20
	s_waitcnt lgkmcnt(0)
	s_nop 1
	v_permlane16_swap_b32_e32 v20, v24
	v_permlane16_swap_b32_e32 v21, v25
	v_pk_add_f32 v[20:21], v[20:21], v[24:25]
	s_waitcnt lgkmcnt(0)
	s_nop 1
	v_add_f32_dpp v20, v20, v20 row_ror:8 row_mask:0xf bank_mask:0xf
	v_add_f32_dpp v21, v21, v21 row_ror:8 row_mask:0xf bank_mask:0xf
	s_waitcnt lgkmcnt(0)
	s_nop 1
	v_add_f32_dpp v20, v20, v20 row_ror:4 row_mask:0xf bank_mask:0xf
	v_add_f32_dpp v21, v21, v21 row_ror:4 row_mask:0xf bank_mask:0xf
	s_waitcnt lgkmcnt(0)
	s_nop 1
	v_add_f32_dpp v20, v20, v20 quad_perm:[2,3,0,1] row_mask:0xf bank_mask:0xf
	v_add_f32_dpp v21, v21, v21 quad_perm:[2,3,0,1] row_mask:0xf bank_mask:0xf
	s_waitcnt lgkmcnt(0)
	s_nop 1
	v_add_f32_dpp v20, v20, v20 quad_perm:[1,0,3,2] row_mask:0xf bank_mask:0xf
	v_add_f32_dpp v21, v21, v21 quad_perm:[1,0,3,2] row_mask:0xf bank_mask:0xf
	s_nop 0
	v_pk_fma_f32 v[20:21], v[20:21], s[28:29], v[52:53] op_sel_hi:[1,0,0]
	s_nop 0
	v_mul_f32_e32 v5, 0x4b800000, v21
	v_cmp_gt_f32_e64 s[2:3], s59, v21
	v_cmp_gt_f32_e32 vcc, s59, v20
	s_nop 0
	v_cndmask_b32_e64 v5, v21, v5, s[2:3]
	v_rsq_f32_e32 v5, v5
	s_nop 0
	v_mul_f32_e32 v21, 0x45800000, v5
	v_cndmask_b32_e64 v24, v5, v21, s[2:3]
	v_pk_mul_f32 v[18:19], v[18:19], v[24:25] op_sel_hi:[1,0]
	s_nop 0
	v_pk_mul_f32 v[18:19], v[14:15], v[18:19]
	s_nop 0
	v_cvt_pk_bf16_f32 v5, v18, v19
	global_store_dword v[16:17], v5, off offset:3584
	v_mul_f32_e32 v5, 0x4b800000, v20
	v_cndmask_b32_e32 v5, v20, v5, vcc
	v_rsq_f32_e32 v5, v5
	s_nop 0
	v_mul_f32_e32 v18, 0x45800000, v5
	v_cndmask_b32_e32 v18, v5, v18, vcc
	v_pk_mul_f32 v[18:19], v[22:23], v[18:19] op_sel_hi:[1,0]
	s_nop 0
	v_pk_mul_f32 v[18:19], v[14:15], v[18:19]
	s_nop 0
	v_cvt_pk_bf16_f32 v5, v18, v19
	global_store_dword v[16:17], v5, off offset:3840
	s_branch .LBB0_494

; DEVI void st4bf(u16* p, float a, float b, float c, float d) { u32x2 w = {cvtpk(a, b), cvtpk(c, d)}; *(u32x2*)p = w; }
; DEVI void ln_stats(const float (&v)[16], float& mu, float& rstd) {
;   float s = 0.f;
; #pragma unroll
;   for (int i = 0; i < 16; ++i) s += v[i];
;   mu = wave_sum(s) * (1.f / 1024.f);
;   float q = 0.f;
; #pragma unroll
;   for (int i = 0; i < 16; ++i) { const float d = v[i] - mu; q += d * d; }
;   rstd = rsqrtf(wave_sum(q) * (1.f / 1024.f) + EPS);
; }
; DEVI void rowproc(float (&v)[16], float* __restrict__ dst, const float* __restrict__ ag, const float* __restrict__ ab,
;                   u16* __restrict__ hout, const float* __restrict__ sh, const float* __restrict__ sc) {
;     ...
;   if (hout) {
;     ln_stats(v, mu, rstd);
; #pragma unroll
;     for (int i = 0; i < 4; ++i) {
;       const f32x4 s1 = *(const f32x4*)(sc + i * 256 + lane * 4);
;       const f32x4 s0 = *(const f32x4*)(sh + i * 256 + lane * 4);
;       float h[4];
; #pragma unroll
;       for (int j = 0; j < 4; ++j) h[j] = (v[i * 4 + j] - mu) * rstd * (1.f + s1[j]) + s0[j];
;       st4bf(hout + i * 256 + lane * 4, h[0], h[1], h[2], h[3]);
.LBB0_565:
	s_waitcnt vmcnt(3)
	v_add_f32_e32 v0, 0, v16
	v_add_f32_e32 v0, v17, v0
	v_add_f32_e32 v0, v18, v0
	v_add_f32_e32 v0, v19, v0
	v_add_f32_e32 v0, v20, v0
	v_add_f32_e32 v0, v21, v0
	v_add_f32_e32 v0, v22, v0
	v_add_f32_e32 v0, v23, v0
	v_add_f32_e32 v0, v24, v0
	v_add_f32_e32 v0, v25, v0
	v_add_f32_e32 v0, v26, v0
	v_add_f32_e32 v0, v27, v0
	v_add_f32_e32 v0, v28, v0
	v_add_f32_e32 v0, v29, v0
	v_add_f32_e32 v0, v30, v0
	v_add_f32_e32 v0, v31, v0
	v_mov_b32_e32 v1, v0
	v_readlane_b32 s2, v252, 43
	v_readlane_b32 s3, v252, 44
	s_waitcnt vmcnt(2)
	v_add_u32_e32 v4, s39, v66
	s_waitcnt lgkmcnt(0)
	s_nop 1
	v_permlane32_swap_b32_e32 v0, v1
	v_add_f32_e32 v2, v0, v1
	v_mov_b32_e32 v3, v2
	v_mov_b64_e32 v[0:1], s[2:3]
	s_movk_i32 s2, 0x6000
	v_mad_u64_u32 v[0:1], s[2:3], v4, s2, v[0:1]
	s_waitcnt lgkmcnt(0)
	s_nop 1
	v_permlane16_swap_b32_e32 v2, v3
	v_add_f32_e32 v2, v2, v3
	s_waitcnt vmcnt(1)
	v_lshl_add_u64 v[8:9], v[192:193], 2, v[0:1]
	s_mov_b64 s[2:3], 0x4000
	v_lshl_add_u64 v[16:17], v[8:9], 0, s[2:3]
	s_mov_b64 s[2:3], 0x3000
	s_waitcnt lgkmcnt(0)
	s_nop 1
	v_add_f32_dpp v10, v2, v2 row_ror:8 row_mask:0xf bank_mask:0xf
	v_lshl_add_u64 v[28:29], v[8:9], 0, s[2:3]
	s_movk_i32 s2, 0x4000
	v_add_co_u32_e32 v0, vcc, s2, v8
	s_waitcnt lgkmcnt(0)
	s_nop 1
	v_add_f32_dpp v10, v10, v10 row_ror:4 row_mask:0xf bank_mask:0xf
	v_addc_co_u32_e32 v1, vcc, 0, v9, vcc
	s_movk_i32 s2, 0x3000
	v_add_co_u32_e32 v20, vcc, s2, v8
	global_load_dwordx4 v[0:3], v[0:1], off
	s_nop 0
	global_load_dwordx4 v[4:7], v[16:17], off offset:1024
	v_addc_co_u32_e32 v21, vcc, 0, v9, vcc
	s_waitcnt lgkmcnt(0)
	s_nop 1
	v_add_f32_dpp v24, v10, v10 quad_perm:[2,3,0,1] row_mask:0xf bank_mask:0xf
	global_load_dwordx4 v[8:11], v[16:17], off offset:2048
	global_load_dwordx4 v[12:15], v[28:29], off offset:1024
	s_nop 0
	global_load_dwordx4 v[16:19], v[16:17], off offset:3072
	s_nop 0
	global_load_dwordx4 v[20:23], v[20:21], off
	v_readlane_b32 s2, v253, 6
	v_readlane_b32 s3, v253, 7
	s_waitcnt lgkmcnt(0)
	s_nop 1
	v_add_f32_dpp v24, v24, v24 quad_perm:[1,0,3,2] row_mask:0xf bank_mask:0xf
	v_mul_f32_e32 v66, 0x3a800000, v24
	global_load_dwordx4 v[24:27], v[28:29], off offset:2048
	s_nop 0
	global_load_dwordx4 v[28:31], v[28:29], off offset:3072
	v_pk_add_f32 v[32:33], v[32:33], v[66:67] op_sel_hi:[1,0] neg_lo:[0,1] neg_hi:[0,1]
	v_pk_add_f32 v[34:35], v[34:35], v[66:67] op_sel_hi:[1,0] neg_lo:[0,1] neg_hi:[0,1]
	v_pk_mul_f32 v[72:73], v[32:33], v[32:33]
	v_pk_mul_f32 v[70:71], v[34:35], v[34:35]
	v_add_f32_e32 v65, v72, v73
	v_pk_add_f32 v[36:37], v[36:37], v[66:67] op_sel_hi:[1,0] neg_lo:[0,1] neg_hi:[0,1]
	v_add_f32_e32 v65, v70, v65
	v_pk_mul_f32 v[76:77], v[36:37], v[36:37]
	v_add_f32_e32 v65, v71, v65
	v_pk_add_f32 v[38:39], v[38:39], v[66:67] op_sel_hi:[1,0] neg_lo:[0,1] neg_hi:[0,1]
	v_add_f32_e32 v65, v76, v65
	v_pk_mul_f32 v[74:75], v[38:39], v[38:39]
	v_add_f32_e32 v65, v77, v65
	v_pk_add_f32 v[40:41], v[40:41], v[66:67] op_sel_hi:[1,0] neg_lo:[0,1] neg_hi:[0,1]
	v_add_f32_e32 v65, v74, v65
	v_pk_mul_f32 v[80:81], v[40:41], v[40:41]
	v_add_f32_e32 v65, v75, v65
	v_pk_add_f32 v[42:43], v[42:43], v[66:67] op_sel_hi:[1,0] neg_lo:[0,1] neg_hi:[0,1]
	v_add_f32_e32 v65, v80, v65
	v_pk_mul_f32 v[78:79], v[42:43], v[42:43]
	v_add_f32_e32 v65, v81, v65
	v_pk_add_f32 v[44:45], v[44:45], v[66:67] op_sel_hi:[1,0] neg_lo:[0,1] neg_hi:[0,1]
	v_add_f32_e32 v65, v78, v65
	v_pk_add_f32 v[46:47], v[46:47], v[66:67] op_sel_hi:[1,0] neg_lo:[0,1] neg_hi:[0,1]
	v_pk_mul_f32 v[66:67], v[44:45], v[44:45]
	v_add_f32_e32 v65, v79, v65
	v_add_f32_e32 v65, v66, v65
	v_pk_mul_f32 v[82:83], v[46:47], v[46:47]
	v_add_f32_e32 v65, v67, v65
	v_add_f32_e32 v65, v82, v65
	v_add_f32_e32 v65, v83, v65
	v_mov_b32_e32 v66, v65
	s_waitcnt lgkmcnt(0)
; DEVI void st4bf(u16* p, float a, float b, float c, float d) { u32x2 w = {cvtpk(a, b), cvtpk(c, d)}; *(u32x2*)p = w; }
; DEVI void ln_stats(const float (&v)[16], float& mu, float& rstd) {
;     ...
;   mu = wave_sum(s) * (1.f / 1024.f);
;   float q = 0.f;
; #pragma unroll
;   for (int i = 0; i < 16; ++i) { const float d = v[i] - mu; q += d * d; }
;   rstd = rsqrtf(wave_sum(q) * (1.f / 1024.f) + EPS);
; }
; DEVI void rowproc(float (&v)[16], float* __restrict__ dst, const float* __restrict__ ag, const float* __restrict__ ab,
;                   u16* __restrict__ hout, const float* __restrict__ sh, const float* __restrict__ sc) {
;     ...
;   if (hout) {
;     ln_stats(v, mu, rstd);
; #pragma unroll
;     for (int i = 0; i < 4; ++i) {
;       const f32x4 s1 = *(const f32x4*)(sc + i * 256 + lane * 4);
;       const f32x4 s0 = *(const f32x4*)(sh + i * 256 + lane * 4);
;       float h[4];
; #pragma unroll
;       for (int j = 0; j < 4; ++j) h[j] = (v[i * 4 + j] - mu) * rstd * (1.f + s1[j]) + s0[j];
;       st4bf(hout + i * 256 + lane * 4, h[0], h[1], h[2], h[3]);
;     }
;   }
	s_nop 1
	v_permlane32_swap_b32_e32 v65, v66
	v_add_f32_e32 v65, v65, v66
	v_mov_b32_e32 v66, v65
	s_waitcnt lgkmcnt(0)
	s_nop 1
	v_permlane16_swap_b32_e32 v65, v66
	v_add_f32_e32 v65, v65, v66
	s_waitcnt lgkmcnt(0)
	s_nop 1
	v_add_f32_dpp v65, v65, v65 row_ror:8 row_mask:0xf bank_mask:0xf
	s_waitcnt lgkmcnt(0)
	s_nop 1
	v_add_f32_dpp v66, v65, v65 row_ror:4 row_mask:0xf bank_mask:0xf
	v_ashrrev_i32_e32 v65, 31, v64
	v_lshlrev_b64 v[64:65], 11, v[64:65]
	v_lshl_add_u64 v[64:65], s[2:3], 0, v[64:65]
	v_lshl_add_u64 v[64:65], v[192:193], 1, v[64:65]
	s_waitcnt lgkmcnt(0)
	s_nop 1
	v_add_f32_dpp v66, v66, v66 quad_perm:[2,3,0,1] row_mask:0xf bank_mask:0xf
	s_waitcnt lgkmcnt(0)
	s_nop 1
	v_add_f32_dpp v66, v66, v66 quad_perm:[1,0,3,2] row_mask:0xf bank_mask:0xf
	v_fmamk_f32 v66, v66, 0x3a800000, v211
	v_mul_f32_e32 v67, 0x4b800000, v66
	v_cmp_gt_f32_e32 vcc, s59, v66
	s_waitcnt vmcnt(7)
	v_pk_add_f32 v[0:1], v[0:1], 1.0 op_sel_hi:[1,0]
	v_pk_add_f32 v[2:3], v[2:3], 1.0 op_sel_hi:[1,0]
	v_cndmask_b32_e32 v66, v66, v67, vcc
	v_rsq_f32_e32 v66, v66
	s_waitcnt vmcnt(6)
	v_pk_add_f32 v[4:5], v[4:5], 1.0 op_sel_hi:[1,0]
	v_pk_add_f32 v[6:7], v[6:7], 1.0 op_sel_hi:[1,0]
	s_waitcnt vmcnt(5)
	v_pk_add_f32 v[8:9], v[8:9], 1.0 op_sel_hi:[1,0]
	v_mul_f32_e32 v67, 0x45800000, v66
	v_cndmask_b32_e32 v66, v66, v67, vcc
	v_pk_mul_f32 v[32:33], v[32:33], v[66:67] op_sel_hi:[1,0]
	v_pk_mul_f32 v[34:35], v[34:35], v[66:67] op_sel_hi:[1,0]
	s_waitcnt vmcnt(2)
	v_pk_fma_f32 v[0:1], v[0:1], v[32:33], v[20:21]
	v_pk_fma_f32 v[2:3], v[2:3], v[34:35], v[22:23]
	v_cvt_pk_bf16_f32 v0, v0, v1
	v_cvt_pk_bf16_f32 v1, v2, v3
	global_store_dwordx2 v[64:65], v[0:1], off
	v_pk_mul_f32 v[0:1], v[36:37], v[66:67] op_sel_hi:[1,0]
	v_pk_mul_f32 v[2:3], v[38:39], v[66:67] op_sel_hi:[1,0]
	v_pk_fma_f32 v[0:1], v[4:5], v[0:1], v[12:13]
	v_pk_fma_f32 v[2:3], v[6:7], v[2:3], v[14:15]
	v_cvt_pk_bf16_f32 v0, v0, v1
	v_cvt_pk_bf16_f32 v1, v2, v3
	v_pk_add_f32 v[10:11], v[10:11], 1.0 op_sel_hi:[1,0]
	global_store_dwordx2 v[64:65], v[0:1], off offset:512
	v_pk_mul_f32 v[0:1], v[40:41], v[66:67] op_sel_hi:[1,0]
	v_pk_mul_f32 v[2:3], v[42:43], v[66:67] op_sel_hi:[1,0]
	s_waitcnt vmcnt(3)
	v_pk_fma_f32 v[0:1], v[8:9], v[0:1], v[24:25]
	v_pk_fma_f32 v[2:3], v[10:11], v[2:3], v[26:27]
	v_cvt_pk_bf16_f32 v0, v0, v1
	v_cvt_pk_bf16_f32 v1, v2, v3
	v_pk_add_f32 v[16:17], v[16:17], 1.0 op_sel_hi:[1,0]
	global_store_dwordx2 v[64:65], v[0:1], off offset:1024
	v_pk_mul_f32 v[0:1], v[44:45], v[66:67] op_sel_hi:[1,0]
	v_pk_mul_f32 v[2:3], v[46:47], v[66:67] op_sel_hi:[1,0]
	v_pk_add_f32 v[4:5], v[18:19], 1.0 op_sel_hi:[1,0]
	s_waitcnt vmcnt(3)
	v_pk_fma_f32 v[0:1], v[16:17], v[0:1], v[28:29]
	v_pk_fma_f32 v[2:3], v[4:5], v[2:3], v[30:31]
	v_cvt_pk_bf16_f32 v0, v0, v1
	v_cvt_pk_bf16_f32 v1, v2, v3
	global_store_dwordx2 v[64:65], v[0:1], off offset:1536
	v_mov_b32_e32 v64, v68
	v_mov_b32_e32 v0, v48
	v_mov_b32_e32 v1, v49
	v_mov_b32_e32 v2, v50
	v_mov_b32_e32 v3, v51
	v_mov_b32_e32 v4, v52
	v_mov_b32_e32 v5, v53
	v_mov_b32_e32 v6, v54
	v_mov_b32_e32 v7, v55
	v_mov_b32_e32 v8, v56
	v_mov_b32_e32 v9, v57
	v_mov_b32_e32 v10, v58
	v_mov_b32_e32 v11, v59
	v_mov_b32_e32 v12, v60
	v_mov_b32_e32 v13, v61
	v_mov_b32_e32 v14, v62
	v_mov_b32_e32 v15, v63
	s_andn2_b64 exec, exec, s[16:17]
	s_cbranch_execz .LBB0_586

; DEVI int otid() { int t = threadIdx.x; asm volatile("" : "+v"(t)); return t; }
; DEVI void ln_stats(const float (&v)[16], float& mu, float& rstd) {
;   float s = 0.f;
; #pragma unroll
;   for (int i = 0; i < 16; ++i) s += v[i];
;   mu = wave_sum(s) * (1.f / 1024.f);
;   float q = 0.f;
; #pragma unroll
;   for (int i = 0; i < 16; ++i) { const float d = v[i] - mu; q += d * d; }
;   rstd = rsqrtf(wave_sum(q) * (1.f / 1024.f) + EPS);
; }
; DEVI void rowload(const float* __restrict__ src, float (&v)[16]) {
;   const int lane = otid() & 63;
; #pragma unroll
;   for (int i = 0; i < 4; ++i) {
;     const f32x4 t = *(const f32x4*)(src + i * 256 + lane * 4);
;     v[i * 4 + 0] = t[0]; v[i * 4 + 1] = t[1]; v[i * 4 + 2] = t[2]; v[i * 4 + 3] = t[3];
;   }
; }
; DEVI void rowproc(float (&v)[16], float* __restrict__ dst, const float* __restrict__ ag, const float* __restrict__ ab,
;                   u16* __restrict__ hout, const float* __restrict__ sh, const float* __restrict__ sc) {
;   const int lane = otid() & 63;
;   float mu, rstd;
;   if (ag) {
;     ln_stats(v, mu, rstd);
; #pragma unroll
;     for (int i = 0; i < 4; ++i) {
;       const f32x4 g = *(const f32x4*)(ag + i * 256 + lane * 4);
;       const f32x4 b = *(const f32x4*)(ab + i * 256 + lane * 4);
;       f32x4 o;
; #pragma unroll
;       for (int j = 0; j < 4; ++j) { v[i * 4 + j] = (v[i * 4 + j] - mu) * rstd * g[j] + b[j]; o[j] = v[i * 4 + j]; }
;       *(f32x4*)(dst + i * 256 + lane * 4) = o;
;     }
;   }
.LBB0_582:
	s_or_b64 exec, exec, s[2:3]
	v_mov_b32_e32 v20, v208
	v_readlane_b32 s2, v253, 48
	v_and_b32_e32 v20, 63, v20
	v_readlane_b32 s3, v253, 49
	s_and_b64 vcc, exec, s[2:3]
	v_lshlrev_b32_e32 v192, 2, v20
	s_cbranch_vccz .LBB0_584
	v_lshlrev_b64 v[16:17], 12, v[16:17]
	v_lshl_add_u64 v[16:17], v[18:19], 0, v[16:17]
	s_waitcnt vmcnt(3)
	v_add_f32_e32 v18, 0, v0
	v_add_f32_e32 v18, v1, v18
	v_add_f32_e32 v18, v2, v18
	v_add_f32_e32 v18, v3, v18
	s_waitcnt vmcnt(2)
	v_add_f32_e32 v18, v4, v18
	v_add_f32_e32 v18, v5, v18
	v_add_f32_e32 v18, v6, v18
	v_add_f32_e32 v18, v7, v18
	s_waitcnt vmcnt(1)
	v_add_f32_e32 v18, v8, v18
	v_add_f32_e32 v18, v9, v18
	v_add_f32_e32 v18, v10, v18
	v_add_f32_e32 v18, v11, v18
	s_waitcnt vmcnt(0)
	v_add_f32_e32 v18, v12, v18
	v_add_f32_e32 v18, v13, v18
	v_add_f32_e32 v18, v14, v18
	v_add_f32_e32 v18, v15, v18
	v_mov_b32_e32 v19, v18
	v_lshlrev_b32_e32 v70, 4, v20
	v_mov_b32_e32 v71, v193
	v_lshl_add_u64 v[32:33], v[16:17], 0, v[70:71]
	s_waitcnt lgkmcnt(0)
	s_nop 1
	v_permlane32_swap_b32_e32 v18, v19
	v_add_f32_e32 v18, v18, v19
	v_mov_b32_e32 v19, v18
	s_waitcnt lgkmcnt(0)
	s_nop 1
	v_permlane16_swap_b32_e32 v18, v19
	v_add_f32_e32 v18, v18, v19
	s_waitcnt lgkmcnt(0)
	s_nop 1
	v_add_f32_dpp v18, v18, v18 row_ror:8 row_mask:0xf bank_mask:0xf
	s_waitcnt lgkmcnt(0)
	s_nop 1
	v_add_f32_dpp v18, v18, v18 row_ror:4 row_mask:0xf bank_mask:0xf
	s_waitcnt lgkmcnt(0)
	s_nop 1
	v_add_f32_dpp v18, v18, v18 quad_perm:[2,3,0,1] row_mask:0xf bank_mask:0xf
	s_waitcnt lgkmcnt(0)
	s_nop 1
	v_add_f32_dpp v18, v18, v18 quad_perm:[1,0,3,2] row_mask:0xf bank_mask:0xf
	v_mul_f32_e32 v46, 0x3a800000, v18
	global_load_dwordx4 v[16:19], v70, s[12:13]
	global_load_dwordx4 v[20:23], v70, s[14:15]
	global_load_dwordx4 v[24:27], v70, s[12:13] offset:1024
	global_load_dwordx4 v[28:31], v70, s[14:15] offset:1024
	global_load_dwordx4 v[34:37], v70, s[12:13] offset:2048
	global_load_dwordx4 v[38:41], v70, s[14:15] offset:2048
	global_load_dwordx4 v[42:45], v70, s[12:13] offset:3072
	s_nop 0
	global_load_dwordx4 v[70:73], v70, s[14:15] offset:3072
	v_pk_add_f32 v[74:75], v[0:1], v[46:47] op_sel_hi:[1,0] neg_lo:[0,1] neg_hi:[0,1]
	v_pk_add_f32 v[78:79], v[2:3], v[46:47] op_sel_hi:[1,0] neg_lo:[0,1] neg_hi:[0,1]
	v_pk_mul_f32 v[76:77], v[74:75], v[74:75]
	v_pk_mul_f32 v[80:81], v[78:79], v[78:79]
	v_add_f32_e32 v65, v76, v77
	v_pk_add_f32 v[82:83], v[4:5], v[46:47] op_sel_hi:[1,0] neg_lo:[0,1] neg_hi:[0,1]
	v_add_f32_e32 v65, v80, v65
	v_pk_mul_f32 v[84:85], v[82:83], v[82:83]
	v_add_f32_e32 v65, v81, v65
	v_pk_add_f32 v[86:87], v[6:7], v[46:47] op_sel_hi:[1,0] neg_lo:[0,1] neg_hi:[0,1]
	v_add_f32_e32 v65, v84, v65
	v_pk_mul_f32 v[88:89], v[86:87], v[86:87]
	v_add_f32_e32 v65, v85, v65
	v_pk_add_f32 v[90:91], v[8:9], v[46:47] op_sel_hi:[1,0] neg_lo:[0,1] neg_hi:[0,1]
	v_add_f32_e32 v65, v88, v65
	v_pk_mul_f32 v[92:93], v[90:91], v[90:91]
	v_add_f32_e32 v65, v89, v65
	v_pk_add_f32 v[94:95], v[10:11], v[46:47] op_sel_hi:[1,0] neg_lo:[0,1] neg_hi:[0,1]
	v_add_f32_e32 v65, v92, v65
	v_pk_mul_f32 v[96:97], v[94:95], v[94:95]
	v_add_f32_e32 v65, v93, v65
	v_pk_add_f32 v[98:99], v[12:13], v[46:47] op_sel_hi:[1,0] neg_lo:[0,1] neg_hi:[0,1]
	v_add_f32_e32 v65, v96, v65
	v_pk_mul_f32 v[100:101], v[98:99], v[98:99]
	v_add_f32_e32 v65, v97, v65
	v_pk_add_f32 v[46:47], v[14:15], v[46:47] op_sel_hi:[1,0] neg_lo:[0,1] neg_hi:[0,1]
	v_add_f32_e32 v65, v100, v65
	v_pk_mul_f32 v[102:103], v[46:47], v[46:47]
	v_add_f32_e32 v65, v101, v65
	v_add_f32_e32 v65, v102, v65
	v_add_f32_e32 v65, v103, v65
	v_mov_b32_e32 v67, v65
	s_waitcnt lgkmcnt(0)
	s_nop 1
	v_permlane32_swap_b32_e32 v65, v67
	v_add_f32_e32 v65, v65, v67
	v_mov_b32_e32 v67, v65
	s_waitcnt lgkmcnt(0)
	s_nop 1
	v_permlane16_swap_b32_e32 v65, v67
	v_add_f32_e32 v65, v65, v67
	s_waitcnt lgkmcnt(0)
	s_nop 1
	v_add_f32_dpp v65, v65, v65 row_ror:8 row_mask:0xf bank_mask:0xf
	s_waitcnt lgkmcnt(0)
	s_nop 1
	v_add_f32_dpp v65, v65, v65 row_ror:4 row_mask:0xf bank_mask:0xf
	s_waitcnt lgkmcnt(0)
	s_nop 1
	v_add_f32_dpp v65, v65, v65 quad_perm:[2,3,0,1] row_mask:0xf bank_mask:0xf
	s_waitcnt lgkmcnt(0)
	s_nop 1
	v_add_f32_dpp v65, v65, v65 quad_perm:[1,0,3,2] row_mask:0xf bank_mask:0xf
	v_fmamk_f32 v65, v65, 0x3a800000, v211
	v_cmp_gt_f32_e32 vcc, s59, v65
	v_mul_f32_e32 v67, 0x4b800000, v65
	s_nop 0
	v_cndmask_b32_e32 v65, v65, v67, vcc
	v_rsq_f32_e32 v65, v65
	s_nop 0
	v_mul_f32_e32 v67, 0x45800000, v65
	v_cndmask_b32_e32 v76, v65, v67, vcc
	v_pk_mul_f32 v[74:75], v[74:75], v[76:77] op_sel_hi:[1,0]
	s_waitcnt vmcnt(6)
	v_pk_fma_f32 v[16:17], v[16:17], v[74:75], v[20:21]
	v_pk_mul_f32 v[20:21], v[78:79], v[76:77] op_sel_hi:[1,0]
	s_nop 0
	v_pk_fma_f32 v[18:19], v[18:19], v[20:21], v[22:23]
	v_pk_mul_f32 v[20:21], v[82:83], v[76:77] op_sel_hi:[1,0]
	v_pk_mul_f32 v[22:23], v[86:87], v[76:77] op_sel_hi:[1,0]
	s_waitcnt vmcnt(4)
	v_pk_fma_f32 v[20:21], v[24:25], v[20:21], v[28:29]
	v_pk_fma_f32 v[22:23], v[26:27], v[22:23], v[30:31]
	v_pk_mul_f32 v[24:25], v[90:91], v[76:77] op_sel_hi:[1,0]
	v_pk_mul_f32 v[26:27], v[94:95], v[76:77] op_sel_hi:[1,0]
	v_pk_mul_f32 v[28:29], v[98:99], v[76:77] op_sel_hi:[1,0]
	v_pk_mul_f32 v[30:31], v[46:47], v[76:77] op_sel_hi:[1,0]
	s_waitcnt vmcnt(2)
	v_pk_fma_f32 v[24:25], v[34:35], v[24:25], v[38:39]
	v_pk_fma_f32 v[26:27], v[36:37], v[26:27], v[40:41]
	s_waitcnt vmcnt(0)
	v_pk_fma_f32 v[28:29], v[42:43], v[28:29], v[70:71]
	v_pk_fma_f32 v[30:31], v[44:45], v[30:31], v[72:73]
	global_store_dwordx4 v[32:33], v[16:19], off
	global_store_dwordx4 v[32:33], v[20:23], off offset:1024
	global_store_dwordx4 v[32:33], v[24:27], off offset:2048
	global_store_dwordx4 v[32:33], v[28:31], off offset:3072
	v_mov_b64_e32 v[46:47], v[30:31]
	v_mov_b64_e32 v[44:45], v[28:29]
	v_mov_b64_e32 v[42:43], v[26:27]
	v_mov_b64_e32 v[40:41], v[24:25]
	v_mov_b64_e32 v[38:39], v[22:23]
	v_mov_b64_e32 v[36:37], v[20:21]
	v_mov_b64_e32 v[34:35], v[18:19]
	v_mov_b64_e32 v[32:33], v[16:17]
	s_cbranch_execnz .LBB0_565
	s_branch .LBB0_585

; DEVI int otid() { int t = threadIdx.x; asm volatile("" : "+v"(t)); return t; }
; DEVI void ln_stats(const float (&v)[16], float& mu, float& rstd) {
;   float s = 0.f;
; #pragma unroll
;   for (int i = 0; i < 16; ++i) s += v[i];
;   mu = wave_sum(s) * (1.f / 1024.f);
;   float q = 0.f;
; #pragma unroll
;   for (int i = 0; i < 16; ++i) { const float d = v[i] - mu; q += d * d; }
;   rstd = rsqrtf(wave_sum(q) * (1.f / 1024.f) + EPS);
; }
; DEVI void rowload(const float* __restrict__ src, float (&v)[16]) {
;   const int lane = otid() & 63;
; #pragma unroll
;   for (int i = 0; i < 4; ++i) {
;     const f32x4 t = *(const f32x4*)(src + i * 256 + lane * 4);
;     v[i * 4 + 0] = t[0]; v[i * 4 + 1] = t[1]; v[i * 4 + 2] = t[2]; v[i * 4 + 3] = t[3];
;   }
; }
; DEVI void rowproc(float (&v)[16], float* __restrict__ dst, const float* __restrict__ ag, const float* __restrict__ ab,
;                   u16* __restrict__ hout, const float* __restrict__ sh, const float* __restrict__ sc) {
;   const int lane = otid() & 63;
;   float mu, rstd;
;   if (ag) {
;     ln_stats(v, mu, rstd);
; #pragma unroll
;     for (int i = 0; i < 4; ++i) {
;       const f32x4 g = *(const f32x4*)(ag + i * 256 + lane * 4);
;       const f32x4 b = *(const f32x4*)(ab + i * 256 + lane * 4);
;       f32x4 o;
; #pragma unroll
;       for (int j = 0; j < 4; ++j) { v[i * 4 + j] = (v[i * 4 + j] - mu) * rstd * g[j] + b[j]; o[j] = v[i * 4 + j]; }
;       *(f32x4*)(dst + i * 256 + lane * 4) = o;
;     }
;   }
.LBB0_651:
	s_or_b64 exec, exec, s[2:3]
	v_lshlrev_b64 v[32:33], 12, v[32:33]
	v_lshl_add_u64 v[32:33], v[34:35], 0, v[32:33]
	s_waitcnt vmcnt(3)
	v_add_f32_e32 v35, 0, v20
	v_add_f32_e32 v35, v21, v35
	v_add_f32_e32 v35, v22, v35
	v_add_f32_e32 v35, v23, v35
	s_waitcnt vmcnt(2)
	v_add_f32_e32 v35, v28, v35
	v_add_f32_e32 v35, v29, v35
	v_add_f32_e32 v35, v30, v35
	v_add_f32_e32 v35, v31, v35
	s_waitcnt vmcnt(1)
	v_add_f32_e32 v35, v24, v35
	v_add_f32_e32 v35, v25, v35
	v_add_f32_e32 v35, v26, v35
	v_add_f32_e32 v35, v27, v35
	s_waitcnt vmcnt(0)
	v_add_f32_e32 v35, v16, v35
	v_add_f32_e32 v35, v17, v35
	v_add_f32_e32 v35, v18, v35
	v_add_f32_e32 v35, v19, v35
	v_mov_b32_e32 v37, v35
	v_mov_b32_e32 v34, v208
	v_readlane_b32 s2, v253, 50
	v_lshlrev_b32_e32 v34, 4, v34
	s_waitcnt lgkmcnt(0)
	s_nop 1
	v_permlane32_swap_b32_e32 v35, v37
	v_add_f32_e32 v35, v35, v37
	v_mov_b32_e32 v37, v35
	v_readlane_b32 s6, v253, 52
	v_and_b32_e32 v192, 0x3f0, v34
	v_readlane_b32 s3, v253, 51
	v_readlane_b32 s7, v253, 53
	s_waitcnt lgkmcnt(0)
	s_nop 1
	v_permlane16_swap_b32_e32 v35, v37
	v_add_f32_e32 v35, v35, v37
	v_lshl_add_u64 v[56:57], v[32:33], 0, v[192:193]
	s_waitcnt lgkmcnt(0)
	s_nop 1
	v_add_f32_dpp v35, v35, v35 row_ror:8 row_mask:0xf bank_mask:0xf
	global_load_dwordx4 v[38:41], v192, s[6:7]
	s_waitcnt lgkmcnt(0)
	s_nop 1
	v_add_f32_dpp v35, v35, v35 row_ror:4 row_mask:0xf bank_mask:0xf
	s_waitcnt lgkmcnt(0)
	s_nop 1
	v_add_f32_dpp v35, v35, v35 quad_perm:[2,3,0,1] row_mask:0xf bank_mask:0xf
	s_waitcnt lgkmcnt(0)
	s_nop 1
	v_add_f32_dpp v35, v35, v35 quad_perm:[1,0,3,2] row_mask:0xf bank_mask:0xf
	v_mul_f32_e32 v54, 0x3a800000, v35
	global_load_dwordx4 v[32:35], v192, s[2:3]
	v_pk_add_f32 v[58:59], v[20:21], v[54:55] op_sel_hi:[1,0] neg_lo:[0,1] neg_hi:[0,1]
	v_pk_add_f32 v[62:63], v[22:23], v[54:55] op_sel_hi:[1,0] neg_lo:[0,1] neg_hi:[0,1]
	global_load_dwordx4 v[20:23], v192, s[2:3] offset:1024
	global_load_dwordx4 v[42:45], v192, s[6:7] offset:1024
	v_pk_add_f32 v[66:67], v[28:29], v[54:55] op_sel_hi:[1,0] neg_lo:[0,1] neg_hi:[0,1]
	v_pk_add_f32 v[72:73], v[30:31], v[54:55] op_sel_hi:[1,0] neg_lo:[0,1] neg_hi:[0,1]
	global_load_dwordx4 v[28:31], v192, s[2:3] offset:2048
	global_load_dwordx4 v[46:49], v192, s[6:7] offset:2048
	v_pk_add_f32 v[76:77], v[24:25], v[54:55] op_sel_hi:[1,0] neg_lo:[0,1] neg_hi:[0,1]
	v_pk_add_f32 v[80:81], v[26:27], v[54:55] op_sel_hi:[1,0] neg_lo:[0,1] neg_hi:[0,1]
	global_load_dwordx4 v[24:27], v192, s[2:3] offset:3072
	global_load_dwordx4 v[50:53], v192, s[6:7] offset:3072
	v_pk_mul_f32 v[60:61], v[58:59], v[58:59]
	v_pk_mul_f32 v[64:65], v[62:63], v[62:63]
	v_add_f32_e32 v37, v60, v61
	v_add_f32_e32 v37, v64, v37
	v_pk_mul_f32 v[70:71], v[66:67], v[66:67]
	v_add_f32_e32 v37, v65, v37
	v_add_f32_e32 v37, v70, v37
	v_pk_mul_f32 v[74:75], v[72:73], v[72:73]
	v_add_f32_e32 v37, v71, v37
	v_add_f32_e32 v37, v74, v37
	v_pk_mul_f32 v[78:79], v[76:77], v[76:77]
	v_add_f32_e32 v37, v75, v37
	v_add_f32_e32 v37, v78, v37
	v_pk_mul_f32 v[82:83], v[80:81], v[80:81]
	v_add_f32_e32 v37, v79, v37
	v_pk_add_f32 v[84:85], v[16:17], v[54:55] op_sel_hi:[1,0] neg_lo:[0,1] neg_hi:[0,1]
	v_add_f32_e32 v37, v82, v37
	v_pk_mul_f32 v[16:17], v[84:85], v[84:85]
	v_add_f32_e32 v37, v83, v37
	v_pk_add_f32 v[54:55], v[18:19], v[54:55] op_sel_hi:[1,0] neg_lo:[0,1] neg_hi:[0,1]
	v_add_f32_e32 v16, v16, v37
	v_pk_mul_f32 v[18:19], v[54:55], v[54:55]
	v_add_f32_e32 v16, v17, v16
	v_add_f32_e32 v16, v18, v16
	v_add_f32_e32 v16, v19, v16
	v_mov_b32_e32 v17, v16
	s_waitcnt lgkmcnt(0)
	s_nop 1
	v_permlane32_swap_b32_e32 v16, v17
	v_add_f32_e32 v16, v16, v17
	v_mov_b32_e32 v17, v16
	s_waitcnt lgkmcnt(0)
	s_nop 1
	v_permlane16_swap_b32_e32 v16, v17
	v_add_f32_e32 v16, v16, v17
	s_waitcnt lgkmcnt(0)
	s_nop 1
	v_add_f32_dpp v16, v16, v16 row_ror:8 row_mask:0xf bank_mask:0xf
	s_waitcnt lgkmcnt(0)
	s_nop 1
	v_add_f32_dpp v16, v16, v16 row_ror:4 row_mask:0xf bank_mask:0xf
	s_waitcnt lgkmcnt(0)
	s_nop 1
	v_add_f32_dpp v16, v16, v16 quad_perm:[2,3,0,1] row_mask:0xf bank_mask:0xf
	s_waitcnt lgkmcnt(0)
	s_nop 1
	v_add_f32_dpp v16, v16, v16 quad_perm:[1,0,3,2] row_mask:0xf bank_mask:0xf
	v_fmamk_f32 v16, v16, 0x3a800000, v211
	v_cmp_gt_f32_e32 vcc, s59, v16
	v_mul_f32_e32 v17, 0x4b800000, v16
	s_nop 0
	v_cndmask_b32_e32 v16, v16, v17, vcc
	v_rsq_f32_e32 v16, v16
	s_nop 0
	v_mul_f32_e32 v17, 0x45800000, v16
	v_cndmask_b32_e32 v60, v16, v17, vcc
	v_pk_mul_f32 v[16:17], v[58:59], v[60:61] op_sel_hi:[1,0]
	v_pk_mul_f32 v[18:19], v[62:63], v[60:61] op_sel_hi:[1,0]
	s_waitcnt vmcnt(6)
	v_pk_fma_f32 v[16:17], v[32:33], v[16:17], v[38:39]
	v_pk_fma_f32 v[18:19], v[34:35], v[18:19], v[40:41]
	global_store_dwordx4 v[56:57], v[16:19], off
	v_mov_b32_e32 v32, v36
	s_nop 0
	v_pk_mul_f32 v[16:17], v[66:67], v[60:61] op_sel_hi:[1,0]
	v_pk_mul_f32 v[18:19], v[72:73], v[60:61] op_sel_hi:[1,0]
	s_waitcnt vmcnt(5)
	v_pk_fma_f32 v[16:17], v[20:21], v[16:17], v[42:43]
	v_pk_fma_f32 v[18:19], v[22:23], v[18:19], v[44:45]
	global_store_dwordx4 v[56:57], v[16:19], off offset:1024
	v_mov_b32_e32 v20, v0
	v_mov_b32_e32 v21, v1
	v_pk_mul_f32 v[16:17], v[76:77], v[60:61] op_sel_hi:[1,0]
	v_pk_mul_f32 v[18:19], v[80:81], v[60:61] op_sel_hi:[1,0]
	s_waitcnt vmcnt(4)
	v_pk_fma_f32 v[16:17], v[28:29], v[16:17], v[46:47]
	v_pk_fma_f32 v[18:19], v[30:31], v[18:19], v[48:49]
	global_store_dwordx4 v[56:57], v[16:19], off offset:2048
	v_mov_b32_e32 v22, v2
	v_mov_b32_e32 v23, v3
	v_pk_mul_f32 v[16:17], v[84:85], v[60:61] op_sel_hi:[1,0]
	v_pk_mul_f32 v[18:19], v[54:55], v[60:61] op_sel_hi:[1,0]
	s_waitcnt vmcnt(3)
	v_pk_fma_f32 v[16:17], v[24:25], v[16:17], v[50:51]
	v_pk_fma_f32 v[18:19], v[26:27], v[18:19], v[52:53]
	global_store_dwordx4 v[56:57], v[16:19], off offset:3072
	v_mov_b32_e32 v28, v4
	v_mov_b32_e32 v29, v5
	v_mov_b32_e32 v30, v6
	v_mov_b32_e32 v31, v7
	v_mov_b32_e32 v24, v8
	v_mov_b32_e32 v25, v9
	v_mov_b32_e32 v26, v10
	v_mov_b32_e32 v27, v11
	v_mov_b32_e32 v16, v12
	v_mov_b32_e32 v17, v13
	v_mov_b32_e32 v18, v14
	v_mov_b32_e32 v19, v15
	s_andn2_b64 exec, exec, s[12:13]
	s_cbranch_execz .LBB0_668

; DEVI void st4bf(u16* p, float a, float b, float c, float d) { u32x2 w = {cvtpk(a, b), cvtpk(c, d)}; *(u32x2*)p = w; }
; DEVI void ln_stats(const float (&v)[16], float& mu, float& rstd) {
;   float s = 0.f;
; #pragma unroll
;   for (int i = 0; i < 16; ++i) s += v[i];
;   mu = wave_sum(s) * (1.f / 1024.f);
;   float q = 0.f;
; #pragma unroll
;   for (int i = 0; i < 16; ++i) { const float d = v[i] - mu; q += d * d; }
;   rstd = rsqrtf(wave_sum(q) * (1.f / 1024.f) + EPS);
; }
; DEVI void rowproc(float (&v)[16], float* __restrict__ dst, const float* __restrict__ ag, const float* __restrict__ ab,
;                   u16* __restrict__ hout, const float* __restrict__ sh, const float* __restrict__ sc) {
;     ...
;   if (hout) {
;     ln_stats(v, mu, rstd);
; #pragma unroll
;     for (int i = 0; i < 4; ++i) {
;       const f32x4 s1 = *(const f32x4*)(sc + i * 256 + lane * 4);
;       const f32x4 s0 = *(const f32x4*)(sh + i * 256 + lane * 4);
;       float h[4];
; #pragma unroll
;       for (int j = 0; j < 4; ++j) h[j] = (v[i * 4 + j] - mu) * rstd * (1.f + s1[j]) + s0[j];
;       st4bf(hout + i * 256 + lane * 4, h[0], h[1], h[2], h[3]);
.LBB0_671:
	s_or_b64 exec, exec, s[14:15]
	s_waitcnt vmcnt(3)
	v_add_f32_e32 v35, 0, v28
	v_add_f32_e32 v35, v29, v35
	v_add_f32_e32 v35, v30, v35
	v_add_f32_e32 v35, v31, v35
	s_waitcnt vmcnt(2)
	v_add_f32_e32 v35, v24, v35
	v_add_f32_e32 v35, v25, v35
	v_add_f32_e32 v35, v26, v35
	v_add_f32_e32 v35, v27, v35
	s_waitcnt vmcnt(1)
	v_add_f32_e32 v35, v20, v35
	v_add_f32_e32 v35, v21, v35
	v_add_f32_e32 v35, v22, v35
	v_add_f32_e32 v35, v23, v35
	s_waitcnt vmcnt(0)
	v_add_f32_e32 v35, v16, v35
	v_add_f32_e32 v35, v17, v35
	v_add_f32_e32 v35, v18, v35
	v_add_f32_e32 v35, v19, v35
	v_mov_b32_e32 v38, v35
	s_and_b64 s[2:3], exec, vcc
	v_cmp_lt_i32_e32 vcc, s53, v32
	v_add_u32_e32 v33, 0xffffdf00, v32
	s_or_b64 s[12:13], s[2:3], s[12:13]
	s_waitcnt lgkmcnt(0)
	s_nop 1
	v_permlane32_swap_b32_e32 v35, v38
	v_add_f32_e32 v35, v35, v38
	v_mov_b32_e32 v38, v35
	v_cndmask_b32_e32 v32, v32, v33, vcc
	v_cmp_gt_i32_e64 s[2:3], s95, v32
	v_cndmask_b32_e64 v32, 0, 1, vcc
	v_readlane_b32 s9, v254, 21
	s_waitcnt lgkmcnt(0)
	s_nop 1
	v_permlane16_swap_b32_e32 v35, v38
	v_add_f32_e32 v35, v35, v38
	v_or_b32_e32 v32, s9, v32
	s_movk_i32 s9, 0x6000
	v_mul_lo_u32 v32, v32, s9
	v_cndmask_b32_e64 v192, v213, v32, s[2:3]
	s_waitcnt lgkmcnt(0)
	s_nop 1
	v_add_f32_dpp v35, v35, v35 row_ror:8 row_mask:0xf bank_mask:0xf
	v_readlane_b32 s2, v252, 43
	v_mov_b32_e32 v34, v208
	v_readlane_b32 s3, v252, 44
	s_waitcnt lgkmcnt(0)
	s_nop 1
	v_add_f32_dpp v35, v35, v35 row_ror:4 row_mask:0xf bank_mask:0xf
	v_lshl_add_u64 v[32:33], s[2:3], 0, v[192:193]
	s_mov_b64 s[2:3], 0x1000
	s_waitcnt lgkmcnt(0)
	s_nop 1
	v_add_f32_dpp v35, v35, v35 quad_perm:[2,3,0,1] row_mask:0xf bank_mask:0xf
	s_waitcnt lgkmcnt(0)
	s_nop 1
	v_add_f32_dpp v35, v35, v35 quad_perm:[1,0,3,2] row_mask:0xf bank_mask:0xf
	v_mul_f32_e32 v40, 0x3a800000, v35
	v_lshlrev_b32_e32 v35, 4, v34
	v_and_b32_e32 v192, 0x3f0, v35
	v_lshl_add_u64 v[62:63], v[32:33], 0, v[192:193]
	v_lshl_add_u64 v[64:65], v[62:63], 0, s[2:3]
	v_and_b32_e32 v32, 63, v34
	s_movk_i32 s2, 0x1000
	v_lshlrev_b32_e32 v192, 3, v32
	v_add_co_u32_e32 v32, vcc, s2, v62
	v_pk_add_f32 v[42:43], v[30:31], v[40:41] op_sel_hi:[1,0] neg_lo:[0,1] neg_hi:[0,1]
	s_nop 0
	v_addc_co_u32_e32 v33, vcc, 0, v63, vcc
	global_load_dwordx4 v[48:51], v[32:33], off
	s_nop 0
	global_load_dwordx4 v[32:35], v[62:63], off
	v_pk_add_f32 v[44:45], v[28:29], v[40:41] op_sel_hi:[1,0] neg_lo:[0,1] neg_hi:[0,1]
	global_load_dwordx4 v[52:55], v[64:65], off offset:1024
	global_load_dwordx4 v[28:31], v[62:63], off offset:1024
	v_pk_add_f32 v[76:77], v[22:23], v[40:41] op_sel_hi:[1,0] neg_lo:[0,1] neg_hi:[0,1]
	v_pk_add_f32 v[80:81], v[20:21], v[40:41] op_sel_hi:[1,0] neg_lo:[0,1] neg_hi:[0,1]
	v_pk_mul_f32 v[70:71], v[44:45], v[44:45]
	v_pk_mul_f32 v[66:67], v[42:43], v[42:43]
	v_pk_add_f32 v[26:27], v[26:27], v[40:41] op_sel_hi:[1,0] neg_lo:[0,1] neg_hi:[0,1]
	v_pk_add_f32 v[24:25], v[24:25], v[40:41] op_sel_hi:[1,0] neg_lo:[0,1] neg_hi:[0,1]
	v_pk_add_f32 v[18:19], v[18:19], v[40:41] op_sel_hi:[1,0] neg_lo:[0,1] neg_hi:[0,1]
	v_pk_add_f32 v[16:17], v[16:17], v[40:41] op_sel_hi:[1,0] neg_lo:[0,1] neg_hi:[0,1]
	v_add_f32_e32 v40, v70, v71
	v_add_f32_e32 v40, v66, v40
	v_pk_mul_f32 v[74:75], v[24:25], v[24:25]
	v_add_f32_e32 v40, v67, v40
	v_add_f32_e32 v40, v74, v40
	v_pk_mul_f32 v[72:73], v[26:27], v[26:27]
	v_add_f32_e32 v40, v75, v40
	v_add_f32_e32 v40, v72, v40
	v_pk_mul_f32 v[82:83], v[80:81], v[80:81]
	v_add_f32_e32 v40, v73, v40
	v_add_f32_e32 v40, v82, v40
	v_pk_mul_f32 v[78:79], v[76:77], v[76:77]
	v_add_f32_e32 v40, v83, v40
	v_add_f32_e32 v40, v78, v40
	v_add_f32_e32 v40, v79, v40
	v_lshl_add_u64 v[38:39], v[36:37], 0, v[192:193]
	v_lshl_add_u64 v[36:37], v[36:37], 0, s[10:11]
	s_waitcnt vmcnt(3)
; DEVI void st4bf(u16* p, float a, float b, float c, float d) { u32x2 w = {cvtpk(a, b), cvtpk(c, d)}; *(u32x2*)p = w; }
; DEVI void ln_stats(const float (&v)[16], float& mu, float& rstd) {
;     ...
;   float q = 0.f;
; #pragma unroll
;   for (int i = 0; i < 16; ++i) { const float d = v[i] - mu; q += d * d; }
;   rstd = rsqrtf(wave_sum(q) * (1.f / 1024.f) + EPS);
; }
; DEVI void rowproc(float (&v)[16], float* __restrict__ dst, const float* __restrict__ ag, const float* __restrict__ ab,
;                   u16* __restrict__ hout, const float* __restrict__ sh, const float* __restrict__ sc) {
;     ...
;   if (hout) {
;     ln_stats(v, mu, rstd);
; #pragma unroll
;     for (int i = 0; i < 4; ++i) {
;       const f32x4 s1 = *(const f32x4*)(sc + i * 256 + lane * 4);
;       const f32x4 s0 = *(const f32x4*)(sh + i * 256 + lane * 4);
;       float h[4];
; #pragma unroll
;       for (int j = 0; j < 4; ++j) h[j] = (v[i * 4 + j] - mu) * rstd * (1.f + s1[j]) + s0[j];
;       st4bf(hout + i * 256 + lane * 4, h[0], h[1], h[2], h[3]);
;     }
;   }
	v_pk_add_f32 v[46:47], v[50:51], 1.0 op_sel_hi:[1,0]
	v_pk_add_f32 v[48:49], v[48:49], 1.0 op_sel_hi:[1,0]
	s_waitcnt vmcnt(1)
	v_pk_add_f32 v[50:51], v[54:55], 1.0 op_sel_hi:[1,0]
	global_load_dwordx4 v[54:57], v[64:65], off offset:2048
	global_load_dwordx4 v[58:61], v[62:63], off offset:2048
	v_pk_add_f32 v[52:53], v[52:53], 1.0 op_sel_hi:[1,0]
	s_waitcnt vmcnt(1)
	v_pk_add_f32 v[84:85], v[54:55], 1.0 op_sel_hi:[1,0]
	v_pk_add_f32 v[86:87], v[56:57], 1.0 op_sel_hi:[1,0]
	global_load_dwordx4 v[20:23], v[64:65], off offset:3072
	global_load_dwordx4 v[54:57], v[62:63], off offset:3072
	v_pk_mul_f32 v[64:65], v[16:17], v[16:17]
	v_pk_mul_f32 v[62:63], v[18:19], v[18:19]
	v_add_f32_e32 v40, v64, v40
	v_add_f32_e32 v40, v65, v40
	v_add_f32_e32 v40, v62, v40
	v_add_f32_e32 v40, v63, v40
	v_mov_b32_e32 v62, v40
	s_waitcnt lgkmcnt(0)
	s_nop 1
	v_permlane32_swap_b32_e32 v40, v62
	v_add_f32_e32 v40, v40, v62
	v_mov_b32_e32 v62, v40
	s_waitcnt lgkmcnt(0)
	s_nop 1
	v_permlane16_swap_b32_e32 v40, v62
	v_add_f32_e32 v40, v40, v62
	s_waitcnt lgkmcnt(0)
	s_nop 1
	v_add_f32_dpp v40, v40, v40 row_ror:8 row_mask:0xf bank_mask:0xf
	s_waitcnt lgkmcnt(0)
	s_nop 1
	v_add_f32_dpp v40, v40, v40 row_ror:4 row_mask:0xf bank_mask:0xf
	s_waitcnt lgkmcnt(0)
	s_nop 1
	v_add_f32_dpp v40, v40, v40 quad_perm:[2,3,0,1] row_mask:0xf bank_mask:0xf
	s_waitcnt lgkmcnt(0)
	s_nop 1
	v_add_f32_dpp v40, v40, v40 quad_perm:[1,0,3,2] row_mask:0xf bank_mask:0xf
	v_fmamk_f32 v40, v40, 0x3a800000, v211
	v_cmp_gt_f32_e32 vcc, s59, v40
	v_mul_f32_e32 v62, 0x4b800000, v40
	s_waitcnt vmcnt(1)
	v_pk_add_f32 v[20:21], v[20:21], 1.0 op_sel_hi:[1,0]
	v_cndmask_b32_e32 v40, v40, v62, vcc
	v_rsq_f32_e32 v40, v40
	s_nop 0
	v_mul_f32_e32 v62, 0x45800000, v40
	v_cndmask_b32_e32 v40, v40, v62, vcc
	v_pk_mul_f32 v[24:25], v[24:25], v[40:41] op_sel_hi:[1,0]
	v_pk_mul_f32 v[26:27], v[26:27], v[40:41] op_sel_hi:[1,0]
	v_pk_fma_f32 v[24:25], v[52:53], v[24:25], v[28:29]
	v_pk_fma_f32 v[26:27], v[50:51], v[26:27], v[30:31]
	v_cvt_pk_bf16_f32 v24, v24, v25
	v_cvt_pk_bf16_f32 v25, v26, v27
	v_pk_mul_f32 v[16:17], v[16:17], v[40:41] op_sel_hi:[1,0]
	v_pk_mul_f32 v[44:45], v[44:45], v[40:41] op_sel_hi:[1,0]
	v_pk_mul_f32 v[42:43], v[42:43], v[40:41] op_sel_hi:[1,0]
	global_store_dwordx2 v[38:39], v[24:25], off offset:512
	v_pk_mul_f32 v[24:25], v[80:81], v[40:41] op_sel_hi:[1,0]
	v_pk_mul_f32 v[26:27], v[76:77], v[40:41] op_sel_hi:[1,0]
	s_waitcnt vmcnt(1)
	v_pk_fma_f32 v[16:17], v[20:21], v[16:17], v[54:55]
	v_pk_mul_f32 v[18:19], v[18:19], v[40:41] op_sel_hi:[1,0]
	v_pk_add_f32 v[20:21], v[22:23], 1.0 op_sel_hi:[1,0]
	v_pk_fma_f32 v[32:33], v[48:49], v[44:45], v[32:33]
	v_pk_fma_f32 v[34:35], v[46:47], v[42:43], v[34:35]
	v_pk_fma_f32 v[24:25], v[84:85], v[24:25], v[58:59]
	v_pk_fma_f32 v[26:27], v[86:87], v[26:27], v[60:61]
	v_pk_fma_f32 v[18:19], v[20:21], v[18:19], v[56:57]
	v_cvt_pk_bf16_f32 v32, v32, v33
	v_cvt_pk_bf16_f32 v33, v34, v35
	v_cvt_pk_bf16_f32 v24, v24, v25
	v_cvt_pk_bf16_f32 v25, v26, v27
	v_cvt_pk_bf16_f32 v16, v16, v17
	v_cvt_pk_bf16_f32 v17, v18, v19
	global_store_dwordx2 v[38:39], v[32:33], off
	global_store_dwordx2 v[38:39], v[24:25], off offset:1024
	global_store_dwordx2 v[38:39], v[16:17], off offset:1536
	v_mov_b32_e32 v32, v41
	v_mov_b32_e32 v28, v0
	v_mov_b32_e32 v29, v1
	v_mov_b32_e32 v30, v2
	v_mov_b32_e32 v31, v3
	v_mov_b32_e32 v24, v4
	v_mov_b32_e32 v25, v5
	v_mov_b32_e32 v26, v6
	v_mov_b32_e32 v27, v7
	v_mov_b32_e32 v20, v8
	v_mov_b32_e32 v21, v9
	v_mov_b32_e32 v22, v10
	v_mov_b32_e32 v23, v11
	v_mov_b32_e32 v16, v12
	v_mov_b32_e32 v17, v13
	v_mov_b32_e32 v18, v14
	v_mov_b32_e32 v19, v15
	s_andn2_b64 exec, exec, s[12:13]
	s_cbranch_execz .LBB0_674

; DEVI void st4bf(u16* p, float a, float b, float c, float d) { u32x2 w = {cvtpk(a, b), cvtpk(c, d)}; *(u32x2*)p = w; }
; DEVI void ln_stats(const float (&v)[16], float& mu, float& rstd) {
;   float s = 0.f;
; #pragma unroll
;   for (int i = 0; i < 16; ++i) s += v[i];
;   mu = wave_sum(s) * (1.f / 1024.f);
;   float q = 0.f;
; #pragma unroll
;   for (int i = 0; i < 16; ++i) { const float d = v[i] - mu; q += d * d; }
;   rstd = rsqrtf(wave_sum(q) * (1.f / 1024.f) + EPS);
; }
; DEVI void rowproc(float (&v)[16], float* __restrict__ dst, const float* __restrict__ ag, const float* __restrict__ ab,
;                   u16* __restrict__ hout, const float* __restrict__ sh, const float* __restrict__ sc) {
;     ...
;   if (hout) {
;     ln_stats(v, mu, rstd);
; #pragma unroll
;     for (int i = 0; i < 4; ++i) {
;       const f32x4 s1 = *(const f32x4*)(sc + i * 256 + lane * 4);
;       const f32x4 s0 = *(const f32x4*)(sh + i * 256 + lane * 4);
;       float h[4];
; #pragma unroll
;       for (int j = 0; j < 4; ++j) h[j] = (v[i * 4 + j] - mu) * rstd * (1.f + s1[j]) + s0[j];
;       st4bf(hout + i * 256 + lane * 4, h[0], h[1], h[2], h[3]);
;     }
;   }
.LBB0_683:
	s_waitcnt vmcnt(3)
	v_add_f32_e32 v0, 0, v16
	v_add_f32_e32 v0, v17, v0
	v_add_f32_e32 v0, v18, v0
	v_add_f32_e32 v0, v19, v0
	v_add_f32_e32 v0, v20, v0
	v_add_f32_e32 v0, v21, v0
	v_add_f32_e32 v0, v22, v0
	v_add_f32_e32 v0, v23, v0
	v_add_f32_e32 v0, v24, v0
	v_add_f32_e32 v0, v25, v0
	v_add_f32_e32 v0, v26, v0
	v_add_f32_e32 v0, v27, v0
	v_add_f32_e32 v0, v28, v0
	v_add_f32_e32 v0, v29, v0
	v_add_f32_e32 v0, v30, v0
	v_add_f32_e32 v0, v31, v0
	v_mov_b32_e32 v1, v0
	v_readlane_b32 s2, v253, 54
	v_readlane_b32 s3, v253, 55
	s_waitcnt lgkmcnt(0)
	s_nop 1
	v_permlane32_swap_b32_e32 v0, v1
	v_add_f32_e32 v0, v0, v1
	v_mov_b32_e32 v1, v0
	s_waitcnt lgkmcnt(0)
	s_nop 1
	v_permlane16_swap_b32_e32 v0, v1
	v_add_f32_e32 v2, v0, v1
	v_lshl_add_u64 v[0:1], s[2:3], 0, v[66:67]
	v_lshl_add_u64 v[28:29], v[192:193], 2, v[0:1]
	s_movk_i32 s2, 0x1000
	v_add_co_u32_e32 v0, vcc, s2, v28
	s_waitcnt vmcnt(1) lgkmcnt(0)
	s_nop 1
	v_add_f32_dpp v8, v2, v2 row_ror:8 row_mask:0xf bank_mask:0xf
	v_addc_co_u32_e32 v1, vcc, 0, v29, vcc
	s_mov_b64 s[2:3], 0x1000
	global_load_dwordx4 v[0:3], v[0:1], off
	s_waitcnt vmcnt(1) lgkmcnt(0)
	s_nop 1
	v_add_f32_dpp v14, v8, v8 row_ror:4 row_mask:0xf bank_mask:0xf
	v_lshl_add_u64 v[12:13], v[28:29], 0, s[2:3]
	global_load_dwordx4 v[4:7], v[12:13], off offset:1024
	global_load_dwordx4 v[8:11], v[12:13], off offset:2048
	s_waitcnt lgkmcnt(0)
	s_nop 1
	v_add_f32_dpp v30, v14, v14 quad_perm:[2,3,0,1] row_mask:0xf bank_mask:0xf
	global_load_dwordx4 v[12:15], v[12:13], off offset:3072
	s_nop 0
	global_load_dwordx4 v[16:19], v[28:29], off
	global_load_dwordx4 v[20:23], v[28:29], off offset:1024
	global_load_dwordx4 v[24:27], v[28:29], off offset:2048
	s_waitcnt lgkmcnt(0)
	s_nop 1
	v_add_f32_dpp v30, v30, v30 quad_perm:[1,0,3,2] row_mask:0xf bank_mask:0xf
	v_mul_f32_e32 v66, 0x3a800000, v30
	global_load_dwordx4 v[28:31], v[28:29], off offset:3072
	v_pk_add_f32 v[32:33], v[32:33], v[66:67] op_sel_hi:[1,0] neg_lo:[0,1] neg_hi:[0,1]
	v_pk_add_f32 v[34:35], v[34:35], v[66:67] op_sel_hi:[1,0] neg_lo:[0,1] neg_hi:[0,1]
	v_pk_mul_f32 v[72:73], v[32:33], v[32:33]
	v_pk_mul_f32 v[70:71], v[34:35], v[34:35]
	v_add_f32_e32 v72, v72, v73
	v_pk_add_f32 v[36:37], v[36:37], v[66:67] op_sel_hi:[1,0] neg_lo:[0,1] neg_hi:[0,1]
	v_add_f32_e32 v70, v70, v72
	v_pk_mul_f32 v[76:77], v[36:37], v[36:37]
	v_add_f32_e32 v70, v71, v70
	v_pk_add_f32 v[38:39], v[38:39], v[66:67] op_sel_hi:[1,0] neg_lo:[0,1] neg_hi:[0,1]
	v_add_f32_e32 v70, v76, v70
	v_pk_mul_f32 v[74:75], v[38:39], v[38:39]
	v_add_f32_e32 v70, v77, v70
	v_pk_add_f32 v[40:41], v[40:41], v[66:67] op_sel_hi:[1,0] neg_lo:[0,1] neg_hi:[0,1]
	v_add_f32_e32 v70, v74, v70
	v_pk_mul_f32 v[80:81], v[40:41], v[40:41]
	v_add_f32_e32 v70, v75, v70
	v_pk_add_f32 v[42:43], v[42:43], v[66:67] op_sel_hi:[1,0] neg_lo:[0,1] neg_hi:[0,1]
	v_add_f32_e32 v70, v80, v70
	v_pk_mul_f32 v[78:79], v[42:43], v[42:43]
	v_add_f32_e32 v70, v81, v70
	v_pk_add_f32 v[44:45], v[44:45], v[66:67] op_sel_hi:[1,0] neg_lo:[0,1] neg_hi:[0,1]
	v_add_f32_e32 v70, v78, v70
	v_pk_add_f32 v[46:47], v[46:47], v[66:67] op_sel_hi:[1,0] neg_lo:[0,1] neg_hi:[0,1]
	v_pk_mul_f32 v[66:67], v[44:45], v[44:45]
	v_add_f32_e32 v70, v79, v70
	v_add_f32_e32 v66, v66, v70
	v_pk_mul_f32 v[82:83], v[46:47], v[46:47]
	v_add_f32_e32 v66, v67, v66
	v_add_f32_e32 v66, v82, v66
	v_add_f32_e32 v66, v83, v66
	v_mov_b32_e32 v67, v66
	s_waitcnt lgkmcnt(0)
	s_nop 1
	v_permlane32_swap_b32_e32 v66, v67
	v_add_f32_e32 v66, v66, v67
	v_mov_b32_e32 v67, v66
	s_waitcnt lgkmcnt(0)
	s_nop 1
	v_permlane16_swap_b32_e32 v66, v67
	v_add_f32_e32 v66, v66, v67
	s_waitcnt lgkmcnt(0)
	s_nop 1
	v_add_f32_dpp v66, v66, v66 row_ror:8 row_mask:0xf bank_mask:0xf
	s_waitcnt lgkmcnt(0)
	s_nop 1
	v_add_f32_dpp v70, v66, v66 row_ror:4 row_mask:0xf bank_mask:0xf
	v_lshl_add_u64 v[66:67], v[192:193], 1, v[64:65]
	v_lshl_add_u64 v[64:65], v[64:65], 0, s[12:13]
	s_waitcnt lgkmcnt(0)
	s_nop 1
	v_add_f32_dpp v70, v70, v70 quad_perm:[2,3,0,1] row_mask:0xf bank_mask:0xf
	s_waitcnt vmcnt(7)
	v_pk_add_f32 v[0:1], v[0:1], 1.0 op_sel_hi:[1,0]
	v_pk_add_f32 v[2:3], v[2:3], 1.0 op_sel_hi:[1,0]
	s_waitcnt lgkmcnt(0)
	s_nop 1
	v_add_f32_dpp v70, v70, v70 quad_perm:[1,0,3,2] row_mask:0xf bank_mask:0xf
	v_fmamk_f32 v70, v70, 0x3a800000, v211
	v_mul_f32_e32 v71, 0x4b800000, v70
	v_cmp_gt_f32_e32 vcc, s59, v70
	s_waitcnt vmcnt(6)
	v_pk_add_f32 v[4:5], v[4:5], 1.0 op_sel_hi:[1,0]
	v_pk_add_f32 v[6:7], v[6:7], 1.0 op_sel_hi:[1,0]
	v_cndmask_b32_e32 v70, v70, v71, vcc
	v_rsq_f32_e32 v70, v70
	s_waitcnt vmcnt(5)
	v_pk_add_f32 v[8:9], v[8:9], 1.0 op_sel_hi:[1,0]
	v_pk_add_f32 v[10:11], v[10:11], 1.0 op_sel_hi:[1,0]
	s_waitcnt vmcnt(4)
	v_pk_add_f32 v[12:13], v[12:13], 1.0 op_sel_hi:[1,0]
	v_mul_f32_e32 v71, 0x45800000, v70
	v_cndmask_b32_e32 v70, v70, v71, vcc
	v_pk_mul_f32 v[32:33], v[32:33], v[70:71] op_sel_hi:[1,0]
	v_pk_mul_f32 v[34:35], v[34:35], v[70:71] op_sel_hi:[1,0]
	v_pk_mul_f32 v[36:37], v[36:37], v[70:71] op_sel_hi:[1,0]
	v_pk_mul_f32 v[38:39], v[38:39], v[70:71] op_sel_hi:[1,0]
	s_waitcnt vmcnt(3)
	v_pk_fma_f32 v[0:1], v[0:1], v[32:33], v[16:17]
	v_pk_fma_f32 v[2:3], v[2:3], v[34:35], v[18:19]
	v_pk_mul_f32 v[40:41], v[40:41], v[70:71] op_sel_hi:[1,0]
	v_pk_mul_f32 v[42:43], v[42:43], v[70:71] op_sel_hi:[1,0]
	s_waitcnt vmcnt(2)
	v_pk_fma_f32 v[4:5], v[4:5], v[36:37], v[20:21]
	v_pk_fma_f32 v[6:7], v[6:7], v[38:39], v[22:23]
	v_cvt_pk_bf16_f32 v0, v0, v1
	v_cvt_pk_bf16_f32 v1, v2, v3
	s_waitcnt vmcnt(1)
	v_pk_fma_f32 v[8:9], v[8:9], v[40:41], v[24:25]
	v_cvt_pk_bf16_f32 v2, v4, v5
	v_cvt_pk_bf16_f32 v3, v6, v7
	global_store_dwordx2 v[66:67], v[0:1], off
	global_store_dwordx2 v[66:67], v[2:3], off offset:512
	v_pk_fma_f32 v[0:1], v[10:11], v[42:43], v[26:27]
	v_cvt_pk_bf16_f32 v2, v8, v9
	v_cvt_pk_bf16_f32 v3, v0, v1
	global_store_dwordx2 v[66:67], v[2:3], off offset:1024
	v_pk_mul_f32 v[0:1], v[44:45], v[70:71] op_sel_hi:[1,0]
	v_pk_mul_f32 v[2:3], v[46:47], v[70:71] op_sel_hi:[1,0]
	v_pk_add_f32 v[4:5], v[14:15], 1.0 op_sel_hi:[1,0]
	s_waitcnt vmcnt(3)
	v_pk_fma_f32 v[0:1], v[12:13], v[0:1], v[28:29]
	v_pk_fma_f32 v[2:3], v[4:5], v[2:3], v[30:31]
	v_cvt_pk_bf16_f32 v0, v0, v1
	v_cvt_pk_bf16_f32 v1, v2, v3
	global_store_dwordx2 v[66:67], v[0:1], off offset:1536
	v_mov_b32_e32 v16, v69
	v_mov_b32_e32 v0, v48
	v_mov_b32_e32 v1, v49
	v_mov_b32_e32 v2, v50
	v_mov_b32_e32 v3, v51
	v_mov_b32_e32 v4, v52
	v_mov_b32_e32 v5, v53
	v_mov_b32_e32 v6, v54
	v_mov_b32_e32 v7, v55
	v_mov_b32_e32 v8, v56
	v_mov_b32_e32 v9, v57
	v_mov_b32_e32 v10, v58
	v_mov_b32_e32 v11, v59
	v_mov_b32_e32 v12, v60
	v_mov_b32_e32 v13, v61
	v_mov_b32_e32 v14, v62
	v_mov_b32_e32 v15, v63
	s_andn2_b64 exec, exec, s[14:15]
	s_cbranch_execz .LBB0_698

; DEVI int otid() { int t = threadIdx.x; asm volatile("" : "+v"(t)); return t; }
; DEVI void ln_stats(const float (&v)[16], float& mu, float& rstd) {
;   float s = 0.f;
; #pragma unroll
;   for (int i = 0; i < 16; ++i) s += v[i];
;   mu = wave_sum(s) * (1.f / 1024.f);
;   float q = 0.f;
; #pragma unroll
;   for (int i = 0; i < 16; ++i) { const float d = v[i] - mu; q += d * d; }
;   rstd = rsqrtf(wave_sum(q) * (1.f / 1024.f) + EPS);
; }
; DEVI void rowload(const float* __restrict__ src, float (&v)[16]) {
;   const int lane = otid() & 63;
; #pragma unroll
;   for (int i = 0; i < 4; ++i) {
;     const f32x4 t = *(const f32x4*)(src + i * 256 + lane * 4);
;     v[i * 4 + 0] = t[0]; v[i * 4 + 1] = t[1]; v[i * 4 + 2] = t[2]; v[i * 4 + 3] = t[3];
;   }
; }
; DEVI void rowproc(float (&v)[16], float* __restrict__ dst, const float* __restrict__ ag, const float* __restrict__ ab,
;                   u16* __restrict__ hout, const float* __restrict__ sh, const float* __restrict__ sc) {
;   const int lane = otid() & 63;
;   float mu, rstd;
;   if (ag) {
;     ln_stats(v, mu, rstd);
; #pragma unroll
;     for (int i = 0; i < 4; ++i) {
;       const f32x4 g = *(const f32x4*)(ag + i * 256 + lane * 4);
;       const f32x4 b = *(const f32x4*)(ab + i * 256 + lane * 4);
;       f32x4 o;
; #pragma unroll
;       for (int j = 0; j < 4; ++j) { v[i * 4 + j] = (v[i * 4 + j] - mu) * rstd * g[j] + b[j]; o[j] = v[i * 4 + j]; }
;       *(f32x4*)(dst + i * 256 + lane * 4) = o;
;     }
;   }
.LBB0_694:
	s_or_b64 exec, exec, s[2:3]
	v_mov_b32_e32 v20, v208
	v_readlane_b32 s2, v253, 56
	v_and_b32_e32 v20, 63, v20
	v_readlane_b32 s3, v253, 57
	s_and_b64 vcc, exec, s[2:3]
	v_lshlrev_b32_e32 v192, 2, v20
	s_cbranch_vccz .LBB0_696
	v_lshlrev_b64 v[16:17], 12, v[16:17]
	v_lshl_add_u64 v[16:17], v[18:19], 0, v[16:17]
	s_waitcnt vmcnt(3)
	v_add_f32_e32 v18, 0, v0
	v_add_f32_e32 v18, v1, v18
	v_add_f32_e32 v18, v2, v18
	v_add_f32_e32 v18, v3, v18
	s_waitcnt vmcnt(2)
	v_add_f32_e32 v18, v4, v18
	v_add_f32_e32 v18, v5, v18
	v_add_f32_e32 v18, v6, v18
	v_add_f32_e32 v18, v7, v18
	s_waitcnt vmcnt(1)
	v_add_f32_e32 v18, v8, v18
	v_add_f32_e32 v18, v9, v18
	v_add_f32_e32 v18, v10, v18
	v_add_f32_e32 v18, v11, v18
	s_waitcnt vmcnt(0)
	v_add_f32_e32 v18, v12, v18
	v_add_f32_e32 v18, v13, v18
	v_add_f32_e32 v18, v14, v18
	v_add_f32_e32 v18, v15, v18
	v_mov_b32_e32 v19, v18
	v_readlane_b32 s68, v252, 18
	v_readlane_b32 s80, v252, 30
	v_readlane_b32 s81, v252, 31
	v_lshlrev_b32_e32 v70, 4, v20
	s_waitcnt lgkmcnt(0)
	s_nop 1
	v_permlane32_swap_b32_e32 v18, v19
	v_add_f32_e32 v18, v18, v19
	v_mov_b32_e32 v19, v18
	v_mov_b32_e32 v71, v193
	v_readlane_b32 s82, v252, 32
	v_readlane_b32 s83, v252, 33
	s_mov_b64 s[48:49], s[80:81]
	s_waitcnt lgkmcnt(0)
	s_nop 1
	v_permlane16_swap_b32_e32 v18, v19
	v_add_f32_e32 v18, v18, v19
	v_lshl_add_u64 v[32:33], v[16:17], 0, v[70:71]
	s_mov_b64 s[50:51], s[82:83]
	v_readlane_b32 s69, v252, 19
	v_readlane_b32 s70, v252, 20
	s_waitcnt lgkmcnt(0)
	s_nop 1
	v_add_f32_dpp v18, v18, v18 row_ror:8 row_mask:0xf bank_mask:0xf
	v_readlane_b32 s71, v252, 21
	v_readlane_b32 s72, v252, 22
	v_readlane_b32 s73, v252, 23
	v_readlane_b32 s74, v252, 24
	s_waitcnt lgkmcnt(0)
	s_nop 1
	v_add_f32_dpp v18, v18, v18 row_ror:4 row_mask:0xf bank_mask:0xf
	v_readlane_b32 s75, v252, 25
	v_readlane_b32 s76, v252, 26
	v_readlane_b32 s77, v252, 27
	v_readlane_b32 s78, v252, 28
	s_waitcnt lgkmcnt(0)
	s_nop 1
	v_add_f32_dpp v18, v18, v18 quad_perm:[2,3,0,1] row_mask:0xf bank_mask:0xf
	v_readlane_b32 s79, v252, 29
	s_waitcnt lgkmcnt(0)
	s_nop 1
	v_add_f32_dpp v18, v18, v18 quad_perm:[1,0,3,2] row_mask:0xf bank_mask:0xf
	v_mul_f32_e32 v46, 0x3a800000, v18
	global_load_dwordx4 v[16:19], v70, s[48:49]
	global_load_dwordx4 v[20:23], v70, s[50:51]
	global_load_dwordx4 v[24:27], v70, s[48:49] offset:1024
	global_load_dwordx4 v[28:31], v70, s[50:51] offset:1024
	global_load_dwordx4 v[34:37], v70, s[48:49] offset:2048
	global_load_dwordx4 v[38:41], v70, s[50:51] offset:2048
	global_load_dwordx4 v[42:45], v70, s[48:49] offset:3072
	s_nop 0
	global_load_dwordx4 v[70:73], v70, s[50:51] offset:3072
	v_pk_add_f32 v[74:75], v[0:1], v[46:47] op_sel_hi:[1,0] neg_lo:[0,1] neg_hi:[0,1]
	v_pk_add_f32 v[78:79], v[2:3], v[46:47] op_sel_hi:[1,0] neg_lo:[0,1] neg_hi:[0,1]
	v_pk_mul_f32 v[76:77], v[74:75], v[74:75]
	v_pk_mul_f32 v[80:81], v[78:79], v[78:79]
	v_add_f32_e32 v76, v76, v77
	v_pk_add_f32 v[82:83], v[4:5], v[46:47] op_sel_hi:[1,0] neg_lo:[0,1] neg_hi:[0,1]
	v_add_f32_e32 v76, v80, v76
	v_pk_mul_f32 v[84:85], v[82:83], v[82:83]
	v_add_f32_e32 v76, v81, v76
	v_pk_add_f32 v[86:87], v[6:7], v[46:47] op_sel_hi:[1,0] neg_lo:[0,1] neg_hi:[0,1]
	v_add_f32_e32 v76, v84, v76
	v_pk_mul_f32 v[88:89], v[86:87], v[86:87]
	v_add_f32_e32 v76, v85, v76
	v_pk_add_f32 v[90:91], v[8:9], v[46:47] op_sel_hi:[1,0] neg_lo:[0,1] neg_hi:[0,1]
	v_add_f32_e32 v76, v88, v76
	v_pk_mul_f32 v[92:93], v[90:91], v[90:91]
	v_add_f32_e32 v76, v89, v76
	v_pk_add_f32 v[94:95], v[10:11], v[46:47] op_sel_hi:[1,0] neg_lo:[0,1] neg_hi:[0,1]
	v_add_f32_e32 v76, v92, v76
	v_pk_mul_f32 v[96:97], v[94:95], v[94:95]
	v_add_f32_e32 v76, v93, v76
	v_pk_add_f32 v[98:99], v[12:13], v[46:47] op_sel_hi:[1,0] neg_lo:[0,1] neg_hi:[0,1]
	v_add_f32_e32 v76, v96, v76
	v_pk_mul_f32 v[100:101], v[98:99], v[98:99]
	v_add_f32_e32 v76, v97, v76
	v_pk_add_f32 v[46:47], v[14:15], v[46:47] op_sel_hi:[1,0] neg_lo:[0,1] neg_hi:[0,1]
	v_add_f32_e32 v76, v100, v76
	v_pk_mul_f32 v[102:103], v[46:47], v[46:47]
	v_add_f32_e32 v76, v101, v76
	v_add_f32_e32 v76, v102, v76
	v_add_f32_e32 v76, v103, v76
	v_mov_b32_e32 v77, v76
	s_waitcnt lgkmcnt(0)
	s_nop 1
	v_permlane32_swap_b32_e32 v76, v77
	v_add_f32_e32 v76, v76, v77
	v_mov_b32_e32 v77, v76
	s_waitcnt lgkmcnt(0)
	s_nop 1
	v_permlane16_swap_b32_e32 v76, v77
	v_add_f32_e32 v76, v76, v77
	s_waitcnt lgkmcnt(0)
	s_nop 1
	v_add_f32_dpp v76, v76, v76 row_ror:8 row_mask:0xf bank_mask:0xf
	s_waitcnt lgkmcnt(0)
	s_nop 1
	v_add_f32_dpp v76, v76, v76 row_ror:4 row_mask:0xf bank_mask:0xf
	s_waitcnt lgkmcnt(0)
	s_nop 1
	v_add_f32_dpp v76, v76, v76 quad_perm:[2,3,0,1] row_mask:0xf bank_mask:0xf
	s_waitcnt lgkmcnt(0)
	s_nop 1
	v_add_f32_dpp v76, v76, v76 quad_perm:[1,0,3,2] row_mask:0xf bank_mask:0xf
	v_fmamk_f32 v76, v76, 0x3a800000, v211
	v_cmp_gt_f32_e32 vcc, s59, v76
	v_mul_f32_e32 v77, 0x4b800000, v76
	s_nop 0
	v_cndmask_b32_e32 v76, v76, v77, vcc
	v_rsq_f32_e32 v76, v76
	s_nop 0
	v_mul_f32_e32 v77, 0x45800000, v76
	v_cndmask_b32_e32 v76, v76, v77, vcc
	v_pk_mul_f32 v[74:75], v[74:75], v[76:77] op_sel_hi:[1,0]
	s_waitcnt vmcnt(6)
	v_pk_fma_f32 v[16:17], v[16:17], v[74:75], v[20:21]
	v_pk_mul_f32 v[20:21], v[78:79], v[76:77] op_sel_hi:[1,0]
	s_nop 0
	v_pk_fma_f32 v[18:19], v[18:19], v[20:21], v[22:23]
	v_pk_mul_f32 v[20:21], v[82:83], v[76:77] op_sel_hi:[1,0]
	v_pk_mul_f32 v[22:23], v[86:87], v[76:77] op_sel_hi:[1,0]
	s_waitcnt vmcnt(4)
	v_pk_fma_f32 v[20:21], v[24:25], v[20:21], v[28:29]
	v_pk_fma_f32 v[22:23], v[26:27], v[22:23], v[30:31]
	v_pk_mul_f32 v[24:25], v[90:91], v[76:77] op_sel_hi:[1,0]
	v_pk_mul_f32 v[26:27], v[94:95], v[76:77] op_sel_hi:[1,0]
	v_pk_mul_f32 v[28:29], v[98:99], v[76:77] op_sel_hi:[1,0]
	v_pk_mul_f32 v[30:31], v[46:47], v[76:77] op_sel_hi:[1,0]
	s_waitcnt vmcnt(2)
	v_pk_fma_f32 v[24:25], v[34:35], v[24:25], v[38:39]
	v_pk_fma_f32 v[26:27], v[36:37], v[26:27], v[40:41]
	s_waitcnt vmcnt(0)
	v_pk_fma_f32 v[28:29], v[42:43], v[28:29], v[70:71]
	v_pk_fma_f32 v[30:31], v[44:45], v[30:31], v[72:73]
	global_store_dwordx4 v[32:33], v[16:19], off
	global_store_dwordx4 v[32:33], v[20:23], off offset:1024
	global_store_dwordx4 v[32:33], v[24:27], off offset:2048
	global_store_dwordx4 v[32:33], v[28:31], off offset:3072
	v_mov_b64_e32 v[46:47], v[30:31]
	v_mov_b64_e32 v[44:45], v[28:29]
	v_mov_b64_e32 v[42:43], v[26:27]
	v_mov_b64_e32 v[40:41], v[24:25]
	v_mov_b64_e32 v[38:39], v[22:23]
	v_mov_b64_e32 v[36:37], v[20:21]
	v_mov_b64_e32 v[34:35], v[18:19]
	v_mov_b64_e32 v[32:33], v[16:17]
	s_cbranch_execnz .LBB0_683
	s_branch .LBB0_697
